# dma+cvt2 + sc1 write-through on P1 and attention/pool epilogue stores
# baseline (speedup 1.0000x reference)
.LBB0_340:
	v_mbcnt_lo_u32_b32 v0, -1, 0
	v_mbcnt_hi_u32_b32 v0, -1, v0
	v_mov_b64_e32 v[66:67], s[88:89]
	v_and_or_b32 v96, v0, 31, v191
	v_ashrrev_i32_e32 v0, 3, v0
	v_mad_i64_i32 v[66:67], s[0:1], v96, s87, v[66:67]
	s_lshl_b32 s94, s4, 1
	v_and_b32_e32 v98, -4, v0
	v_lshl_add_u64 v[66:67], v[66:67], 0, s[94:95]
	v_ashrrev_i32_e32 v99, 31, v98
	v_lshl_add_u64 v[66:67], v[98:99], 1, v[66:67]
	s_mov_b64 s[0:1], 0x3800
	v_lshl_add_u64 v[100:101], v[66:67], 0, s[0:1]
	s_movk_i32 s0, 0x3000
	v_add_co_u32_e32 v66, vcc, s0, v66
	v_ashrrev_i32_e32 v97, 31, v96
	s_nop 0
	v_addc_co_u32_e32 v67, vcc, 0, v67, vcc
	global_load_dwordx2 v[102:103], v[66:67], off offset:2048
	global_load_dwordx2 v[94:95], v[100:101], off offset:16
	global_load_dwordx2 v[92:93], v[100:101], off offset:32
	global_load_dwordx2 v[90:91], v[100:101], off offset:48
	global_load_dwordx2 v[88:89], v[100:101], off offset:64
	global_load_dwordx2 v[86:87], v[100:101], off offset:80
	global_load_dwordx2 v[84:85], v[100:101], off offset:96
	global_load_dwordx2 v[82:83], v[100:101], off offset:112
	global_load_dwordx2 v[80:81], v[100:101], off offset:128
	global_load_dwordx2 v[78:79], v[100:101], off offset:144
	global_load_dwordx2 v[76:77], v[100:101], off offset:160
	global_load_dwordx2 v[74:75], v[100:101], off offset:176
	global_load_dwordx2 v[72:73], v[100:101], off offset:192
	global_load_dwordx2 v[70:71], v[100:101], off offset:208
	global_load_dwordx2 v[68:69], v[100:101], off offset:224
	global_load_dwordx2 v[66:67], v[100:101], off offset:240
	v_readlane_b32 s0, v255, 57
	v_add_u32_e32 v98, s4, v98
	v_lshlrev_b64 v[96:97], 11, v[96:97]
	v_readlane_b32 s1, v255, 58
	v_ashrrev_i32_e32 v99, 31, v98
	s_waitcnt vmcnt(15)
	v_lshlrev_b32_e32 v100, 16, v102
	v_mul_f32_e32 v0, 0xbfb8aa3b, v100
	v_exp_f32_e32 v0, v0
	v_and_b32_e32 v101, 0xffff0000, v102
	v_lshl_add_u64 v[96:97], s[0:1], 0, v[96:97]
	v_add_f32_e32 v0, 1.0, v0
	v_rcp_f32_e32 v104, v0
	v_mul_f32_e32 v0, 0xbfb8aa3b, v101
	v_exp_f32_e32 v0, v0
	s_nop 0
	v_add_f32_e32 v0, 1.0, v0
	v_rcp_f32_e32 v105, v0
	s_nop 0
	v_pk_mul_f32 v[100:101], v[104:105], v[100:101]
	s_nop 0
	v_pk_mul_f32 v[50:51], v[50:51], v[100:101]
	s_nop 0
	v_cvt_pk_bf16_f32 v100, v50, v51
	v_lshlrev_b32_e32 v50, 16, v103
	v_mul_f32_e32 v0, 0xbfb8aa3b, v50
	v_exp_f32_e32 v0, v0
	v_and_b32_e32 v51, 0xffff0000, v103
	v_add_f32_e32 v0, 1.0, v0
	v_rcp_f32_e32 v102, v0
	v_mul_f32_e32 v0, 0xbfb8aa3b, v51
	v_exp_f32_e32 v0, v0
	s_nop 0
	v_add_f32_e32 v0, 1.0, v0
	v_rcp_f32_e32 v103, v0
	s_nop 0
	v_pk_mul_f32 v[50:51], v[102:103], v[50:51]
	s_nop 0
	v_pk_mul_f32 v[50:51], v[52:53], v[50:51]
	s_waitcnt vmcnt(14)
	v_lshlrev_b32_e32 v52, 16, v94
	v_mul_f32_e32 v0, 0xbfb8aa3b, v52
	v_exp_f32_e32 v0, v0
	v_and_b32_e32 v53, 0xffff0000, v94
	v_cvt_pk_bf16_f32 v101, v50, v51
	v_lshl_add_u64 v[50:51], v[98:99], 1, v[96:97]
	v_add_f32_e32 v0, 1.0, v0
	v_rcp_f32_e32 v96, v0
	v_mul_f32_e32 v0, 0xbfb8aa3b, v53
	v_exp_f32_e32 v0, v0
	global_store_dwordx2 v[50:51], v[100:101], off sc1
	v_add_f32_e32 v0, 1.0, v0
	v_rcp_f32_e32 v97, v0
	s_nop 0
	v_pk_mul_f32 v[52:53], v[96:97], v[52:53]
	s_nop 0
	v_pk_mul_f32 v[52:53], v[54:55], v[52:53]
	v_lshlrev_b32_e32 v54, 16, v95
	v_mul_f32_e32 v0, 0xbfb8aa3b, v54
	v_exp_f32_e32 v0, v0
	v_and_b32_e32 v55, 0xffff0000, v95
	v_cvt_pk_bf16_f32 v52, v52, v53
	v_add_f32_e32 v0, 1.0, v0
	v_rcp_f32_e32 v94, v0
	v_mul_f32_e32 v0, 0xbfb8aa3b, v55
	v_exp_f32_e32 v0, v0
	s_nop 0
	v_add_f32_e32 v0, 1.0, v0
	v_rcp_f32_e32 v95, v0
	s_nop 0
	v_pk_mul_f32 v[54:55], v[94:95], v[54:55]
	s_nop 0
	v_pk_mul_f32 v[54:55], v[56:57], v[54:55]
	s_nop 0
	v_cvt_pk_bf16_f32 v53, v54, v55
	global_store_dwordx2 v[50:51], v[52:53], off offset:16 sc1
	s_waitcnt vmcnt(15)
	v_lshlrev_b32_e32 v52, 16, v92
	v_mul_f32_e32 v0, 0xbfb8aa3b, v52
	v_exp_f32_e32 v0, v0
	v_and_b32_e32 v53, 0xffff0000, v92
	v_add_f32_e32 v0, 1.0, v0
	v_rcp_f32_e32 v54, v0
	v_mul_f32_e32 v0, 0xbfb8aa3b, v53
	v_exp_f32_e32 v0, v0
	s_nop 0
	v_add_f32_e32 v0, 1.0, v0
	v_rcp_f32_e32 v55, v0
	s_nop 0
	v_pk_mul_f32 v[52:53], v[54:55], v[52:53]
	v_lshlrev_b32_e32 v54, 16, v93
	v_mul_f32_e32 v0, 0xbfb8aa3b, v54
	v_exp_f32_e32 v0, v0
	v_and_b32_e32 v55, 0xffff0000, v93
	v_pk_mul_f32 v[52:53], v[58:59], v[52:53]
	v_add_f32_e32 v0, 1.0, v0
	v_rcp_f32_e32 v56, v0
	v_mul_f32_e32 v0, 0xbfb8aa3b, v55
	v_exp_f32_e32 v0, v0
	v_cvt_pk_bf16_f32 v52, v52, v53
	v_add_f32_e32 v0, 1.0, v0
	v_rcp_f32_e32 v57, v0
	s_nop 0
	v_pk_mul_f32 v[54:55], v[56:57], v[54:55]
	s_nop 0
	v_pk_mul_f32 v[54:55], v[60:61], v[54:55]
	s_nop 0
	v_cvt_pk_bf16_f32 v53, v54, v55
	global_store_dwordx2 v[50:51], v[52:53], off offset:32 sc1
	s_waitcnt vmcnt(15)
	v_lshlrev_b32_e32 v52, 16, v90
	v_mul_f32_e32 v0, 0xbfb8aa3b, v52
	v_exp_f32_e32 v0, v0
	v_and_b32_e32 v53, 0xffff0000, v90
	v_add_f32_e32 v0, 1.0, v0
	v_rcp_f32_e32 v54, v0
	v_mul_f32_e32 v0, 0xbfb8aa3b, v53
	v_exp_f32_e32 v0, v0
	s_nop 0
	v_add_f32_e32 v0, 1.0, v0
	v_rcp_f32_e32 v55, v0
	s_nop 0
	v_pk_mul_f32 v[52:53], v[54:55], v[52:53]
	v_lshlrev_b32_e32 v54, 16, v91
	v_mul_f32_e32 v0, 0xbfb8aa3b, v54
	v_exp_f32_e32 v0, v0
	v_and_b32_e32 v55, 0xffff0000, v91
	v_pk_mul_f32 v[52:53], v[62:63], v[52:53]
	v_add_f32_e32 v0, 1.0, v0
	v_rcp_f32_e32 v56, v0
	v_mul_f32_e32 v0, 0xbfb8aa3b, v55
	v_exp_f32_e32 v0, v0
	v_cvt_pk_bf16_f32 v52, v52, v53
	v_add_f32_e32 v0, 1.0, v0
	v_rcp_f32_e32 v57, v0
	s_nop 0
	v_pk_mul_f32 v[54:55], v[56:57], v[54:55]
	s_nop 0
	v_pk_mul_f32 v[54:55], v[64:65], v[54:55]
	s_nop 0
	v_cvt_pk_bf16_f32 v53, v54, v55
	global_store_dwordx2 v[50:51], v[52:53], off offset:48 sc1
	s_waitcnt vmcnt(15)
	v_lshlrev_b32_e32 v52, 16, v88
	v_mul_f32_e32 v0, 0xbfb8aa3b, v52
	v_exp_f32_e32 v0, v0
	v_and_b32_e32 v53, 0xffff0000, v88
	v_add_f32_e32 v0, 1.0, v0
	v_rcp_f32_e32 v54, v0
	v_mul_f32_e32 v0, 0xbfb8aa3b, v53
	v_exp_f32_e32 v0, v0
	s_nop 0
	v_add_f32_e32 v0, 1.0, v0
	v_rcp_f32_e32 v55, v0
	s_nop 0
	v_pk_mul_f32 v[52:53], v[54:55], v[52:53]
	s_nop 0
	v_pk_mul_f32 v[34:35], v[34:35], v[52:53]
	v_lshlrev_b32_e32 v52, 16, v89
	v_mul_f32_e32 v0, 0xbfb8aa3b, v52
	v_exp_f32_e32 v0, v0
	v_and_b32_e32 v53, 0xffff0000, v89
	v_cvt_pk_bf16_f32 v34, v34, v35
	v_add_f32_e32 v0, 1.0, v0
	v_rcp_f32_e32 v54, v0
	v_mul_f32_e32 v0, 0xbfb8aa3b, v53
	v_exp_f32_e32 v0, v0
	s_nop 0
	v_add_f32_e32 v0, 1.0, v0
	v_rcp_f32_e32 v55, v0
	s_nop 0
	v_pk_mul_f32 v[52:53], v[54:55], v[52:53]
	s_nop 0
	v_pk_mul_f32 v[36:37], v[36:37], v[52:53]
	s_nop 0
	v_cvt_pk_bf16_f32 v35, v36, v37
	global_store_dwordx2 v[50:51], v[34:35], off offset:64 sc1
	s_waitcnt vmcnt(15)
	v_lshlrev_b32_e32 v34, 16, v86
	v_mul_f32_e32 v0, 0xbfb8aa3b, v34
	v_exp_f32_e32 v0, v0
	v_and_b32_e32 v35, 0xffff0000, v86
	v_add_f32_e32 v0, 1.0, v0
	v_rcp_f32_e32 v36, v0
	v_mul_f32_e32 v0, 0xbfb8aa3b, v35
	v_exp_f32_e32 v0, v0
	s_nop 0
	v_add_f32_e32 v0, 1.0, v0
	v_rcp_f32_e32 v37, v0
	s_nop 0
	v_pk_mul_f32 v[34:35], v[36:37], v[34:35]
	v_lshlrev_b32_e32 v36, 16, v87
	v_mul_f32_e32 v0, 0xbfb8aa3b, v36
	v_exp_f32_e32 v0, v0
	v_and_b32_e32 v37, 0xffff0000, v87
	v_pk_mul_f32 v[34:35], v[38:39], v[34:35]
	v_add_f32_e32 v0, 1.0, v0
	v_rcp_f32_e32 v38, v0
	v_mul_f32_e32 v0, 0xbfb8aa3b, v37
	v_exp_f32_e32 v0, v0
	v_cvt_pk_bf16_f32 v34, v34, v35
	v_add_f32_e32 v0, 1.0, v0
	v_rcp_f32_e32 v39, v0
	s_nop 0
	v_pk_mul_f32 v[36:37], v[38:39], v[36:37]
	s_nop 0
	v_pk_mul_f32 v[36:37], v[40:41], v[36:37]
	s_nop 0
	v_cvt_pk_bf16_f32 v35, v36, v37
	global_store_dwordx2 v[50:51], v[34:35], off offset:80 sc1
	s_waitcnt vmcnt(15)
	v_lshlrev_b32_e32 v34, 16, v84
	v_mul_f32_e32 v0, 0xbfb8aa3b, v34
	v_exp_f32_e32 v0, v0
	v_and_b32_e32 v35, 0xffff0000, v84
	v_add_f32_e32 v0, 1.0, v0
	v_rcp_f32_e32 v36, v0
	v_mul_f32_e32 v0, 0xbfb8aa3b, v35
	v_exp_f32_e32 v0, v0
	s_nop 0
	v_add_f32_e32 v0, 1.0, v0
	v_rcp_f32_e32 v37, v0
	s_nop 0
	v_pk_mul_f32 v[34:35], v[36:37], v[34:35]
	v_lshlrev_b32_e32 v36, 16, v85
	v_mul_f32_e32 v0, 0xbfb8aa3b, v36
	v_exp_f32_e32 v0, v0
	v_and_b32_e32 v37, 0xffff0000, v85
	v_pk_mul_f32 v[34:35], v[42:43], v[34:35]
	v_add_f32_e32 v0, 1.0, v0
	v_rcp_f32_e32 v38, v0
	v_mul_f32_e32 v0, 0xbfb8aa3b, v37
	v_exp_f32_e32 v0, v0
	v_cvt_pk_bf16_f32 v34, v34, v35
	v_add_f32_e32 v0, 1.0, v0
	v_rcp_f32_e32 v39, v0
	s_nop 0
	v_pk_mul_f32 v[36:37], v[38:39], v[36:37]
	s_nop 0
	v_pk_mul_f32 v[36:37], v[44:45], v[36:37]
	s_nop 0
	v_cvt_pk_bf16_f32 v35, v36, v37
	global_store_dwordx2 v[50:51], v[34:35], off offset:96 sc1
	s_waitcnt vmcnt(15)
	v_lshlrev_b32_e32 v34, 16, v82
	v_mul_f32_e32 v0, 0xbfb8aa3b, v34
	v_exp_f32_e32 v0, v0
	v_and_b32_e32 v35, 0xffff0000, v82
	v_add_f32_e32 v0, 1.0, v0
	v_rcp_f32_e32 v36, v0
	v_mul_f32_e32 v0, 0xbfb8aa3b, v35
	v_exp_f32_e32 v0, v0
	s_nop 0
	v_add_f32_e32 v0, 1.0, v0
	v_rcp_f32_e32 v37, v0
	s_nop 0
	v_pk_mul_f32 v[34:35], v[36:37], v[34:35]
	v_lshlrev_b32_e32 v36, 16, v83
	v_mul_f32_e32 v0, 0xbfb8aa3b, v36
	v_exp_f32_e32 v0, v0
	v_and_b32_e32 v37, 0xffff0000, v83
	v_pk_mul_f32 v[34:35], v[46:47], v[34:35]
	v_add_f32_e32 v0, 1.0, v0
	v_rcp_f32_e32 v38, v0
	v_mul_f32_e32 v0, 0xbfb8aa3b, v37
	v_exp_f32_e32 v0, v0
	v_cvt_pk_bf16_f32 v34, v34, v35
	v_add_f32_e32 v0, 1.0, v0
	v_rcp_f32_e32 v39, v0
	s_nop 0
	v_pk_mul_f32 v[36:37], v[38:39], v[36:37]
	s_nop 0
	v_pk_mul_f32 v[36:37], v[48:49], v[36:37]
	s_nop 0
	v_cvt_pk_bf16_f32 v35, v36, v37
	global_store_dwordx2 v[50:51], v[34:35], off offset:112 sc1
	s_waitcnt vmcnt(15)
	v_lshlrev_b32_e32 v34, 16, v80
	v_mul_f32_e32 v0, 0xbfb8aa3b, v34
	v_exp_f32_e32 v0, v0
	v_and_b32_e32 v35, 0xffff0000, v80
	v_add_f32_e32 v0, 1.0, v0
	v_rcp_f32_e32 v36, v0
	v_mul_f32_e32 v0, 0xbfb8aa3b, v35
	v_exp_f32_e32 v0, v0
	s_nop 0
	v_add_f32_e32 v0, 1.0, v0
	v_rcp_f32_e32 v37, v0
	s_nop 0
	v_pk_mul_f32 v[34:35], v[36:37], v[34:35]
	s_nop 0
	v_pk_mul_f32 v[18:19], v[18:19], v[34:35]
	v_lshlrev_b32_e32 v34, 16, v81
	v_mul_f32_e32 v0, 0xbfb8aa3b, v34
	v_exp_f32_e32 v0, v0
	v_and_b32_e32 v35, 0xffff0000, v81
	v_cvt_pk_bf16_f32 v18, v18, v19
	v_add_f32_e32 v0, 1.0, v0
	v_rcp_f32_e32 v36, v0
	v_mul_f32_e32 v0, 0xbfb8aa3b, v35
	v_exp_f32_e32 v0, v0
	s_nop 0
	v_add_f32_e32 v0, 1.0, v0
	v_rcp_f32_e32 v37, v0
	s_nop 0
	v_pk_mul_f32 v[34:35], v[36:37], v[34:35]
	s_nop 0
	v_pk_mul_f32 v[20:21], v[20:21], v[34:35]
	s_nop 0
	v_cvt_pk_bf16_f32 v19, v20, v21
	global_store_dwordx2 v[50:51], v[18:19], off offset:128 sc1
	s_waitcnt vmcnt(15)
	v_lshlrev_b32_e32 v18, 16, v78
	v_mul_f32_e32 v0, 0xbfb8aa3b, v18
	v_exp_f32_e32 v0, v0
	v_and_b32_e32 v19, 0xffff0000, v78
	v_add_f32_e32 v0, 1.0, v0
	v_rcp_f32_e32 v20, v0
	v_mul_f32_e32 v0, 0xbfb8aa3b, v19
	v_exp_f32_e32 v0, v0
	s_nop 0
	v_add_f32_e32 v0, 1.0, v0
	v_rcp_f32_e32 v21, v0
	s_nop 0
	v_pk_mul_f32 v[18:19], v[20:21], v[18:19]
	v_lshlrev_b32_e32 v20, 16, v79
	v_mul_f32_e32 v0, 0xbfb8aa3b, v20
	v_exp_f32_e32 v0, v0
	v_and_b32_e32 v21, 0xffff0000, v79
	v_pk_mul_f32 v[18:19], v[22:23], v[18:19]
	v_add_f32_e32 v0, 1.0, v0
	v_rcp_f32_e32 v22, v0
	v_mul_f32_e32 v0, 0xbfb8aa3b, v21
	v_exp_f32_e32 v0, v0
	v_cvt_pk_bf16_f32 v18, v18, v19
	v_add_f32_e32 v0, 1.0, v0
	v_rcp_f32_e32 v23, v0
	s_nop 0
	v_pk_mul_f32 v[20:21], v[22:23], v[20:21]
	s_nop 0
	v_pk_mul_f32 v[20:21], v[24:25], v[20:21]
	s_nop 0
	v_cvt_pk_bf16_f32 v19, v20, v21
	global_store_dwordx2 v[50:51], v[18:19], off offset:144 sc1
	s_waitcnt vmcnt(15)
	v_lshlrev_b32_e32 v18, 16, v76
	v_mul_f32_e32 v0, 0xbfb8aa3b, v18
	v_exp_f32_e32 v0, v0
	v_and_b32_e32 v19, 0xffff0000, v76
	v_add_f32_e32 v0, 1.0, v0
	v_rcp_f32_e32 v20, v0
	v_mul_f32_e32 v0, 0xbfb8aa3b, v19
	v_exp_f32_e32 v0, v0
	s_nop 0
	v_add_f32_e32 v0, 1.0, v0
	v_rcp_f32_e32 v21, v0
	s_nop 0
	v_pk_mul_f32 v[18:19], v[20:21], v[18:19]
	v_lshlrev_b32_e32 v20, 16, v77
	v_mul_f32_e32 v0, 0xbfb8aa3b, v20
	v_exp_f32_e32 v0, v0
	v_and_b32_e32 v21, 0xffff0000, v77
	v_pk_mul_f32 v[18:19], v[26:27], v[18:19]
	v_add_f32_e32 v0, 1.0, v0
	v_rcp_f32_e32 v22, v0
	v_mul_f32_e32 v0, 0xbfb8aa3b, v21
	v_exp_f32_e32 v0, v0
	v_cvt_pk_bf16_f32 v18, v18, v19
	v_add_f32_e32 v0, 1.0, v0
	v_rcp_f32_e32 v23, v0
	s_nop 0
	v_pk_mul_f32 v[20:21], v[22:23], v[20:21]
	s_nop 0
	v_pk_mul_f32 v[20:21], v[28:29], v[20:21]
	s_nop 0
	v_cvt_pk_bf16_f32 v19, v20, v21
	global_store_dwordx2 v[50:51], v[18:19], off offset:160 sc1
	s_waitcnt vmcnt(15)
	v_lshlrev_b32_e32 v18, 16, v74
	v_mul_f32_e32 v0, 0xbfb8aa3b, v18
	v_exp_f32_e32 v0, v0
	v_and_b32_e32 v19, 0xffff0000, v74
	v_add_f32_e32 v0, 1.0, v0
	v_rcp_f32_e32 v20, v0
	v_mul_f32_e32 v0, 0xbfb8aa3b, v19
	v_exp_f32_e32 v0, v0
	s_nop 0
	v_add_f32_e32 v0, 1.0, v0
	v_rcp_f32_e32 v21, v0
	s_nop 0
	v_pk_mul_f32 v[18:19], v[20:21], v[18:19]
	v_lshlrev_b32_e32 v20, 16, v75
	v_mul_f32_e32 v0, 0xbfb8aa3b, v20
	v_exp_f32_e32 v0, v0
	v_and_b32_e32 v21, 0xffff0000, v75
	v_pk_mul_f32 v[18:19], v[30:31], v[18:19]
	v_add_f32_e32 v0, 1.0, v0
	v_rcp_f32_e32 v22, v0
	v_mul_f32_e32 v0, 0xbfb8aa3b, v21
	v_exp_f32_e32 v0, v0
	v_cvt_pk_bf16_f32 v18, v18, v19
	v_add_f32_e32 v0, 1.0, v0
	v_rcp_f32_e32 v23, v0
	s_nop 0
	v_pk_mul_f32 v[20:21], v[22:23], v[20:21]
	s_nop 0
	v_pk_mul_f32 v[20:21], v[32:33], v[20:21]
	s_nop 0
	v_cvt_pk_bf16_f32 v19, v20, v21
	global_store_dwordx2 v[50:51], v[18:19], off offset:176 sc1
	s_waitcnt vmcnt(15)
	v_lshlrev_b32_e32 v18, 16, v72
	v_mul_f32_e32 v0, 0xbfb8aa3b, v18
	v_exp_f32_e32 v0, v0
	v_and_b32_e32 v19, 0xffff0000, v72
	v_add_f32_e32 v0, 1.0, v0
	v_rcp_f32_e32 v20, v0
	v_mul_f32_e32 v0, 0xbfb8aa3b, v19
	v_exp_f32_e32 v0, v0
	s_nop 0
	v_add_f32_e32 v0, 1.0, v0
	v_rcp_f32_e32 v21, v0
	s_nop 0
	v_pk_mul_f32 v[18:19], v[20:21], v[18:19]
	s_nop 0
	v_pk_mul_f32 v[2:3], v[2:3], v[18:19]
	v_lshlrev_b32_e32 v18, 16, v73
	v_mul_f32_e32 v0, 0xbfb8aa3b, v18
	v_exp_f32_e32 v0, v0
	v_and_b32_e32 v19, 0xffff0000, v73
	v_cvt_pk_bf16_f32 v2, v2, v3
	v_add_f32_e32 v0, 1.0, v0
	v_rcp_f32_e32 v20, v0
	v_mul_f32_e32 v0, 0xbfb8aa3b, v19
	v_exp_f32_e32 v0, v0
	s_nop 0
	v_add_f32_e32 v0, 1.0, v0
	v_rcp_f32_e32 v21, v0
	s_nop 0
	v_pk_mul_f32 v[18:19], v[20:21], v[18:19]
	s_nop 0
	v_pk_mul_f32 v[4:5], v[4:5], v[18:19]
	s_nop 0
	v_cvt_pk_bf16_f32 v3, v4, v5
	global_store_dwordx2 v[50:51], v[2:3], off offset:192 sc1
	s_waitcnt vmcnt(15)
	v_lshlrev_b32_e32 v2, 16, v70
	v_mul_f32_e32 v0, 0xbfb8aa3b, v2
	v_exp_f32_e32 v0, v0
	v_and_b32_e32 v3, 0xffff0000, v70
	v_add_f32_e32 v0, 1.0, v0
	v_rcp_f32_e32 v4, v0
	v_mul_f32_e32 v0, 0xbfb8aa3b, v3
	v_exp_f32_e32 v0, v0
	s_nop 0
	v_add_f32_e32 v0, 1.0, v0
	v_rcp_f32_e32 v5, v0
	s_nop 0
	v_pk_mul_f32 v[2:3], v[4:5], v[2:3]
	v_lshlrev_b32_e32 v4, 16, v71
	v_mul_f32_e32 v0, 0xbfb8aa3b, v4
	v_exp_f32_e32 v0, v0
	v_and_b32_e32 v5, 0xffff0000, v71
	v_pk_mul_f32 v[2:3], v[6:7], v[2:3]
	v_add_f32_e32 v0, 1.0, v0
	v_rcp_f32_e32 v6, v0
	v_mul_f32_e32 v0, 0xbfb8aa3b, v5
	v_exp_f32_e32 v0, v0
	v_cvt_pk_bf16_f32 v2, v2, v3
	v_add_f32_e32 v0, 1.0, v0
	v_rcp_f32_e32 v7, v0
	s_nop 0
	v_pk_mul_f32 v[4:5], v[6:7], v[4:5]
	s_nop 0
	v_pk_mul_f32 v[4:5], v[8:9], v[4:5]
	s_nop 0
	v_cvt_pk_bf16_f32 v3, v4, v5
	global_store_dwordx2 v[50:51], v[2:3], off offset:208 sc1
	s_waitcnt vmcnt(15)
	v_lshlrev_b32_e32 v2, 16, v68
	v_mul_f32_e32 v0, 0xbfb8aa3b, v2
	v_exp_f32_e32 v0, v0
	v_and_b32_e32 v3, 0xffff0000, v68
	v_add_f32_e32 v0, 1.0, v0
	v_rcp_f32_e32 v4, v0
	v_mul_f32_e32 v0, 0xbfb8aa3b, v3
	v_exp_f32_e32 v0, v0
	s_nop 0
	v_add_f32_e32 v0, 1.0, v0
	v_rcp_f32_e32 v5, v0
	s_nop 0
	v_pk_mul_f32 v[2:3], v[4:5], v[2:3]
	v_lshlrev_b32_e32 v4, 16, v69
	v_mul_f32_e32 v0, 0xbfb8aa3b, v4
	v_exp_f32_e32 v0, v0
	v_and_b32_e32 v5, 0xffff0000, v69
	v_pk_mul_f32 v[2:3], v[10:11], v[2:3]
	v_add_f32_e32 v0, 1.0, v0
	v_rcp_f32_e32 v6, v0
	v_mul_f32_e32 v0, 0xbfb8aa3b, v5
	v_exp_f32_e32 v0, v0
	v_cvt_pk_bf16_f32 v2, v2, v3
	v_add_f32_e32 v0, 1.0, v0
	v_rcp_f32_e32 v7, v0
	s_nop 0
	v_pk_mul_f32 v[4:5], v[6:7], v[4:5]
	s_nop 0
	v_pk_mul_f32 v[4:5], v[12:13], v[4:5]
	s_nop 0
	v_cvt_pk_bf16_f32 v3, v4, v5
	global_store_dwordx2 v[50:51], v[2:3], off offset:224 sc1
	s_waitcnt vmcnt(15)
	v_lshlrev_b32_e32 v2, 16, v66
	v_mul_f32_e32 v0, 0xbfb8aa3b, v2
	v_exp_f32_e32 v0, v0
	v_and_b32_e32 v3, 0xffff0000, v66
	v_add_f32_e32 v0, 1.0, v0
	v_rcp_f32_e32 v4, v0
	v_mul_f32_e32 v0, 0xbfb8aa3b, v3
	v_exp_f32_e32 v0, v0
	s_nop 0
	v_add_f32_e32 v0, 1.0, v0
	v_rcp_f32_e32 v5, v0
	s_nop 0
	v_pk_mul_f32 v[2:3], v[4:5], v[2:3]
	v_lshlrev_b32_e32 v4, 16, v67
	v_mul_f32_e32 v0, 0xbfb8aa3b, v4
	v_exp_f32_e32 v0, v0
	v_and_b32_e32 v5, 0xffff0000, v67
	v_pk_mul_f32 v[2:3], v[14:15], v[2:3]
	v_add_f32_e32 v0, 1.0, v0
	v_rcp_f32_e32 v6, v0
	v_mul_f32_e32 v0, 0xbfb8aa3b, v5
	v_exp_f32_e32 v0, v0
	v_cvt_pk_bf16_f32 v2, v2, v3
	v_add_f32_e32 v0, 1.0, v0
	v_rcp_f32_e32 v7, v0
	s_nop 0
	v_pk_mul_f32 v[4:5], v[6:7], v[4:5]
	s_nop 0
	v_pk_mul_f32 v[4:5], v[16:17], v[4:5]
	s_nop 0
	v_cvt_pk_bf16_f32 v3, v4, v5
	global_store_dwordx2 v[50:51], v[2:3], off offset:240 sc1

.LBB0_349:
	v_readlane_b32 s0, v255, 16
	s_waitcnt lgkmcnt(0)
	s_barrier
	v_mov_b32_e32 v0, s0
	ds_read_b32 v0, v0
	s_movk_i32 s0, 0x4ff
	s_waitcnt lgkmcnt(0)
	s_barrier
	v_cmp_lt_u32_e32 vcc, s0, v0
	v_readfirstlane_b32 s16, v0
	s_mov_b64 s[0:1], -1
	s_cbranch_vccnz .LBB0_342
	s_cmpk_gt_u32 s16, 0x3ff
	s_cbranch_scc0 .LBB0_352
	s_add_i32 s0, s16, 0xfffffc00
	s_lshr_b32 s1, s0, 6
	s_lshl_b32 s0, s16, 8
	s_and_b32 s0, s0, 0xf00
	v_readlane_b32 s5, v254, 18
	s_lshl_b32 s4, s1, 12
	s_add_i32 s0, s0, s5
	s_add_i32 s5, s0, s4
	s_lshl_b32 s0, s16, 4
	v_mbcnt_lo_u32_b32 v22, -1, 0
	v_mbcnt_hi_u32_b32 v22, -1, v22
	s_and_b32 s0, s0, 0x300
	v_add_u32_e32 v182, s83, v22
	s_lshl_b32 s4, s1, 8
	s_lshl_b32 s94, s0, 1
	v_readlane_b32 s6, v255, 41
	v_ashrrev_i32_e32 v40, 4, v182
	s_add_u32 s6, s6, s94
	v_readlane_b32 s7, v255, 42
	v_lshlrev_b32_e32 v183, 4, v22
	v_add_u32_e32 v2, s4, v40
	s_addc_u32 s7, s7, 0
	v_and_b32_e32 v0, 0xf0, v183
	v_ashrrev_i32_e32 v3, 31, v2
	v_add_u32_e32 v184, 0x200, v182
	v_lshl_add_u64 v[10:11], s[6:7], 0, v[0:1]
	v_lshlrev_b64 v[2:3], 11, v[2:3]
	v_ashrrev_i32_e32 v41, 4, v184
	v_lshl_add_u64 v[6:7], v[10:11], 0, v[2:3]
	v_add_u32_e32 v2, s4, v41
	v_ashrrev_i32_e32 v3, 31, v2
	v_lshlrev_b64 v[2:3], 11, v[2:3]
	v_lshl_add_u64 v[8:9], v[10:11], 0, v[2:3]
	global_load_dwordx4 v[2:5], v[6:7], off
	global_load_dwordx4 v[12:15], v[8:9], off
	v_and_b32_e32 v180, 31, v22
	v_mov_b64_e32 v[16:17], s[88:89]
	v_ashrrev_i32_e32 v181, 5, v22
	v_or_b32_e32 v158, s5, v180
	v_lshlrev_b32_e32 v18, 3, v181
	v_add_u32_e32 v0, 0, v0
	s_movk_i32 s8, 0x110
	v_mad_i64_i32 v[16:17], s[6:7], v158, s87, v[16:17]
	s_or_b32 s5, s4, 64
	v_ashrrev_i32_e32 v19, 31, v18
	v_mad_u64_u32 v[162:163], s[6:7], v40, s8, v[0:1]
	v_mad_u64_u32 v[164:165], s[6:7], v41, s8, v[0:1]
	v_lshl_add_u64 v[160:161], v[16:17], 0, s[94:95]
	v_add_u32_e32 v20, s5, v41
	v_add_u32_e32 v16, s5, v40
	v_lshl_add_u64 v[18:19], v[18:19], 1, v[160:161]
	v_ashrrev_i32_e32 v21, 31, v20
	s_mov_b64 s[6:7], 0x2000
	s_movk_i32 s5, 0x2000
	v_ashrrev_i32_e32 v17, 31, v16
	v_lshl_add_u64 v[166:167], v[18:19], 0, s[6:7]
	v_lshlrev_b64 v[20:21], 11, v[20:21]
	v_add_co_u32_e32 v18, vcc, s5, v18
	v_lshlrev_b64 v[16:17], 11, v[16:17]
	s_nop 0
	v_addc_co_u32_e32 v19, vcc, 0, v19, vcc
	v_lshl_add_u64 v[170:171], v[10:11], 0, v[20:21]
	v_lshl_add_u64 v[168:169], v[10:11], 0, v[16:17]
	v_lshlrev_b32_e32 v0, 1, v22
	v_lshrrev_b32_e32 v20, 1, v22
	v_and_b32_e32 v0, 8, v0
	v_and_b32_e32 v20, 4, v20
	v_and_b32_e32 v21, 19, v22
	v_or3_b32 v0, v0, v21, v20
	v_lshlrev_b32_e32 v36, 4, v181
	v_mul_u32_u24_e32 v20, 0x110, v0
	v_add3_u32 v165, 0, v20, v36
	v_ashrrev_i32_e32 v159, 31, v158
	v_add_u32_e32 v163, 0, v36
	s_waitcnt vmcnt(1)
	ds_write_b128 v162, v[2:5]
	s_waitcnt vmcnt(0)
	ds_write_b128 v164, v[12:15]
	s_waitcnt lgkmcnt(0)
	s_barrier
	global_load_dwordx4 v[12:15], v[170:171], off
	global_load_dwordx4 v[2:5], v[18:19], off
	global_load_dwordx4 v[154:157], v[166:167], off offset:32
	global_load_dwordx4 v[150:153], v[166:167], off offset:64
	global_load_dwordx4 v[146:149], v[166:167], off offset:96
	global_load_dwordx4 v[142:145], v[166:167], off offset:128
	global_load_dwordx4 v[138:141], v[166:167], off offset:160
	global_load_dwordx4 v[134:137], v[166:167], off offset:192
	global_load_dwordx4 v[16:19], v[168:169], off
	global_load_dwordx4 v[130:133], v[166:167], off offset:224
	ds_read_b128 v[20:23], v165
	ds_read_b128 v[24:27], v165 offset:32
	ds_read_b128 v[28:31], v165 offset:8704
	ds_read_b128 v[32:35], v165 offset:8736
	s_waitcnt vmcnt(8) lgkmcnt(3)
	v_mfma_f32_32x32x16_bf16 v[114:129], v[20:23], v[2:5], 0
	v_mad_u32_u24 v0, v0, s8, v163
	s_waitcnt lgkmcnt(1)
	v_mfma_f32_32x32x16_bf16 v[82:97], v[28:31], v[2:5], 0
	s_waitcnt vmcnt(7)
	v_mfma_f32_32x32x16_bf16 v[114:129], v[24:27], v[154:157], v[114:129]
	ds_read_b128 v[20:23], v0 offset:64
	ds_read_b128 v[24:27], v0 offset:96
	ds_read_b128 v[28:31], v0 offset:8768
	ds_read_b128 v[36:39], v0 offset:8800
	s_waitcnt lgkmcnt(4)
	v_mfma_f32_32x32x16_bf16 v[82:97], v[32:35], v[154:157], v[82:97]
	s_waitcnt vmcnt(6) lgkmcnt(3)
	v_mfma_f32_32x32x16_bf16 v[114:129], v[20:23], v[150:153], v[114:129]
	s_waitcnt lgkmcnt(1)
	v_mfma_f32_32x32x16_bf16 v[82:97], v[28:31], v[150:153], v[82:97]
	s_waitcnt vmcnt(5)
	v_mfma_f32_32x32x16_bf16 v[114:129], v[24:27], v[146:149], v[114:129]
	ds_read_b128 v[20:23], v0 offset:128
	ds_read_b128 v[24:27], v0 offset:160
	ds_read_b128 v[28:31], v0 offset:8832
	ds_read_b128 v[32:35], v0 offset:8864
	s_waitcnt lgkmcnt(4)
	v_mfma_f32_32x32x16_bf16 v[82:97], v[36:39], v[146:149], v[82:97]
	s_waitcnt vmcnt(4) lgkmcnt(3)
	v_mfma_f32_32x32x16_bf16 v[114:129], v[20:23], v[142:145], v[114:129]
	s_waitcnt lgkmcnt(1)
	v_mfma_f32_32x32x16_bf16 v[82:97], v[28:31], v[142:145], v[82:97]
	s_waitcnt vmcnt(3)
	v_mfma_f32_32x32x16_bf16 v[114:129], v[24:27], v[138:141], v[114:129]
	ds_read_b128 v[20:23], v0 offset:192
	ds_read_b128 v[24:27], v0 offset:224
	ds_read_b128 v[28:31], v0 offset:8896
	ds_read_b128 v[36:39], v0 offset:8928
	s_waitcnt lgkmcnt(4)
	v_mfma_f32_32x32x16_bf16 v[82:97], v[32:35], v[138:141], v[82:97]
	s_waitcnt vmcnt(2) lgkmcnt(3)
	v_mfma_f32_32x32x16_bf16 v[114:129], v[20:23], v[134:137], v[114:129]
	s_waitcnt lgkmcnt(1)
	v_mfma_f32_32x32x16_bf16 v[82:97], v[28:31], v[134:137], v[82:97]
	s_waitcnt vmcnt(0)
	v_mfma_f32_32x32x16_bf16 v[114:129], v[24:27], v[130:133], v[114:129]
	s_waitcnt lgkmcnt(0)
	v_mfma_f32_32x32x16_bf16 v[82:97], v[36:39], v[130:133], v[82:97]
	s_or_b32 s5, s4, 0x80
	ds_write_b128 v162, v[16:19] offset:18432
	ds_write_b128 v164, v[12:15] offset:18432
	v_add_u32_e32 v12, s5, v40
	v_ashrrev_i32_e32 v13, 31, v12
	v_lshlrev_b64 v[12:13], 11, v[12:13]
	v_lshl_add_u64 v[172:173], v[10:11], 0, v[12:13]
	v_add_u32_e32 v12, s5, v41
	v_ashrrev_i32_e32 v13, 31, v12
	v_lshlrev_b64 v[12:13], 11, v[12:13]
	s_waitcnt lgkmcnt(0)
	s_barrier
	v_lshl_add_u64 v[174:175], v[10:11], 0, v[12:13]
	global_load_dwordx4 v[12:15], v[172:173], off
	global_load_dwordx4 v[16:19], v[174:175], off
	ds_read_b128 v[20:23], v165 offset:18432
	ds_read_b128 v[24:27], v165 offset:18464
	ds_read_b128 v[28:31], v165 offset:27136
	ds_read_b128 v[32:35], v165 offset:27168
	s_waitcnt lgkmcnt(3)
	v_mfma_f32_32x32x16_bf16 v[98:113], v[20:23], v[2:5], 0
	s_waitcnt lgkmcnt(1)
	v_mfma_f32_32x32x16_bf16 v[50:65], v[28:31], v[2:5], 0
	v_mfma_f32_32x32x16_bf16 v[98:113], v[24:27], v[154:157], v[98:113]
	ds_read_b128 v[20:23], v0 offset:18496
	ds_read_b128 v[24:27], v0 offset:18528
	ds_read_b128 v[28:31], v0 offset:27200
	ds_read_b128 v[36:39], v0 offset:27232
	s_waitcnt lgkmcnt(4)
	v_mfma_f32_32x32x16_bf16 v[50:65], v[32:35], v[154:157], v[50:65]
	s_waitcnt lgkmcnt(3)
	v_mfma_f32_32x32x16_bf16 v[98:113], v[20:23], v[150:153], v[98:113]
	s_waitcnt lgkmcnt(1)
	v_mfma_f32_32x32x16_bf16 v[50:65], v[28:31], v[150:153], v[50:65]
	v_mfma_f32_32x32x16_bf16 v[98:113], v[24:27], v[146:149], v[98:113]
	ds_read_b128 v[20:23], v0 offset:18560
	ds_read_b128 v[24:27], v0 offset:18592
	ds_read_b128 v[28:31], v0 offset:27264
	ds_read_b128 v[32:35], v0 offset:27296
	s_waitcnt lgkmcnt(4)
	v_mfma_f32_32x32x16_bf16 v[50:65], v[36:39], v[146:149], v[50:65]
	s_waitcnt lgkmcnt(3)
	v_mfma_f32_32x32x16_bf16 v[98:113], v[20:23], v[142:145], v[98:113]
	s_waitcnt lgkmcnt(1)
	v_mfma_f32_32x32x16_bf16 v[50:65], v[28:31], v[142:145], v[50:65]
	v_mfma_f32_32x32x16_bf16 v[98:113], v[24:27], v[138:141], v[98:113]
	ds_read_b128 v[20:23], v0 offset:18624
	ds_read_b128 v[24:27], v0 offset:18656
	ds_read_b128 v[28:31], v0 offset:27328
	ds_read_b128 v[36:39], v0 offset:27360
	s_waitcnt lgkmcnt(4)
	v_mfma_f32_32x32x16_bf16 v[50:65], v[32:35], v[138:141], v[50:65]
	s_waitcnt lgkmcnt(3)
	v_mfma_f32_32x32x16_bf16 v[98:113], v[20:23], v[134:137], v[98:113]
	s_waitcnt lgkmcnt(1)
	v_mfma_f32_32x32x16_bf16 v[50:65], v[28:31], v[134:137], v[50:65]
	v_mfma_f32_32x32x16_bf16 v[98:113], v[24:27], v[130:133], v[98:113]
	s_waitcnt lgkmcnt(0)
	v_mfma_f32_32x32x16_bf16 v[50:65], v[36:39], v[130:133], v[50:65]
	s_or_b32 s4, s4, 0xc0
	s_waitcnt vmcnt(1)
	ds_write_b128 v162, v[12:15]
	s_waitcnt vmcnt(0)
	ds_write_b128 v164, v[16:19]
	v_add_u32_e32 v12, s4, v40
	v_ashrrev_i32_e32 v13, 31, v12
	v_lshlrev_b64 v[12:13], 11, v[12:13]
	v_lshl_add_u64 v[176:177], v[10:11], 0, v[12:13]
	v_add_u32_e32 v12, s4, v41
	v_ashrrev_i32_e32 v13, 31, v12
	v_lshlrev_b64 v[12:13], 11, v[12:13]
	s_waitcnt lgkmcnt(0)
	s_barrier
	v_lshl_add_u64 v[178:179], v[10:11], 0, v[12:13]
	global_load_dwordx4 v[10:13], v[176:177], off
	global_load_dwordx4 v[14:17], v[178:179], off
	ds_read_b128 v[18:21], v165
	ds_read_b128 v[22:25], v165 offset:32
	ds_read_b128 v[26:29], v165 offset:8704
	ds_read_b128 v[30:33], v165 offset:8736
	s_waitcnt lgkmcnt(3)
	v_mfma_f32_32x32x16_bf16 v[66:81], v[18:21], v[2:5], 0
	s_waitcnt lgkmcnt(1)
	v_mfma_f32_32x32x16_bf16 v[34:49], v[26:29], v[2:5], 0
	v_mfma_f32_32x32x16_bf16 v[66:81], v[22:25], v[154:157], v[66:81]
	ds_read_b128 v[18:21], v0 offset:64
	ds_read_b128 v[22:25], v0 offset:96
	ds_read_b128 v[26:29], v0 offset:8768
	ds_read_b128 v[186:189], v0 offset:8800
	s_waitcnt lgkmcnt(4)
	v_mfma_f32_32x32x16_bf16 v[34:49], v[30:33], v[154:157], v[34:49]
	s_waitcnt lgkmcnt(3)
	v_mfma_f32_32x32x16_bf16 v[66:81], v[18:21], v[150:153], v[66:81]
	s_waitcnt lgkmcnt(1)
	v_mfma_f32_32x32x16_bf16 v[34:49], v[26:29], v[150:153], v[34:49]
	v_mfma_f32_32x32x16_bf16 v[66:81], v[22:25], v[146:149], v[66:81]
	ds_read_b128 v[18:21], v0 offset:128
	ds_read_b128 v[22:25], v0 offset:160
	ds_read_b128 v[26:29], v0 offset:8832
	ds_read_b128 v[30:33], v0 offset:8864
	s_waitcnt lgkmcnt(4)
	v_mfma_f32_32x32x16_bf16 v[34:49], v[186:189], v[146:149], v[34:49]
	s_waitcnt lgkmcnt(3)
	v_mfma_f32_32x32x16_bf16 v[66:81], v[18:21], v[142:145], v[66:81]
	s_waitcnt lgkmcnt(1)
	v_mfma_f32_32x32x16_bf16 v[34:49], v[26:29], v[142:145], v[34:49]
	v_mfma_f32_32x32x16_bf16 v[66:81], v[22:25], v[138:141], v[66:81]
	ds_read_b128 v[18:21], v0 offset:192
	ds_read_b128 v[22:25], v0 offset:224
	ds_read_b128 v[26:29], v0 offset:8896
	ds_read_b128 v[186:189], v0 offset:8928
	s_waitcnt lgkmcnt(4)
	v_mfma_f32_32x32x16_bf16 v[34:49], v[30:33], v[138:141], v[34:49]
	s_waitcnt lgkmcnt(3)
	v_mfma_f32_32x32x16_bf16 v[66:81], v[18:21], v[134:137], v[66:81]
	s_waitcnt lgkmcnt(1)
	v_mfma_f32_32x32x16_bf16 v[34:49], v[26:29], v[134:137], v[34:49]
	v_mfma_f32_32x32x16_bf16 v[66:81], v[22:25], v[130:133], v[66:81]
	s_waitcnt lgkmcnt(0)
	v_mfma_f32_32x32x16_bf16 v[34:49], v[186:189], v[130:133], v[34:49]
	s_waitcnt vmcnt(1)
	ds_write_b128 v162, v[10:13] offset:18432
	s_waitcnt vmcnt(0)
	ds_write_b128 v164, v[14:17] offset:18432
	s_waitcnt lgkmcnt(0)
	s_barrier
	global_load_dwordx4 v[186:189], v[6:7], off offset:256
	global_load_dwordx4 v[190:193], v[8:9], off offset:256
	ds_read_b128 v[6:9], v165 offset:18432
	ds_read_b128 v[204:207], v165 offset:18464
	ds_read_b128 v[10:13], v165 offset:27136
	ds_read_b128 v[208:211], v165 offset:27168
	s_waitcnt lgkmcnt(3)
	v_mfma_f32_32x32x16_bf16 v[18:33], v[6:9], v[2:5], 0
	s_waitcnt lgkmcnt(1)
	v_mfma_f32_32x32x16_bf16 v[2:17], v[10:13], v[2:5], 0
	v_mfma_f32_32x32x16_bf16 v[18:33], v[204:207], v[154:157], v[18:33]
	ds_read_b128 v[204:207], v0 offset:18496
	ds_read_b128 v[212:215], v0 offset:18528
	ds_read_b128 v[216:219], v0 offset:27200
	ds_read_b128 v[228:231], v0 offset:27232
	s_waitcnt lgkmcnt(4)
	v_mfma_f32_32x32x16_bf16 v[2:17], v[208:211], v[154:157], v[2:17]
	s_waitcnt lgkmcnt(3)
	v_mfma_f32_32x32x16_bf16 v[18:33], v[204:207], v[150:153], v[18:33]
	s_waitcnt lgkmcnt(1)
	v_mfma_f32_32x32x16_bf16 v[2:17], v[216:219], v[150:153], v[2:17]
	ds_read_b128 v[150:153], v0 offset:18560
	ds_read_b128 v[154:157], v0 offset:18592
	ds_read_b128 v[204:207], v0 offset:27264
	ds_read_b128 v[208:211], v0 offset:27296
	v_mfma_f32_32x32x16_bf16 v[18:33], v[212:215], v[146:149], v[18:33]
	s_waitcnt lgkmcnt(4)
	v_mfma_f32_32x32x16_bf16 v[2:17], v[228:231], v[146:149], v[2:17]
	s_waitcnt lgkmcnt(3)
	v_mfma_f32_32x32x16_bf16 v[18:33], v[150:153], v[142:145], v[18:33]
	s_waitcnt lgkmcnt(1)
	v_mfma_f32_32x32x16_bf16 v[2:17], v[204:207], v[142:145], v[2:17]
	v_mfma_f32_32x32x16_bf16 v[18:33], v[154:157], v[138:141], v[18:33]
	ds_read_b128 v[142:145], v0 offset:18624
	ds_read_b128 v[146:149], v0 offset:18656
	ds_read_b128 v[150:153], v0 offset:27328
	ds_read_b128 v[154:157], v0 offset:27360
	s_waitcnt lgkmcnt(4)
	v_mfma_f32_32x32x16_bf16 v[2:17], v[208:211], v[138:141], v[2:17]
	s_waitcnt lgkmcnt(3)
	v_mfma_f32_32x32x16_bf16 v[18:33], v[142:145], v[134:137], v[18:33]
	s_waitcnt lgkmcnt(1)
	v_mfma_f32_32x32x16_bf16 v[2:17], v[150:153], v[134:137], v[2:17]
	v_mfma_f32_32x32x16_bf16 v[18:33], v[146:149], v[130:133], v[18:33]
	s_waitcnt lgkmcnt(0)
	v_mfma_f32_32x32x16_bf16 v[2:17], v[154:157], v[130:133], v[2:17]
	s_waitcnt vmcnt(1)
	ds_write_b128 v162, v[186:189]
	s_waitcnt vmcnt(0)
	ds_write_b128 v164, v[190:193]
	s_waitcnt lgkmcnt(0)
	s_barrier
	global_load_dwordx4 v[154:157], v[168:169], off offset:256
	s_nop 0
	global_load_dwordx4 v[168:171], v[170:171], off offset:256
	s_nop 0
	global_load_dwordx4 v[186:189], v[166:167], off offset:256
	global_load_dwordx4 v[190:193], v[166:167], off offset:288
	global_load_dwordx4 v[150:153], v[166:167], off offset:320
	global_load_dwordx4 v[146:149], v[166:167], off offset:352
	global_load_dwordx4 v[142:145], v[166:167], off offset:384
	global_load_dwordx4 v[138:141], v[166:167], off offset:416
	global_load_dwordx4 v[134:137], v[166:167], off offset:448
	global_load_dwordx4 v[130:133], v[166:167], off offset:480
	ds_read_b128 v[204:207], v165
	ds_read_b128 v[208:211], v165 offset:32
	ds_read_b128 v[212:215], v165 offset:8704
	ds_read_b128 v[216:219], v165 offset:8736
	s_waitcnt vmcnt(7) lgkmcnt(3)
	v_mfma_f32_32x32x16_bf16 v[114:129], v[204:207], v[186:189], v[114:129]
	s_waitcnt lgkmcnt(1)
	v_mfma_f32_32x32x16_bf16 v[82:97], v[212:215], v[186:189], v[82:97]
	s_waitcnt vmcnt(6)
	v_mfma_f32_32x32x16_bf16 v[114:129], v[208:211], v[190:193], v[114:129]
	ds_read_b128 v[204:207], v0 offset:64
	ds_read_b128 v[208:211], v0 offset:96
	ds_read_b128 v[212:215], v0 offset:8768
	ds_read_b128 v[228:231], v0 offset:8800
	s_waitcnt lgkmcnt(4)
	v_mfma_f32_32x32x16_bf16 v[82:97], v[216:219], v[190:193], v[82:97]
	s_waitcnt vmcnt(5) lgkmcnt(3)
	v_mfma_f32_32x32x16_bf16 v[114:129], v[204:207], v[150:153], v[114:129]
	s_waitcnt lgkmcnt(1)
	v_mfma_f32_32x32x16_bf16 v[82:97], v[212:215], v[150:153], v[82:97]
	s_waitcnt vmcnt(4)
	v_mfma_f32_32x32x16_bf16 v[114:129], v[208:211], v[146:149], v[114:129]
	ds_read_b128 v[204:207], v0 offset:128
	ds_read_b128 v[208:211], v0 offset:160
	ds_read_b128 v[212:215], v0 offset:8832
	ds_read_b128 v[216:219], v0 offset:8864
	s_waitcnt lgkmcnt(4)
	v_mfma_f32_32x32x16_bf16 v[82:97], v[228:231], v[146:149], v[82:97]
	s_waitcnt vmcnt(3) lgkmcnt(3)
	v_mfma_f32_32x32x16_bf16 v[114:129], v[204:207], v[142:145], v[114:129]
	s_waitcnt lgkmcnt(1)
	v_mfma_f32_32x32x16_bf16 v[82:97], v[212:215], v[142:145], v[82:97]
	s_waitcnt vmcnt(2)
	v_mfma_f32_32x32x16_bf16 v[114:129], v[208:211], v[138:141], v[114:129]
	ds_read_b128 v[204:207], v0 offset:192
	ds_read_b128 v[208:211], v0 offset:224
	ds_read_b128 v[212:215], v0 offset:8896
	ds_read_b128 v[228:231], v0 offset:8928
	s_waitcnt lgkmcnt(4)
	v_mfma_f32_32x32x16_bf16 v[82:97], v[216:219], v[138:141], v[82:97]
	s_waitcnt vmcnt(1) lgkmcnt(3)
	v_mfma_f32_32x32x16_bf16 v[114:129], v[204:207], v[134:137], v[114:129]
	s_waitcnt lgkmcnt(1)
	v_mfma_f32_32x32x16_bf16 v[82:97], v[212:215], v[134:137], v[82:97]
	s_waitcnt vmcnt(0)
	v_mfma_f32_32x32x16_bf16 v[114:129], v[208:211], v[130:133], v[114:129]
	s_waitcnt lgkmcnt(0)
	v_mfma_f32_32x32x16_bf16 v[82:97], v[228:231], v[130:133], v[82:97]
	ds_write_b128 v162, v[154:157] offset:18432
	ds_write_b128 v164, v[168:171] offset:18432
	s_waitcnt lgkmcnt(0)
	s_barrier
	global_load_dwordx4 v[154:157], v[172:173], off offset:256
	global_load_dwordx4 v[166:169], v[174:175], off offset:256
	ds_read_b128 v[170:173], v165 offset:18432
	ds_read_b128 v[204:207], v165 offset:18464
	ds_read_b128 v[208:211], v165 offset:27136
	ds_read_b128 v[212:215], v165 offset:27168
	s_waitcnt lgkmcnt(3)
	v_mfma_f32_32x32x16_bf16 v[98:113], v[170:173], v[186:189], v[98:113]
	s_waitcnt lgkmcnt(1)
	v_mfma_f32_32x32x16_bf16 v[50:65], v[208:211], v[186:189], v[50:65]
	v_mfma_f32_32x32x16_bf16 v[98:113], v[204:207], v[190:193], v[98:113]
	ds_read_b128 v[170:173], v0 offset:18496
	ds_read_b128 v[204:207], v0 offset:18528
	ds_read_b128 v[208:211], v0 offset:27200
	ds_read_b128 v[216:219], v0 offset:27232
	s_waitcnt lgkmcnt(4)
	v_mfma_f32_32x32x16_bf16 v[50:65], v[212:215], v[190:193], v[50:65]
	s_waitcnt lgkmcnt(3)
	v_mfma_f32_32x32x16_bf16 v[98:113], v[170:173], v[150:153], v[98:113]
	s_waitcnt lgkmcnt(1)
	v_mfma_f32_32x32x16_bf16 v[50:65], v[208:211], v[150:153], v[50:65]
	v_mfma_f32_32x32x16_bf16 v[98:113], v[204:207], v[146:149], v[98:113]
	ds_read_b128 v[170:173], v0 offset:18560
	ds_read_b128 v[204:207], v0 offset:18592
	ds_read_b128 v[208:211], v0 offset:27264
	ds_read_b128 v[212:215], v0 offset:27296
	s_waitcnt lgkmcnt(4)
	v_mfma_f32_32x32x16_bf16 v[50:65], v[216:219], v[146:149], v[50:65]
	s_waitcnt lgkmcnt(3)
	v_mfma_f32_32x32x16_bf16 v[98:113], v[170:173], v[142:145], v[98:113]
	s_waitcnt lgkmcnt(1)
	v_mfma_f32_32x32x16_bf16 v[50:65], v[208:211], v[142:145], v[50:65]
	v_mfma_f32_32x32x16_bf16 v[98:113], v[204:207], v[138:141], v[98:113]
	ds_read_b128 v[170:173], v0 offset:18624
	ds_read_b128 v[204:207], v0 offset:18656
	ds_read_b128 v[208:211], v0 offset:27328
	ds_read_b128 v[216:219], v0 offset:27360
	s_waitcnt lgkmcnt(4)
	v_mfma_f32_32x32x16_bf16 v[50:65], v[212:215], v[138:141], v[50:65]
	s_waitcnt lgkmcnt(3)
	v_mfma_f32_32x32x16_bf16 v[98:113], v[170:173], v[134:137], v[98:113]
	s_waitcnt lgkmcnt(1)
	v_mfma_f32_32x32x16_bf16 v[50:65], v[208:211], v[134:137], v[50:65]
	v_mfma_f32_32x32x16_bf16 v[98:113], v[204:207], v[130:133], v[98:113]
	s_waitcnt lgkmcnt(0)
	v_mfma_f32_32x32x16_bf16 v[50:65], v[216:219], v[130:133], v[50:65]
	s_waitcnt vmcnt(1)
	ds_write_b128 v162, v[154:157]
	s_waitcnt vmcnt(0)
	ds_write_b128 v164, v[166:169]
	s_waitcnt lgkmcnt(0)
	s_barrier
	global_load_dwordx4 v[154:157], v[176:177], off offset:256
	global_load_dwordx4 v[166:169], v[178:179], off offset:256
	ds_read_b128 v[170:173], v165
	ds_read_b128 v[174:177], v165 offset:32
	ds_read_b128 v[204:207], v165 offset:8704
	ds_read_b128 v[208:211], v165 offset:8736
	s_waitcnt lgkmcnt(3)
	v_mfma_f32_32x32x16_bf16 v[66:81], v[170:173], v[186:189], v[66:81]
	s_waitcnt lgkmcnt(1)
	v_mfma_f32_32x32x16_bf16 v[34:49], v[204:207], v[186:189], v[34:49]
	v_mfma_f32_32x32x16_bf16 v[66:81], v[174:177], v[190:193], v[66:81]
	ds_read_b128 v[170:173], v0 offset:64
	ds_read_b128 v[174:177], v0 offset:96
	ds_read_b128 v[204:207], v0 offset:8768
	ds_read_b128 v[212:215], v0 offset:8800
	s_waitcnt lgkmcnt(4)
	v_mfma_f32_32x32x16_bf16 v[34:49], v[208:211], v[190:193], v[34:49]
	s_waitcnt lgkmcnt(3)
	v_mfma_f32_32x32x16_bf16 v[66:81], v[170:173], v[150:153], v[66:81]
	s_waitcnt lgkmcnt(1)
	v_mfma_f32_32x32x16_bf16 v[34:49], v[204:207], v[150:153], v[34:49]
	v_mfma_f32_32x32x16_bf16 v[66:81], v[174:177], v[146:149], v[66:81]
	ds_read_b128 v[170:173], v0 offset:128
	ds_read_b128 v[174:177], v0 offset:160
	ds_read_b128 v[204:207], v0 offset:8832
	ds_read_b128 v[208:211], v0 offset:8864
	s_waitcnt lgkmcnt(4)
	v_mfma_f32_32x32x16_bf16 v[34:49], v[212:215], v[146:149], v[34:49]
	s_waitcnt lgkmcnt(3)
	v_mfma_f32_32x32x16_bf16 v[66:81], v[170:173], v[142:145], v[66:81]
	s_waitcnt lgkmcnt(1)
	v_mfma_f32_32x32x16_bf16 v[34:49], v[204:207], v[142:145], v[34:49]
	v_mfma_f32_32x32x16_bf16 v[66:81], v[174:177], v[138:141], v[66:81]
	ds_read_b128 v[170:173], v0 offset:192
	ds_read_b128 v[174:177], v0 offset:224
	ds_read_b128 v[204:207], v0 offset:8896
	ds_read_b128 v[212:215], v0 offset:8928
	s_waitcnt lgkmcnt(4)
	v_mfma_f32_32x32x16_bf16 v[34:49], v[208:211], v[138:141], v[34:49]
	s_waitcnt lgkmcnt(3)
	v_mfma_f32_32x32x16_bf16 v[66:81], v[170:173], v[134:137], v[66:81]
	s_waitcnt lgkmcnt(1)
	v_mfma_f32_32x32x16_bf16 v[34:49], v[204:207], v[134:137], v[34:49]
	v_mfma_f32_32x32x16_bf16 v[66:81], v[174:177], v[130:133], v[66:81]
	s_waitcnt lgkmcnt(0)
	v_mfma_f32_32x32x16_bf16 v[34:49], v[212:215], v[130:133], v[34:49]
	s_waitcnt vmcnt(1)
	ds_write_b128 v162, v[154:157] offset:18432
	s_waitcnt vmcnt(0)
	ds_write_b128 v164, v[166:169] offset:18432
	s_waitcnt lgkmcnt(0)
	s_barrier
	ds_read_b128 v[154:157], v165 offset:18432
	ds_read_b128 v[166:169], v165 offset:18464
	ds_read_b128 v[170:173], v165 offset:27136
	ds_read_b128 v[174:177], v165 offset:27168
	s_waitcnt lgkmcnt(3)
	v_mfma_f32_32x32x16_bf16 v[18:33], v[154:157], v[186:189], v[18:33]
	s_waitcnt lgkmcnt(1)
	v_mfma_f32_32x32x16_bf16 v[2:17], v[170:173], v[186:189], v[2:17]
	v_mfma_f32_32x32x16_bf16 v[18:33], v[166:169], v[190:193], v[18:33]
	ds_read_b128 v[154:157], v0 offset:18496
	ds_read_b128 v[164:167], v0 offset:18528
	ds_read_b128 v[168:171], v0 offset:27200
	ds_read_b128 v[186:189], v0 offset:27232
	s_waitcnt lgkmcnt(4)
	v_mfma_f32_32x32x16_bf16 v[2:17], v[174:177], v[190:193], v[2:17]
	s_waitcnt lgkmcnt(3)
	v_mfma_f32_32x32x16_bf16 v[18:33], v[154:157], v[150:153], v[18:33]
	s_waitcnt lgkmcnt(1)
	v_mfma_f32_32x32x16_bf16 v[2:17], v[168:171], v[150:153], v[2:17]
	v_mfma_f32_32x32x16_bf16 v[18:33], v[164:167], v[146:149], v[18:33]
	ds_read_b128 v[150:153], v0 offset:18560
	ds_read_b128 v[154:157], v0 offset:18592
	ds_read_b128 v[164:167], v0 offset:27264
	ds_read_b128 v[168:171], v0 offset:27296
	s_waitcnt lgkmcnt(4)
	v_mfma_f32_32x32x16_bf16 v[2:17], v[186:189], v[146:149], v[2:17]
	s_waitcnt lgkmcnt(3)
	v_mfma_f32_32x32x16_bf16 v[18:33], v[150:153], v[142:145], v[18:33]
	s_waitcnt lgkmcnt(1)
	v_mfma_f32_32x32x16_bf16 v[2:17], v[164:167], v[142:145], v[2:17]
	v_mfma_f32_32x32x16_bf16 v[18:33], v[154:157], v[138:141], v[18:33]
	ds_read_b128 v[142:145], v0 offset:18624
	ds_read_b128 v[146:149], v0 offset:18656
	ds_read_b128 v[150:153], v0 offset:27328
	ds_read_b128 v[154:157], v0 offset:27360
	s_waitcnt lgkmcnt(4)
	v_mfma_f32_32x32x16_bf16 v[2:17], v[168:171], v[138:141], v[2:17]
	s_waitcnt lgkmcnt(3)
	v_mfma_f32_32x32x16_bf16 v[18:33], v[142:145], v[134:137], v[18:33]
	s_waitcnt lgkmcnt(1)
	v_mfma_f32_32x32x16_bf16 v[2:17], v[150:153], v[134:137], v[2:17]
	v_mfma_f32_32x32x16_bf16 v[18:33], v[146:149], v[130:133], v[18:33]
	s_waitcnt lgkmcnt(0)
	v_mfma_f32_32x32x16_bf16 v[2:17], v[154:157], v[130:133], v[2:17]
	v_max3_f32 v0, v114, s33, v115
	v_max3_f32 v0, v0, v116, v117
	v_max3_f32 v0, v0, v118, v119
	v_max3_f32 v0, v0, v120, v121
	v_max3_f32 v0, v0, v122, v123
	v_max3_f32 v0, v0, v124, v125
	v_max3_f32 v0, v0, v126, v127
	v_max3_f32 v0, v0, v128, v129
	v_max3_f32 v0, v0, v82, v83
	v_max3_f32 v0, v0, v84, v85
	v_max3_f32 v0, v0, v86, v87
	v_max3_f32 v0, v0, v88, v89
	v_max3_f32 v0, v0, v90, v91
	v_max3_f32 v0, v0, v92, v93
	v_max3_f32 v0, v0, v94, v95
	v_max3_f32 v0, v0, v96, v97
	v_max3_f32 v0, v0, v98, v99
	v_max3_f32 v0, v0, v100, v101
	v_max3_f32 v0, v0, v102, v103
	v_max3_f32 v0, v0, v104, v105
	v_max3_f32 v0, v0, v106, v107
	v_max3_f32 v0, v0, v108, v109
	v_max3_f32 v0, v0, v110, v111
	v_max3_f32 v0, v0, v112, v113
	v_max3_f32 v0, v0, v50, v51
	v_max3_f32 v0, v0, v52, v53
	v_max3_f32 v0, v0, v54, v55
	v_max3_f32 v0, v0, v56, v57
	v_max3_f32 v0, v0, v58, v59
	v_max3_f32 v0, v0, v60, v61
	v_max3_f32 v0, v0, v62, v63
	v_max3_f32 v0, v0, v64, v65
	v_max3_f32 v0, v0, v66, v67
	v_max3_f32 v0, v0, v68, v69
	v_max3_f32 v0, v0, v70, v71
	v_max3_f32 v0, v0, v72, v73
	v_max3_f32 v0, v0, v74, v75
	v_max3_f32 v0, v0, v76, v77
	v_max3_f32 v0, v0, v78, v79
	v_max3_f32 v0, v0, v80, v81
	v_max3_f32 v0, v0, v34, v35
	v_max3_f32 v0, v0, v36, v37
	v_max3_f32 v0, v0, v38, v39
	v_max3_f32 v0, v0, v40, v41
	v_max3_f32 v0, v0, v42, v43
	v_max3_f32 v0, v0, v44, v45
	v_max3_f32 v0, v0, v46, v47
	v_max3_f32 v0, v0, v48, v49
	v_max3_f32 v0, v0, v18, v19
	v_max3_f32 v0, v0, v20, v21
	v_max3_f32 v0, v0, v22, v23
	v_max3_f32 v0, v0, v24, v25
	v_max3_f32 v0, v0, v26, v27
	v_max3_f32 v0, v0, v28, v29
	v_max3_f32 v0, v0, v30, v31
	v_max3_f32 v0, v0, v32, v33
	v_max3_f32 v0, v0, v2, v3
	v_max3_f32 v0, v0, v4, v5
	v_max3_f32 v0, v0, v6, v7
	v_max3_f32 v0, v0, v8, v9
	v_max3_f32 v0, v0, v10, v11
	v_max3_f32 v0, v0, v12, v13
	v_max3_f32 v0, v0, v14, v15
	v_max3_f32 v0, v0, v16, v17
	v_mov_b32_e32 v130, v0
	v_mov_b32_e32 v131, v0
	s_nop 1
	v_permlane32_swap_b32_e32 v130, v131
	v_cmp_eq_u32_e32 vcc, v130, v0
	s_lshl_b32 s1, s1, 9
	v_readlane_b32 s4, v255, 43
	v_cndmask_b32_e32 v130, v130, v131, vcc
	v_max_f32_e32 v130, v130, v130
	v_max_f32_e32 v131, v0, v130
	v_mov_b32_e32 v130, v17
	v_pk_mul_f32 v[130:131], v[130:131], s[76:77] op_sel_hi:[1,0]
	v_ashrrev_i32_e32 v166, 3, v182
	v_fma_f32 v0, v114, s76, -v131
	v_exp_f32_e32 v0, v0
	v_fma_f32 v17, v115, s76, -v131
	v_exp_f32_e32 v17, v17
	v_fma_f32 v114, v116, s76, -v131
	v_exp_f32_e32 v115, v114
	v_fma_f32 v114, v117, s76, -v131
	v_exp_f32_e32 v116, v114
	v_fma_f32 v117, v118, s76, -v131
	v_add_f32_e32 v114, 0, v0
	v_exp_f32_e32 v117, v117
	v_fma_f32 v118, v119, s76, -v131
	v_add_f32_e32 v114, v17, v114
	v_exp_f32_e32 v118, v118
	v_fma_f32 v119, v120, s76, -v131
	v_add_f32_e32 v114, v115, v114
	v_exp_f32_e32 v119, v119
	v_fma_f32 v120, v121, s76, -v131
	v_add_f32_e32 v114, v116, v114
	v_exp_f32_e32 v120, v120
	v_add_f32_e32 v114, v117, v114
	v_add_f32_e32 v114, v118, v114
	v_add_f32_e32 v114, v119, v114
	v_add_f32_e32 v121, v120, v114
	v_cvt_pk_bf16_f32 v114, v0, v17
	v_fma_f32 v0, v122, s76, -v131
	v_exp_f32_e32 v0, v0
	v_fma_f32 v17, v123, s76, -v131
	v_cvt_pk_bf16_f32 v115, v115, v116
	v_cvt_pk_bf16_f32 v116, v117, v118
	v_exp_f32_e32 v17, v17
	v_fma_f32 v118, v124, s76, -v131
	v_cvt_pk_bf16_f32 v117, v119, v120
	v_exp_f32_e32 v119, v118
	v_fma_f32 v118, v125, s76, -v131
	v_exp_f32_e32 v120, v118
	v_add_f32_e32 v118, v0, v121
	v_fma_f32 v121, v126, s76, -v131
	v_exp_f32_e32 v121, v121
	v_fma_f32 v122, v127, s76, -v131
	v_add_f32_e32 v118, v17, v118
	v_exp_f32_e32 v122, v122
	v_fma_f32 v123, v128, s76, -v131
	v_add_f32_e32 v118, v119, v118
	v_exp_f32_e32 v123, v123
	v_fma_f32 v124, v129, s76, -v131
	v_add_f32_e32 v118, v120, v118
	v_exp_f32_e32 v124, v124
	v_add_f32_e32 v118, v121, v118
	v_add_f32_e32 v118, v122, v118
	v_add_f32_e32 v118, v123, v118
	v_add_f32_e32 v125, v124, v118
	v_cvt_pk_bf16_f32 v118, v0, v17
	v_fma_f32 v0, v82, s76, -v131
	v_exp_f32_e32 v0, v0
	v_fma_f32 v17, v83, s76, -v131
	v_exp_f32_e32 v17, v17
	v_fma_f32 v82, v84, s76, -v131
	v_exp_f32_e32 v83, v82
	v_fma_f32 v82, v85, s76, -v131
	v_exp_f32_e32 v84, v82
	v_fma_f32 v85, v86, s76, -v131
	v_add_f32_e32 v82, v0, v125
	v_exp_f32_e32 v85, v85
	v_fma_f32 v86, v87, s76, -v131
	v_add_f32_e32 v82, v17, v82
	v_exp_f32_e32 v86, v86
	v_fma_f32 v87, v88, s76, -v131
	v_add_f32_e32 v82, v83, v82
	v_exp_f32_e32 v87, v87
	v_fma_f32 v88, v89, s76, -v131
	v_add_f32_e32 v82, v84, v82
	v_exp_f32_e32 v88, v88
	v_add_f32_e32 v82, v85, v82
	v_add_f32_e32 v82, v86, v82
	v_add_f32_e32 v82, v87, v82
	v_add_f32_e32 v89, v88, v82
	v_cvt_pk_bf16_f32 v82, v0, v17
	v_fma_f32 v0, v90, s76, -v131
	v_exp_f32_e32 v0, v0
	v_fma_f32 v17, v91, s76, -v131
	v_cvt_pk_bf16_f32 v83, v83, v84
	v_cvt_pk_bf16_f32 v84, v85, v86
	v_exp_f32_e32 v17, v17
	v_fma_f32 v86, v92, s76, -v131
	v_cvt_pk_bf16_f32 v85, v87, v88
	v_exp_f32_e32 v87, v86
	v_fma_f32 v86, v93, s76, -v131
	v_exp_f32_e32 v88, v86
	v_add_f32_e32 v86, v0, v89
	v_fma_f32 v89, v94, s76, -v131
	v_exp_f32_e32 v89, v89
	v_fma_f32 v90, v95, s76, -v131
	v_add_f32_e32 v86, v17, v86
	v_exp_f32_e32 v90, v90
	v_fma_f32 v91, v96, s76, -v131
	v_add_f32_e32 v86, v87, v86
	v_exp_f32_e32 v91, v91
	v_fma_f32 v92, v97, s76, -v131
	v_add_f32_e32 v86, v88, v86
	v_exp_f32_e32 v92, v92
	v_add_f32_e32 v86, v89, v86
	v_add_f32_e32 v86, v90, v86
	v_add_f32_e32 v86, v91, v86
	v_add_f32_e32 v93, v92, v86
	v_cvt_pk_bf16_f32 v86, v0, v17
	v_fma_f32 v0, v98, s76, -v131
	v_exp_f32_e32 v0, v0
	v_fma_f32 v17, v99, s76, -v131
	v_cvt_pk_bf16_f32 v87, v87, v88
	v_cvt_pk_bf16_f32 v88, v89, v90
	v_exp_f32_e32 v17, v17
	v_fma_f32 v90, v100, s76, -v131
	v_cvt_pk_bf16_f32 v89, v91, v92
	v_exp_f32_e32 v91, v90
	v_fma_f32 v90, v101, s76, -v131
	v_exp_f32_e32 v92, v90
	v_add_f32_e32 v90, v0, v93
	v_fma_f32 v93, v102, s76, -v131
	v_exp_f32_e32 v93, v93
	v_fma_f32 v94, v103, s76, -v131
	v_add_f32_e32 v90, v17, v90
	v_exp_f32_e32 v94, v94
	v_fma_f32 v95, v104, s76, -v131
	v_add_f32_e32 v90, v91, v90
	v_exp_f32_e32 v95, v95
	v_fma_f32 v96, v105, s76, -v131
	v_add_f32_e32 v90, v92, v90
	v_exp_f32_e32 v96, v96
	v_add_f32_e32 v90, v93, v90
	v_add_f32_e32 v90, v94, v90
	v_add_f32_e32 v90, v95, v90
	v_add_f32_e32 v97, v96, v90
	v_cvt_pk_bf16_f32 v90, v0, v17
	v_fma_f32 v0, v106, s76, -v131
	v_exp_f32_e32 v0, v0
	v_fma_f32 v17, v107, s76, -v131
	v_cvt_pk_bf16_f32 v91, v91, v92
	v_cvt_pk_bf16_f32 v92, v93, v94
	v_exp_f32_e32 v17, v17
	v_fma_f32 v94, v108, s76, -v131
	v_cvt_pk_bf16_f32 v93, v95, v96
	v_exp_f32_e32 v95, v94
	v_fma_f32 v94, v109, s76, -v131
	v_exp_f32_e32 v96, v94
	v_add_f32_e32 v94, v0, v97
	v_fma_f32 v97, v110, s76, -v131
	v_exp_f32_e32 v97, v97
	v_fma_f32 v98, v111, s76, -v131
	v_add_f32_e32 v94, v17, v94
	v_exp_f32_e32 v98, v98
	v_fma_f32 v99, v112, s76, -v131
	v_add_f32_e32 v94, v95, v94
	v_exp_f32_e32 v99, v99
	v_fma_f32 v100, v113, s76, -v131
	v_add_f32_e32 v94, v96, v94
	v_exp_f32_e32 v100, v100
	v_add_f32_e32 v94, v97, v94
	v_add_f32_e32 v94, v98, v94
	v_add_f32_e32 v94, v99, v94
	v_add_f32_e32 v101, v100, v94
	v_cvt_pk_bf16_f32 v94, v0, v17
	v_fma_f32 v0, v50, s76, -v131
	v_exp_f32_e32 v0, v0
	v_fma_f32 v17, v51, s76, -v131
	v_exp_f32_e32 v17, v17
	v_fma_f32 v50, v52, s76, -v131
	v_exp_f32_e32 v50, v50
	v_fma_f32 v51, v53, s76, -v131
	v_exp_f32_e32 v51, v51
	v_fma_f32 v53, v54, s76, -v131
	v_add_f32_e32 v52, v0, v101
	v_exp_f32_e32 v53, v53
	v_fma_f32 v54, v55, s76, -v131
	v_add_f32_e32 v52, v17, v52
	v_exp_f32_e32 v54, v54
	v_fma_f32 v55, v56, s76, -v131
	v_add_f32_e32 v52, v50, v52
	v_exp_f32_e32 v55, v55
	v_fma_f32 v56, v57, s76, -v131
	v_cvt_pk_bf16_f32 v95, v95, v96
	v_cvt_pk_bf16_f32 v96, v97, v98
	v_add_f32_e32 v52, v51, v52
	v_exp_f32_e32 v56, v56
	v_cvt_pk_bf16_f32 v98, v0, v17
	v_fma_f32 v0, v58, s76, -v131
	v_add_f32_e32 v52, v53, v52
	v_exp_f32_e32 v0, v0
	v_fma_f32 v17, v59, s76, -v131
	v_cvt_pk_bf16_f32 v97, v99, v100
	v_add_f32_e32 v52, v54, v52
	v_cvt_pk_bf16_f32 v99, v50, v51
	v_exp_f32_e32 v17, v17
	v_fma_f32 v50, v60, s76, -v131
	v_add_f32_e32 v52, v55, v52
	v_exp_f32_e32 v50, v50
	v_fma_f32 v51, v61, s76, -v131
	v_add_f32_e32 v52, v56, v52
	v_cvt_pk_bf16_f32 v100, v53, v54
	v_exp_f32_e32 v51, v51
	v_fma_f32 v53, v62, s76, -v131
	v_add_f32_e32 v52, v0, v52
	v_exp_f32_e32 v53, v53
	v_fma_f32 v54, v63, s76, -v131
	v_cvt_pk_bf16_f32 v101, v55, v56
	v_add_f32_e32 v52, v17, v52
	v_exp_f32_e32 v54, v54
	v_fma_f32 v55, v64, s76, -v131
	v_add_f32_e32 v52, v50, v52
	v_exp_f32_e32 v55, v55
	v_fma_f32 v56, v65, s76, -v131
	v_add_f32_e32 v52, v51, v52
	v_exp_f32_e32 v56, v56
	v_cvt_pk_bf16_f32 v102, v0, v17
	v_fma_f32 v0, v66, s76, -v131
	v_add_f32_e32 v52, v53, v52
	v_exp_f32_e32 v0, v0
	v_fma_f32 v17, v67, s76, -v131
	v_add_f32_e32 v52, v54, v52
	v_cvt_pk_bf16_f32 v103, v50, v51
	v_exp_f32_e32 v17, v17
	v_fma_f32 v50, v68, s76, -v131
	v_add_f32_e32 v52, v55, v52
	v_exp_f32_e32 v50, v50
	v_fma_f32 v51, v69, s76, -v131
	v_add_f32_e32 v52, v56, v52
	v_cvt_pk_bf16_f32 v104, v53, v54
	v_exp_f32_e32 v51, v51
	v_fma_f32 v53, v70, s76, -v131
	v_add_f32_e32 v52, v0, v52
	v_exp_f32_e32 v53, v53
	v_fma_f32 v54, v71, s76, -v131
	v_cvt_pk_bf16_f32 v105, v55, v56
	v_add_f32_e32 v52, v17, v52
	v_exp_f32_e32 v54, v54
	v_fma_f32 v55, v72, s76, -v131
	v_add_f32_e32 v52, v50, v52
	v_exp_f32_e32 v55, v55
	v_fma_f32 v56, v73, s76, -v131
	v_add_f32_e32 v52, v51, v52
	v_exp_f32_e32 v56, v56
	v_cvt_pk_bf16_f32 v66, v0, v17
	v_fma_f32 v0, v74, s76, -v131
	v_add_f32_e32 v52, v53, v52
	v_exp_f32_e32 v0, v0
	v_fma_f32 v17, v75, s76, -v131
	v_add_f32_e32 v52, v54, v52
	v_cvt_pk_bf16_f32 v67, v50, v51
	v_exp_f32_e32 v17, v17
	v_fma_f32 v50, v76, s76, -v131
	v_add_f32_e32 v52, v55, v52
	v_exp_f32_e32 v50, v50
	v_fma_f32 v51, v77, s76, -v131
	v_add_f32_e32 v52, v56, v52
	v_cvt_pk_bf16_f32 v68, v53, v54
	v_exp_f32_e32 v51, v51
	v_fma_f32 v53, v78, s76, -v131
	v_add_f32_e32 v52, v0, v52
	v_exp_f32_e32 v53, v53
	v_fma_f32 v54, v79, s76, -v131
	v_cvt_pk_bf16_f32 v69, v55, v56
	v_add_f32_e32 v52, v17, v52
	v_exp_f32_e32 v54, v54
	v_fma_f32 v55, v80, s76, -v131
	v_add_f32_e32 v52, v50, v52
	v_exp_f32_e32 v55, v55
	v_fma_f32 v56, v81, s76, -v131
	v_add_f32_e32 v52, v51, v52
	v_exp_f32_e32 v56, v56
	v_cvt_pk_bf16_f32 v70, v0, v17
	v_fma_f32 v0, v34, s76, -v131
	v_add_f32_e32 v52, v53, v52
	v_exp_f32_e32 v0, v0
	v_fma_f32 v17, v35, s76, -v131
	v_add_f32_e32 v52, v54, v52
	v_exp_f32_e32 v17, v17
	v_fma_f32 v34, v36, s76, -v131
	v_add_f32_e32 v52, v55, v52
	v_exp_f32_e32 v34, v34
	v_fma_f32 v35, v37, s76, -v131
	v_add_f32_e32 v52, v56, v52
	v_exp_f32_e32 v35, v35
	v_fma_f32 v37, v38, s76, -v131
	v_add_f32_e32 v36, v0, v52
	v_exp_f32_e32 v37, v37
	v_fma_f32 v38, v39, s76, -v131
	v_add_f32_e32 v36, v17, v36
	v_exp_f32_e32 v38, v38
	v_fma_f32 v39, v40, s76, -v131
	v_add_f32_e32 v36, v34, v36
	v_exp_f32_e32 v39, v39
	v_fma_f32 v40, v41, s76, -v131
	v_add_f32_e32 v36, v35, v36
	v_exp_f32_e32 v40, v40
	v_cvt_pk_bf16_f32 v74, v0, v17
	v_fma_f32 v0, v42, s76, -v131
	v_add_f32_e32 v36, v37, v36
	v_exp_f32_e32 v17, v0
	v_cvt_pk_bf16_f32 v75, v34, v35
	v_fma_f32 v34, v43, s76, -v131
	v_add_f32_e32 v36, v38, v36
	v_exp_f32_e32 v42, v34
	v_fma_f32 v34, v44, s76, -v131
	v_add_f32_e32 v36, v39, v36
	v_exp_f32_e32 v43, v34
	v_fma_f32 v34, v45, s76, -v131
	v_add_f32_e32 v36, v40, v36
	v_exp_f32_e32 v44, v34
	v_fma_f32 v34, v46, s76, -v131
	v_add_f32_e32 v0, v17, v36
	v_exp_f32_e32 v45, v34
	v_add_f32_e32 v0, v42, v0
	v_add_f32_e32 v0, v43, v0
	v_add_f32_e32 v0, v44, v0
	v_add_f32_e32 v46, v45, v0
	v_fma_f32 v0, v47, s76, -v131
	v_exp_f32_e32 v47, v0
	v_fma_f32 v0, v48, s76, -v131
	v_ashrrev_i32_e32 v167, 3, v184
	v_cvt_pk_bf16_f32 v76, v37, v38
	v_exp_f32_e32 v48, v0
	v_fma_f32 v0, v49, s76, -v131
	s_add_u32 s4, s4, s1
	v_readlane_b32 s1, v255, 44
	v_add_u32_e32 v34, s0, v166
	v_add_u32_e32 v38, s0, v167
	v_cvt_pk_bf16_f32 v77, v39, v40
	v_exp_f32_e32 v49, v0
	s_addc_u32 s5, s1, 0
	v_and_b32_e32 v0, 0x70, v183
	v_ashrrev_i32_e32 v35, 31, v34
	v_ashrrev_i32_e32 v39, 31, v38
	v_lshl_add_u64 v[140:141], s[4:5], 0, v[0:1]
	v_lshlrev_b64 v[34:35], 11, v[34:35]
	v_lshlrev_b64 v[38:39], 11, v[38:39]
	v_lshl_add_u64 v[138:139], v[140:141], 0, v[34:35]
	v_lshl_add_u64 v[142:143], v[140:141], 0, v[38:39]
	s_barrier
	global_load_dwordx4 v[34:37], v[138:139], off
	global_load_dwordx4 v[38:41], v[142:143], off
	v_add_u32_e32 v0, 0, v0
	v_mad_u64_u32 v[132:133], s[4:5], v166, s86, v[0:1]
	v_mad_u64_u32 v[134:135], s[4:5], v167, s86, v[0:1]
	v_cvt_pk_bf16_f32 v78, v17, v42
	v_fma_f32 v17, v18, s76, -v131
	v_exp_f32_e32 v17, v17
	v_fma_f32 v18, v19, s76, -v131
	v_add_f32_e32 v46, v47, v46
	v_exp_f32_e32 v18, v18
	v_fma_f32 v19, v20, s76, -v131
	v_add_f32_e32 v46, v48, v46
	v_exp_f32_e32 v19, v19
	v_fma_f32 v20, v21, s76, -v131
	v_add_f32_e32 v46, v49, v46
	v_exp_f32_e32 v20, v20
	v_fma_f32 v22, v22, s76, -v131
	v_add_f32_e32 v21, v17, v46
	v_exp_f32_e32 v22, v22
	v_fma_f32 v23, v23, s76, -v131
	v_add_f32_e32 v21, v18, v21
	v_exp_f32_e32 v23, v23
	v_fma_f32 v24, v24, s76, -v131
	v_add_f32_e32 v21, v19, v21
	v_exp_f32_e32 v24, v24
	v_fma_f32 v25, v25, s76, -v131
	v_add_f32_e32 v21, v20, v21
	v_exp_f32_e32 v25, v25
	v_cvt_pk_bf16_f32 v106, v17, v18
	v_fma_f32 v17, v26, s76, -v131
	v_add_f32_e32 v21, v22, v21
	v_exp_f32_e32 v17, v17
	v_fma_f32 v18, v27, s76, -v131
	v_add_f32_e32 v21, v23, v21
	v_cvt_pk_bf16_f32 v107, v19, v20
	v_exp_f32_e32 v18, v18
	v_fma_f32 v19, v28, s76, -v131
	v_add_f32_e32 v21, v24, v21
	v_exp_f32_e32 v19, v19
	v_fma_f32 v20, v29, s76, -v131
	v_add_f32_e32 v21, v25, v21
	v_cvt_pk_bf16_f32 v108, v22, v23
	v_exp_f32_e32 v20, v20
	v_fma_f32 v22, v30, s76, -v131
	v_add_f32_e32 v21, v17, v21
	v_exp_f32_e32 v22, v22
	v_fma_f32 v23, v31, s76, -v131
	v_cvt_pk_bf16_f32 v109, v24, v25
	v_add_f32_e32 v21, v18, v21
	v_exp_f32_e32 v23, v23
	v_fma_f32 v24, v32, s76, -v131
	v_add_f32_e32 v21, v19, v21
	v_exp_f32_e32 v24, v24
	v_fma_f32 v25, v33, s76, -v131
	v_add_f32_e32 v21, v20, v21
	v_exp_f32_e32 v25, v25
	v_fma_f32 v2, v2, s76, -v131
	v_add_f32_e32 v21, v22, v21
	v_exp_f32_e32 v2, v2
	v_fma_f32 v3, v3, s76, -v131
	v_add_f32_e32 v21, v23, v21
	v_exp_f32_e32 v3, v3
	v_fma_f32 v4, v4, s76, -v131
	v_add_f32_e32 v21, v24, v21
	v_exp_f32_e32 v4, v4
	v_fma_f32 v5, v5, s76, -v131
	v_add_f32_e32 v21, v25, v21
	v_exp_f32_e32 v5, v5
	v_fma_f32 v6, v6, s76, -v131
	v_cvt_pk_bf16_f32 v110, v17, v18
	v_add_f32_e32 v17, v2, v21
	v_exp_f32_e32 v6, v6
	v_fma_f32 v7, v7, s76, -v131
	v_add_f32_e32 v17, v3, v17
	v_exp_f32_e32 v7, v7
	v_fma_f32 v8, v8, s76, -v131
	v_add_f32_e32 v0, v4, v17
	s_waitcnt vmcnt(1)
	ds_write_b128 v132, v[34:37]
	s_waitcnt vmcnt(0)
	ds_write_b128 v134, v[38:41]
	s_waitcnt lgkmcnt(0)
	s_barrier
	global_load_dwordx4 v[146:149], v[138:139], off offset:128
	global_load_dwordx4 v[150:153], v[142:143], off offset:128
	v_exp_f32_e32 v8, v8
	v_fma_f32 v9, v9, s76, -v131
	v_cvt_pk_bf16_f32 v119, v119, v120
	v_cvt_pk_bf16_f32 v120, v121, v122
	v_add_f32_e32 v0, v5, v0
	v_exp_f32_e32 v9, v9
	v_cvt_pk_bf16_f32 v122, v2, v3
	v_fma_f32 v2, v10, s76, -v131
	v_add_f32_e32 v0, v6, v0
	v_exp_f32_e32 v2, v2
	v_fma_f32 v3, v11, s76, -v131
	v_cvt_pk_bf16_f32 v121, v123, v124
	v_add_f32_e32 v0, v7, v0
	v_cvt_pk_bf16_f32 v123, v4, v5
	v_exp_f32_e32 v3, v3
	v_fma_f32 v4, v12, s76, -v131
	v_add_f32_e32 v0, v8, v0
	v_exp_f32_e32 v4, v4
	v_fma_f32 v5, v13, s76, -v131
	v_add_f32_e32 v0, v9, v0
	v_cvt_pk_bf16_f32 v124, v6, v7
	v_exp_f32_e32 v5, v5
	v_fma_f32 v6, v14, s76, -v131
	v_add_f32_e32 v0, v2, v0
	v_exp_f32_e32 v6, v6
	v_fma_f32 v7, v15, s76, -v131
	v_cvt_pk_bf16_f32 v125, v8, v9
	v_add_f32_e32 v0, v3, v0
	v_exp_f32_e32 v7, v7
	v_fma_f32 v8, v16, s76, -v131
	v_add_f32_e32 v0, v4, v0
	v_exp_f32_e32 v8, v8
	v_sub_f32_e32 v9, v130, v131
	v_add_f32_e32 v0, v5, v0
	v_exp_f32_e32 v9, v9
	v_add_f32_e32 v0, v6, v0
	v_add_f32_e32 v0, v7, v0
	v_add_f32_e32 v0, v8, v0
	v_add_f32_e32 v0, v9, v0
	v_cvt_pk_bf16_f32 v126, v2, v3
	v_mov_b32_e32 v2, v0
	v_mov_b32_e32 v3, v0
	s_nop 1
	v_permlane32_swap_b32_e32 v2, v3
	v_cmp_eq_u32_e32 vcc, v2, v0
	v_cvt_pk_bf16_f32 v127, v4, v5
	v_cvt_pk_bf16_f32 v128, v6, v7
	v_cndmask_b32_e32 v2, v2, v3, vcc
	v_add_f32_e32 v0, v0, v2
	v_div_scale_f32 v2, s[4:5], v0, v0, 1.0
	v_rcp_f32_e32 v3, v2
	v_mad_u32_u24 v133, v180, s86, v163
	v_cvt_pk_bf16_f32 v129, v8, v9
	v_lshlrev_b32_e32 v18, 2, v181
	v_fma_f32 v4, -v2, v3, 1.0
	v_fmac_f32_e32 v3, v4, v3
	v_div_scale_f32 v4, vcc, 1.0, v0, 1.0
	v_mul_f32_e32 v5, v4, v3
	v_fma_f32 v6, -v2, v5, v4
	v_fmac_f32_e32 v5, v6, v3
	v_fma_f32 v2, -v2, v5, v4
	v_div_fmas_f32 v2, v2, v3, v5
	v_div_fixup_f32 v0, v2, v0, 1.0
	ds_read_b128 v[2:5], v133
	ds_read_b128 v[6:9], v133 offset:4608
	ds_read_b128 v[10:13], v133 offset:9216
	ds_read_b128 v[14:17], v133 offset:13824
	v_cvt_pk_bf16_f32 v111, v19, v20
	v_ashrrev_i32_e32 v19, 31, v18
	v_lshl_add_u64 v[144:145], v[18:19], 1, v[160:161]
	s_mov_b64 s[4:5], 0x4800
	v_lshl_add_u64 v[136:137], v[144:145], 0, s[4:5]
	v_readlane_b32 s4, v255, 45
	v_add_u32_e32 v130, s0, v18
	v_lshlrev_b64 v[18:19], 11, v[158:159]
	v_readlane_b32 s5, v255, 46
	v_cvt_pk_bf16_f32 v71, v50, v51
	v_cvt_pk_bf16_f32 v72, v53, v54
	v_cvt_pk_bf16_f32 v73, v55, v56
	v_cvt_pk_bf16_f32 v79, v43, v44
	v_cvt_pk_bf16_f32 v80, v45, v47
	v_cvt_pk_bf16_f32 v81, v48, v49
	v_cvt_pk_bf16_f32 v112, v22, v23
	v_cvt_pk_bf16_f32 v113, v24, v25
	v_lshl_add_u64 v[168:169], s[4:5], 0, v[18:19]
	ds_read_b128 v[154:157], v133 offset:32
	ds_read_b128 v[158:161], v133 offset:4640
	ds_read_b128 v[162:165], v133 offset:9248
	ds_read_b128 v[170:173], v133 offset:13856
	s_waitcnt lgkmcnt(7)
	v_mfma_f32_32x32x16_bf16 v[50:65], v[2:5], v[114:117], 0
	s_waitcnt lgkmcnt(6)
	v_mfma_f32_32x32x16_bf16 v[34:49], v[6:9], v[114:117], 0
	s_waitcnt lgkmcnt(5)
	v_mfma_f32_32x32x16_bf16 v[18:33], v[10:13], v[114:117], 0
	s_waitcnt lgkmcnt(4)
	v_mfma_f32_32x32x16_bf16 v[2:17], v[14:17], v[114:117], 0
	s_waitcnt lgkmcnt(3)
	v_mfma_f32_32x32x16_bf16 v[50:65], v[154:157], v[118:121], v[50:65]
	s_waitcnt lgkmcnt(2)
	v_mfma_f32_32x32x16_bf16 v[34:49], v[158:161], v[118:121], v[34:49]
	s_waitcnt lgkmcnt(1)
	v_mfma_f32_32x32x16_bf16 v[18:33], v[162:165], v[118:121], v[18:33]
	ds_read_b128 v[154:157], v133 offset:64
	ds_read_b128 v[158:161], v133 offset:4672
	ds_read_b128 v[162:165], v133 offset:9280
	ds_read_b128 v[174:177], v133 offset:13888
	s_waitcnt lgkmcnt(4)
	v_mfma_f32_32x32x16_bf16 v[2:17], v[170:173], v[118:121], v[2:17]
	s_waitcnt lgkmcnt(3)
	v_mfma_f32_32x32x16_bf16 v[50:65], v[154:157], v[82:85], v[50:65]
	s_waitcnt lgkmcnt(2)
	v_mfma_f32_32x32x16_bf16 v[34:49], v[158:161], v[82:85], v[34:49]
	s_waitcnt lgkmcnt(1)
	v_mfma_f32_32x32x16_bf16 v[18:33], v[162:165], v[82:85], v[18:33]
	ds_read_b128 v[154:157], v133 offset:96
	ds_read_b128 v[158:161], v133 offset:4704
	ds_read_b128 v[162:165], v133 offset:9312
	ds_read_b128 v[170:173], v133 offset:13920
	s_waitcnt lgkmcnt(4)
	v_mfma_f32_32x32x16_bf16 v[2:17], v[174:177], v[82:85], v[2:17]
	s_waitcnt lgkmcnt(3)
	v_mfma_f32_32x32x16_bf16 v[50:65], v[154:157], v[86:89], v[50:65]
	s_waitcnt lgkmcnt(2)
	v_mfma_f32_32x32x16_bf16 v[34:49], v[158:161], v[86:89], v[34:49]
	s_waitcnt lgkmcnt(1)
	v_mfma_f32_32x32x16_bf16 v[18:33], v[162:165], v[86:89], v[18:33]
	s_waitcnt lgkmcnt(0)
	v_mfma_f32_32x32x16_bf16 v[2:17], v[170:173], v[86:89], v[2:17]
	s_waitcnt vmcnt(1)
	ds_write_b128 v132, v[146:149] offset:18432
	s_waitcnt vmcnt(0)
	ds_write_b128 v134, v[150:153] offset:18432
	s_waitcnt lgkmcnt(0)
	s_barrier
	global_load_dwordx4 v[146:149], v[138:139], off offset:256
	global_load_dwordx4 v[150:153], v[142:143], off offset:256
	ds_read_b128 v[154:157], v133 offset:18432
	ds_read_b128 v[158:161], v133 offset:23040
	ds_read_b128 v[162:165], v133 offset:27648
	ds_read_b128 v[170:173], v133 offset:32256
	s_waitcnt lgkmcnt(3)
	v_mfma_f32_32x32x16_bf16 v[50:65], v[154:157], v[90:93], v[50:65]
	s_waitcnt lgkmcnt(2)
	v_mfma_f32_32x32x16_bf16 v[34:49], v[158:161], v[90:93], v[34:49]
	s_waitcnt lgkmcnt(1)
	v_mfma_f32_32x32x16_bf16 v[18:33], v[162:165], v[90:93], v[18:33]
	ds_read_b128 v[154:157], v133 offset:18464
	ds_read_b128 v[158:161], v133 offset:23072
	ds_read_b128 v[162:165], v133 offset:27680
	ds_read_b128 v[174:177], v133 offset:32288
	s_waitcnt lgkmcnt(4)
	v_mfma_f32_32x32x16_bf16 v[2:17], v[170:173], v[90:93], v[2:17]
	s_waitcnt lgkmcnt(3)
	v_mfma_f32_32x32x16_bf16 v[50:65], v[154:157], v[94:97], v[50:65]
	s_waitcnt lgkmcnt(2)
	v_mfma_f32_32x32x16_bf16 v[34:49], v[158:161], v[94:97], v[34:49]
	s_waitcnt lgkmcnt(1)
	v_mfma_f32_32x32x16_bf16 v[18:33], v[162:165], v[94:97], v[18:33]
	ds_read_b128 v[154:157], v133 offset:18496
	ds_read_b128 v[158:161], v133 offset:23104
	ds_read_b128 v[162:165], v133 offset:27712
	ds_read_b128 v[170:173], v133 offset:32320
	s_waitcnt lgkmcnt(4)
	v_mfma_f32_32x32x16_bf16 v[2:17], v[174:177], v[94:97], v[2:17]
	s_waitcnt lgkmcnt(3)
	v_mfma_f32_32x32x16_bf16 v[50:65], v[154:157], v[98:101], v[50:65]
	s_waitcnt lgkmcnt(2)
	v_mfma_f32_32x32x16_bf16 v[34:49], v[158:161], v[98:101], v[34:49]
	s_waitcnt lgkmcnt(1)
	v_mfma_f32_32x32x16_bf16 v[18:33], v[162:165], v[98:101], v[18:33]
	ds_read_b128 v[154:157], v133 offset:18528
	ds_read_b128 v[158:161], v133 offset:23136
	ds_read_b128 v[162:165], v133 offset:27744
	ds_read_b128 v[174:177], v133 offset:32352
	s_waitcnt lgkmcnt(4)
	v_mfma_f32_32x32x16_bf16 v[2:17], v[170:173], v[98:101], v[2:17]
	s_waitcnt lgkmcnt(3)
	v_mfma_f32_32x32x16_bf16 v[50:65], v[154:157], v[102:105], v[50:65]
	s_waitcnt lgkmcnt(2)
	v_mfma_f32_32x32x16_bf16 v[34:49], v[158:161], v[102:105], v[34:49]
	s_waitcnt lgkmcnt(1)
	v_mfma_f32_32x32x16_bf16 v[18:33], v[162:165], v[102:105], v[18:33]
	s_waitcnt lgkmcnt(0)
	v_mfma_f32_32x32x16_bf16 v[2:17], v[174:177], v[102:105], v[2:17]
	s_waitcnt vmcnt(1)
	ds_write_b128 v132, v[146:149]
	s_waitcnt vmcnt(0)
	ds_write_b128 v134, v[150:153]
	s_waitcnt lgkmcnt(0)
	s_barrier
	global_load_dwordx4 v[146:149], v[138:139], off offset:384
	global_load_dwordx4 v[150:153], v[142:143], off offset:384
	ds_read_b128 v[154:157], v133
	ds_read_b128 v[158:161], v133 offset:4608
	ds_read_b128 v[162:165], v133 offset:9216
	ds_read_b128 v[170:173], v133 offset:13824
	s_waitcnt lgkmcnt(3)
	v_mfma_f32_32x32x16_bf16 v[50:65], v[154:157], v[66:69], v[50:65]
	s_waitcnt lgkmcnt(2)
	v_mfma_f32_32x32x16_bf16 v[34:49], v[158:161], v[66:69], v[34:49]
	s_waitcnt lgkmcnt(1)
	v_mfma_f32_32x32x16_bf16 v[18:33], v[162:165], v[66:69], v[18:33]
	ds_read_b128 v[154:157], v133 offset:32
	ds_read_b128 v[158:161], v133 offset:4640
	ds_read_b128 v[162:165], v133 offset:9248
	ds_read_b128 v[174:177], v133 offset:13856
	s_waitcnt lgkmcnt(4)
	v_mfma_f32_32x32x16_bf16 v[2:17], v[170:173], v[66:69], v[2:17]
	s_waitcnt lgkmcnt(3)
	v_mfma_f32_32x32x16_bf16 v[50:65], v[154:157], v[70:73], v[50:65]
	s_waitcnt lgkmcnt(2)
	v_mfma_f32_32x32x16_bf16 v[34:49], v[158:161], v[70:73], v[34:49]
	s_waitcnt lgkmcnt(1)
	v_mfma_f32_32x32x16_bf16 v[18:33], v[162:165], v[70:73], v[18:33]
	ds_read_b128 v[154:157], v133 offset:64
	ds_read_b128 v[158:161], v133 offset:4672
	ds_read_b128 v[162:165], v133 offset:9280
	ds_read_b128 v[170:173], v133 offset:13888
	s_waitcnt lgkmcnt(4)
	v_mfma_f32_32x32x16_bf16 v[2:17], v[174:177], v[70:73], v[2:17]
	s_waitcnt lgkmcnt(3)
	v_mfma_f32_32x32x16_bf16 v[50:65], v[154:157], v[74:77], v[50:65]
	s_waitcnt lgkmcnt(2)
	v_mfma_f32_32x32x16_bf16 v[34:49], v[158:161], v[74:77], v[34:49]
	s_waitcnt lgkmcnt(1)
	v_mfma_f32_32x32x16_bf16 v[18:33], v[162:165], v[74:77], v[18:33]
	ds_read_b128 v[154:157], v133 offset:96
	ds_read_b128 v[158:161], v133 offset:4704
	ds_read_b128 v[162:165], v133 offset:9312
	ds_read_b128 v[174:177], v133 offset:13920
	s_waitcnt lgkmcnt(4)
	v_mfma_f32_32x32x16_bf16 v[2:17], v[170:173], v[74:77], v[2:17]
	s_waitcnt lgkmcnt(3)
	v_mfma_f32_32x32x16_bf16 v[50:65], v[154:157], v[78:81], v[50:65]
	s_waitcnt lgkmcnt(2)
	v_mfma_f32_32x32x16_bf16 v[34:49], v[158:161], v[78:81], v[34:49]
	s_waitcnt lgkmcnt(1)
	v_mfma_f32_32x32x16_bf16 v[18:33], v[162:165], v[78:81], v[18:33]
	s_waitcnt lgkmcnt(0)
	v_mfma_f32_32x32x16_bf16 v[2:17], v[174:177], v[78:81], v[2:17]
	s_bitset1_b32 s0, 7
	v_add_u32_e32 v138, s0, v166
	v_ashrrev_i32_e32 v139, 31, v138
	v_add_u32_e32 v142, s0, v167
	v_lshlrev_b64 v[138:139], 11, v[138:139]
	v_ashrrev_i32_e32 v143, 31, v142
	v_lshl_add_u64 v[138:139], v[140:141], 0, v[138:139]
	v_lshlrev_b64 v[142:143], 11, v[142:143]
	s_waitcnt vmcnt(1)
	ds_write_b128 v132, v[146:149] offset:18432
	s_waitcnt vmcnt(0)
	ds_write_b128 v134, v[150:153] offset:18432
	s_waitcnt lgkmcnt(0)
	s_barrier
	v_lshl_add_u64 v[140:141], v[140:141], 0, v[142:143]
	global_load_dwordx4 v[146:149], v[138:139], off
	global_load_dwordx4 v[150:153], v[140:141], off
	ds_read_b128 v[154:157], v133 offset:18432
	ds_read_b128 v[158:161], v133 offset:23040
	ds_read_b128 v[162:165], v133 offset:27648
	ds_read_b128 v[170:173], v133 offset:32256
	s_waitcnt lgkmcnt(3)
	v_mfma_f32_32x32x16_bf16 v[50:65], v[154:157], v[106:109], v[50:65]
	s_waitcnt lgkmcnt(2)
	v_mfma_f32_32x32x16_bf16 v[34:49], v[158:161], v[106:109], v[34:49]
	s_waitcnt lgkmcnt(1)
	v_mfma_f32_32x32x16_bf16 v[18:33], v[162:165], v[106:109], v[18:33]
	ds_read_b128 v[154:157], v133 offset:18464
	ds_read_b128 v[158:161], v133 offset:23072
	ds_read_b128 v[162:165], v133 offset:27680
	ds_read_b128 v[174:177], v133 offset:32288
	s_waitcnt lgkmcnt(4)
	v_mfma_f32_32x32x16_bf16 v[2:17], v[170:173], v[106:109], v[2:17]
	s_waitcnt lgkmcnt(3)
	v_mfma_f32_32x32x16_bf16 v[50:65], v[154:157], v[110:113], v[50:65]
	s_waitcnt lgkmcnt(2)
	v_mfma_f32_32x32x16_bf16 v[34:49], v[158:161], v[110:113], v[34:49]
	s_waitcnt lgkmcnt(1)
	v_mfma_f32_32x32x16_bf16 v[18:33], v[162:165], v[110:113], v[18:33]
	ds_read_b128 v[154:157], v133 offset:18496
	ds_read_b128 v[158:161], v133 offset:23104
	ds_read_b128 v[162:165], v133 offset:27712
	ds_read_b128 v[170:173], v133 offset:32320
	s_waitcnt lgkmcnt(4)
	v_mfma_f32_32x32x16_bf16 v[2:17], v[174:177], v[110:113], v[2:17]
	s_waitcnt lgkmcnt(3)
	v_mfma_f32_32x32x16_bf16 v[50:65], v[154:157], v[122:125], v[50:65]
	s_waitcnt lgkmcnt(2)
	v_mfma_f32_32x32x16_bf16 v[34:49], v[158:161], v[122:125], v[34:49]
	s_waitcnt lgkmcnt(1)
	v_mfma_f32_32x32x16_bf16 v[18:33], v[162:165], v[122:125], v[18:33]
	ds_read_b128 v[154:157], v133 offset:18528
	ds_read_b128 v[158:161], v133 offset:23136
	ds_read_b128 v[162:165], v133 offset:27744
	ds_read_b128 v[174:177], v133 offset:32352
	s_waitcnt lgkmcnt(4)
	v_mfma_f32_32x32x16_bf16 v[2:17], v[170:173], v[122:125], v[2:17]
	s_waitcnt lgkmcnt(3)
	v_mfma_f32_32x32x16_bf16 v[50:65], v[154:157], v[126:129], v[50:65]
	s_waitcnt lgkmcnt(2)
	v_mfma_f32_32x32x16_bf16 v[34:49], v[158:161], v[126:129], v[34:49]
	s_waitcnt lgkmcnt(1)
	v_mfma_f32_32x32x16_bf16 v[18:33], v[162:165], v[126:129], v[18:33]
	s_waitcnt lgkmcnt(0)
	v_mfma_f32_32x32x16_bf16 v[2:17], v[174:177], v[126:129], v[2:17]
	v_add_co_u32_e32 v142, vcc, s84, v144
	s_waitcnt vmcnt(1)
	ds_write_b128 v132, v[146:149]
	s_waitcnt vmcnt(0)
	ds_write_b128 v134, v[150:153]
	v_addc_co_u32_e32 v143, vcc, 0, v145, vcc
	global_load_dwordx2 v[172:173], v[142:143], off offset:2048
	global_load_dwordx2 v[174:175], v[136:137], off offset:16
	global_load_dwordx2 v[170:171], v[136:137], off offset:32
	global_load_dwordx2 v[166:167], v[136:137], off offset:48
	global_load_dwordx2 v[164:165], v[136:137], off offset:64
	global_load_dwordx2 v[162:163], v[136:137], off offset:80
	global_load_dwordx2 v[160:161], v[136:137], off offset:96
	global_load_dwordx2 v[158:159], v[136:137], off offset:112
	global_load_dwordx2 v[156:157], v[136:137], off offset:128
	global_load_dwordx2 v[154:155], v[136:137], off offset:144
	global_load_dwordx2 v[152:153], v[136:137], off offset:160
	global_load_dwordx2 v[150:151], v[136:137], off offset:176
	global_load_dwordx2 v[148:149], v[136:137], off offset:192
	global_load_dwordx2 v[146:147], v[136:137], off offset:208
	global_load_dwordx2 v[144:145], v[136:137], off offset:224
	global_load_dwordx2 v[142:143], v[136:137], off offset:240
	v_pk_mul_f32 v[50:51], v[0:1], v[50:51] op_sel_hi:[0,1]
	v_pk_mul_f32 v[52:53], v[0:1], v[52:53] op_sel_hi:[0,1]
	v_pk_mul_f32 v[54:55], v[0:1], v[54:55] op_sel_hi:[0,1]
	v_pk_mul_f32 v[56:57], v[0:1], v[56:57] op_sel_hi:[0,1]
	v_pk_mul_f32 v[34:35], v[0:1], v[34:35] op_sel_hi:[0,1]
	v_pk_mul_f32 v[36:37], v[0:1], v[36:37] op_sel_hi:[0,1]
	v_pk_mul_f32 v[38:39], v[0:1], v[38:39] op_sel_hi:[0,1]
	v_pk_mul_f32 v[40:41], v[0:1], v[40:41] op_sel_hi:[0,1]
	v_pk_mul_f32 v[18:19], v[0:1], v[18:19] op_sel_hi:[0,1]
	v_pk_mul_f32 v[20:21], v[0:1], v[20:21] op_sel_hi:[0,1]
	v_pk_mul_f32 v[22:23], v[0:1], v[22:23] op_sel_hi:[0,1]
	v_pk_mul_f32 v[24:25], v[0:1], v[24:25] op_sel_hi:[0,1]
	v_pk_mul_f32 v[2:3], v[0:1], v[2:3] op_sel_hi:[0,1]
	v_pk_mul_f32 v[4:5], v[0:1], v[4:5] op_sel_hi:[0,1]
	v_pk_mul_f32 v[6:7], v[0:1], v[6:7] op_sel_hi:[0,1]
	v_pk_mul_f32 v[8:9], v[0:1], v[8:9] op_sel_hi:[0,1]
	s_waitcnt vmcnt(15)
	v_lshlrev_b32_e32 v176, 16, v172
	v_mul_f32_e32 v131, 0xbfb8aa3b, v176
	v_exp_f32_e32 v131, v131
	v_and_b32_e32 v177, 0xffff0000, v172
	v_lshlrev_b32_e32 v172, 16, v173
	v_and_b32_e32 v173, 0xffff0000, v173
	v_add_f32_e32 v131, 1.0, v131
	v_rcp_f32_e32 v178, v131
	v_mul_f32_e32 v131, 0xbfb8aa3b, v177
	v_exp_f32_e32 v131, v131
	s_nop 0
	v_add_f32_e32 v131, 1.0, v131
	v_rcp_f32_e32 v179, v131
	v_ashrrev_i32_e32 v131, 31, v130
	v_lshl_add_u64 v[130:131], v[130:131], 1, v[168:169]
	v_pk_mul_f32 v[176:177], v[178:179], v[176:177]
	s_nop 0
	v_pk_mul_f32 v[50:51], v[50:51], v[176:177]
	s_nop 0
	v_cvt_pk_bf16_f32 v50, v50, v51
	v_mul_f32_e32 v51, 0xbfb8aa3b, v172
	v_exp_f32_e32 v51, v51
	s_nop 0
	v_add_f32_e32 v51, 1.0, v51
	v_rcp_f32_e32 v176, v51
	v_mul_f32_e32 v51, 0xbfb8aa3b, v173
	v_exp_f32_e32 v51, v51
	s_nop 0
	v_add_f32_e32 v51, 1.0, v51
	v_rcp_f32_e32 v177, v51
	s_nop 0
	v_pk_mul_f32 v[172:173], v[176:177], v[172:173]
	s_nop 0
	v_pk_mul_f32 v[52:53], v[52:53], v[172:173]
	s_nop 0
	v_cvt_pk_bf16_f32 v51, v52, v53
	global_store_dwordx2 v[130:131], v[50:51], off sc1
	s_waitcnt vmcnt(15)
	v_lshlrev_b32_e32 v50, 16, v174
	v_and_b32_e32 v51, 0xffff0000, v174
	v_mul_f32_e32 v52, 0xbfb8aa3b, v50
	v_mul_f32_e32 v53, 0xbfb8aa3b, v51
	v_exp_f32_e32 v52, v52
	v_exp_f32_e32 v53, v53
	v_add_f32_e32 v52, 1.0, v52
	v_add_f32_e32 v53, 1.0, v53
	v_rcp_f32_e32 v52, v52
	v_rcp_f32_e32 v53, v53
	s_nop 0
	v_pk_mul_f32 v[50:51], v[52:53], v[50:51]
	s_nop 0
	v_pk_mul_f32 v[50:51], v[54:55], v[50:51]
	v_lshlrev_b32_e32 v52, 16, v175
	v_cvt_pk_bf16_f32 v50, v50, v51
	v_mul_f32_e32 v51, 0xbfb8aa3b, v52
	v_exp_f32_e32 v51, v51
	v_and_b32_e32 v53, 0xffff0000, v175
	v_add_f32_e32 v51, 1.0, v51
	v_rcp_f32_e32 v54, v51
	v_mul_f32_e32 v51, 0xbfb8aa3b, v53
	v_exp_f32_e32 v51, v51
	s_nop 0
	v_add_f32_e32 v51, 1.0, v51
	v_rcp_f32_e32 v55, v51
	s_nop 0
	v_pk_mul_f32 v[52:53], v[54:55], v[52:53]
	s_nop 0
	v_pk_mul_f32 v[52:53], v[56:57], v[52:53]
	v_pk_mul_f32 v[54:55], v[0:1], v[58:59] op_sel_hi:[0,1]
	v_cvt_pk_bf16_f32 v51, v52, v53
	global_store_dwordx2 v[130:131], v[50:51], off offset:16 sc1
	s_waitcnt vmcnt(15)
	v_lshlrev_b32_e32 v50, 16, v170
	v_and_b32_e32 v51, 0xffff0000, v170
	v_mul_f32_e32 v52, 0xbfb8aa3b, v50
	v_mul_f32_e32 v53, 0xbfb8aa3b, v51
	v_exp_f32_e32 v52, v52
	v_exp_f32_e32 v53, v53
	v_pk_mul_f32 v[56:57], v[0:1], v[60:61] op_sel_hi:[0,1]
	v_add_f32_e32 v52, 1.0, v52
	v_add_f32_e32 v53, 1.0, v53
	v_rcp_f32_e32 v52, v52
	v_rcp_f32_e32 v53, v53
	s_nop 0
	v_pk_mul_f32 v[50:51], v[52:53], v[50:51]
	s_nop 0
	v_pk_mul_f32 v[50:51], v[54:55], v[50:51]
	v_lshlrev_b32_e32 v52, 16, v171
	v_cvt_pk_bf16_f32 v50, v50, v51
	v_mul_f32_e32 v51, 0xbfb8aa3b, v52
	v_exp_f32_e32 v51, v51
	v_and_b32_e32 v53, 0xffff0000, v171
	v_add_f32_e32 v51, 1.0, v51
	v_rcp_f32_e32 v54, v51
	v_mul_f32_e32 v51, 0xbfb8aa3b, v53
	v_exp_f32_e32 v51, v51
	s_nop 0
	v_add_f32_e32 v51, 1.0, v51
	v_rcp_f32_e32 v55, v51
	s_nop 0
	v_pk_mul_f32 v[52:53], v[54:55], v[52:53]
	s_nop 0
	v_pk_mul_f32 v[52:53], v[56:57], v[52:53]
	v_pk_mul_f32 v[54:55], v[0:1], v[62:63] op_sel_hi:[0,1]
	v_cvt_pk_bf16_f32 v51, v52, v53
	global_store_dwordx2 v[130:131], v[50:51], off offset:32 sc1
	s_waitcnt vmcnt(15)
	v_lshlrev_b32_e32 v50, 16, v166
	v_and_b32_e32 v51, 0xffff0000, v166
	v_mul_f32_e32 v52, 0xbfb8aa3b, v50
	v_mul_f32_e32 v53, 0xbfb8aa3b, v51
	v_exp_f32_e32 v52, v52
	v_exp_f32_e32 v53, v53
	v_pk_mul_f32 v[56:57], v[0:1], v[64:65] op_sel_hi:[0,1]
	v_add_f32_e32 v52, 1.0, v52
	v_add_f32_e32 v53, 1.0, v53
	v_rcp_f32_e32 v52, v52
	v_rcp_f32_e32 v53, v53
	s_nop 0
	v_pk_mul_f32 v[50:51], v[52:53], v[50:51]
	s_nop 0
	v_pk_mul_f32 v[50:51], v[54:55], v[50:51]
	v_lshlrev_b32_e32 v52, 16, v167
	v_cvt_pk_bf16_f32 v50, v50, v51
	v_mul_f32_e32 v51, 0xbfb8aa3b, v52
	v_exp_f32_e32 v51, v51
	v_and_b32_e32 v53, 0xffff0000, v167
	v_add_f32_e32 v51, 1.0, v51
	v_rcp_f32_e32 v54, v51
	v_mul_f32_e32 v51, 0xbfb8aa3b, v53
	v_exp_f32_e32 v51, v51
	s_nop 0
	v_add_f32_e32 v51, 1.0, v51
	v_rcp_f32_e32 v55, v51
	s_nop 0
	v_pk_mul_f32 v[52:53], v[54:55], v[52:53]
	s_nop 0
	v_pk_mul_f32 v[52:53], v[56:57], v[52:53]
	s_nop 0
	v_cvt_pk_bf16_f32 v51, v52, v53
	global_store_dwordx2 v[130:131], v[50:51], off offset:48 sc1
	s_waitcnt vmcnt(15)
	v_lshlrev_b32_e32 v50, 16, v164
	v_and_b32_e32 v51, 0xffff0000, v164
	v_mul_f32_e32 v52, 0xbfb8aa3b, v50
	v_mul_f32_e32 v53, 0xbfb8aa3b, v51
	v_exp_f32_e32 v52, v52
	v_exp_f32_e32 v53, v53
	v_add_f32_e32 v52, 1.0, v52
	v_add_f32_e32 v53, 1.0, v53
	v_rcp_f32_e32 v52, v52
	v_rcp_f32_e32 v53, v53
	s_nop 0
	v_pk_mul_f32 v[50:51], v[52:53], v[50:51]
	s_nop 0
	v_pk_mul_f32 v[34:35], v[34:35], v[50:51]
	v_lshlrev_b32_e32 v50, 16, v165
	v_cvt_pk_bf16_f32 v34, v34, v35
	v_mul_f32_e32 v35, 0xbfb8aa3b, v50
	v_exp_f32_e32 v35, v35
	v_and_b32_e32 v51, 0xffff0000, v165
	v_add_f32_e32 v35, 1.0, v35
	v_rcp_f32_e32 v52, v35
	v_mul_f32_e32 v35, 0xbfb8aa3b, v51
	v_exp_f32_e32 v35, v35
	s_nop 0
	v_add_f32_e32 v35, 1.0, v35
	v_rcp_f32_e32 v53, v35
	s_nop 0
	v_pk_mul_f32 v[50:51], v[52:53], v[50:51]
	s_nop 0
	v_pk_mul_f32 v[36:37], v[36:37], v[50:51]
	s_nop 0
	v_cvt_pk_bf16_f32 v35, v36, v37
	global_store_dwordx2 v[130:131], v[34:35], off offset:64 sc1
	s_waitcnt vmcnt(15)
	v_lshlrev_b32_e32 v34, 16, v162
	v_and_b32_e32 v35, 0xffff0000, v162
	v_mul_f32_e32 v36, 0xbfb8aa3b, v34
	v_mul_f32_e32 v37, 0xbfb8aa3b, v35
	v_exp_f32_e32 v36, v36
	v_exp_f32_e32 v37, v37
	v_add_f32_e32 v36, 1.0, v36
	v_add_f32_e32 v37, 1.0, v37
	v_rcp_f32_e32 v36, v36
	v_rcp_f32_e32 v37, v37
	s_nop 0
	v_pk_mul_f32 v[34:35], v[36:37], v[34:35]
	s_nop 0
	v_pk_mul_f32 v[34:35], v[38:39], v[34:35]
	v_lshlrev_b32_e32 v36, 16, v163
	v_cvt_pk_bf16_f32 v34, v34, v35
	v_mul_f32_e32 v35, 0xbfb8aa3b, v36
	v_exp_f32_e32 v35, v35
	v_and_b32_e32 v37, 0xffff0000, v163
	v_add_f32_e32 v35, 1.0, v35
	v_rcp_f32_e32 v38, v35
	v_mul_f32_e32 v35, 0xbfb8aa3b, v37
	v_exp_f32_e32 v35, v35
	s_nop 0
	v_add_f32_e32 v35, 1.0, v35
	v_rcp_f32_e32 v39, v35
	s_nop 0
	v_pk_mul_f32 v[36:37], v[38:39], v[36:37]
	s_nop 0
	v_pk_mul_f32 v[36:37], v[40:41], v[36:37]
	v_pk_mul_f32 v[38:39], v[0:1], v[42:43] op_sel_hi:[0,1]
	v_cvt_pk_bf16_f32 v35, v36, v37
	global_store_dwordx2 v[130:131], v[34:35], off offset:80 sc1
	s_waitcnt vmcnt(15)
	v_lshlrev_b32_e32 v34, 16, v160
	v_and_b32_e32 v35, 0xffff0000, v160
	v_mul_f32_e32 v36, 0xbfb8aa3b, v34
	v_mul_f32_e32 v37, 0xbfb8aa3b, v35
	v_exp_f32_e32 v36, v36
	v_exp_f32_e32 v37, v37
	v_pk_mul_f32 v[40:41], v[0:1], v[44:45] op_sel_hi:[0,1]
	v_add_f32_e32 v36, 1.0, v36
	v_add_f32_e32 v37, 1.0, v37
	v_rcp_f32_e32 v36, v36
	v_rcp_f32_e32 v37, v37
	s_nop 0
	v_pk_mul_f32 v[34:35], v[36:37], v[34:35]
	s_nop 0
	v_pk_mul_f32 v[34:35], v[38:39], v[34:35]
	v_lshlrev_b32_e32 v36, 16, v161
	v_cvt_pk_bf16_f32 v34, v34, v35
	v_mul_f32_e32 v35, 0xbfb8aa3b, v36
	v_exp_f32_e32 v35, v35
	v_and_b32_e32 v37, 0xffff0000, v161
	v_add_f32_e32 v35, 1.0, v35
	v_rcp_f32_e32 v38, v35
	v_mul_f32_e32 v35, 0xbfb8aa3b, v37
	v_exp_f32_e32 v35, v35
	s_nop 0
	v_add_f32_e32 v35, 1.0, v35
	v_rcp_f32_e32 v39, v35
	s_nop 0
	v_pk_mul_f32 v[36:37], v[38:39], v[36:37]
	s_nop 0
	v_pk_mul_f32 v[36:37], v[40:41], v[36:37]
	v_pk_mul_f32 v[38:39], v[0:1], v[46:47] op_sel_hi:[0,1]
	v_cvt_pk_bf16_f32 v35, v36, v37
	global_store_dwordx2 v[130:131], v[34:35], off offset:96 sc1
	s_waitcnt vmcnt(15)
	v_lshlrev_b32_e32 v34, 16, v158
	v_and_b32_e32 v35, 0xffff0000, v158
	v_mul_f32_e32 v36, 0xbfb8aa3b, v34
	v_mul_f32_e32 v37, 0xbfb8aa3b, v35
	v_exp_f32_e32 v36, v36
	v_exp_f32_e32 v37, v37
	v_pk_mul_f32 v[40:41], v[0:1], v[48:49] op_sel_hi:[0,1]
	v_add_f32_e32 v36, 1.0, v36
	v_add_f32_e32 v37, 1.0, v37
	v_rcp_f32_e32 v36, v36
	v_rcp_f32_e32 v37, v37
	s_nop 0
	v_pk_mul_f32 v[34:35], v[36:37], v[34:35]
	s_nop 0
	v_pk_mul_f32 v[34:35], v[38:39], v[34:35]
	v_lshlrev_b32_e32 v36, 16, v159
	v_cvt_pk_bf16_f32 v34, v34, v35
	v_mul_f32_e32 v35, 0xbfb8aa3b, v36
	v_exp_f32_e32 v35, v35
	v_and_b32_e32 v37, 0xffff0000, v159
	v_add_f32_e32 v35, 1.0, v35
	v_rcp_f32_e32 v38, v35
	v_mul_f32_e32 v35, 0xbfb8aa3b, v37
	v_exp_f32_e32 v35, v35
	s_nop 0
	v_add_f32_e32 v35, 1.0, v35
	v_rcp_f32_e32 v39, v35
	s_nop 0
	v_pk_mul_f32 v[36:37], v[38:39], v[36:37]
	s_nop 0
	v_pk_mul_f32 v[36:37], v[40:41], v[36:37]
	s_nop 0
	v_cvt_pk_bf16_f32 v35, v36, v37
	global_store_dwordx2 v[130:131], v[34:35], off offset:112 sc1
	s_waitcnt vmcnt(15)
	v_lshlrev_b32_e32 v34, 16, v156
	v_and_b32_e32 v35, 0xffff0000, v156
	v_mul_f32_e32 v36, 0xbfb8aa3b, v34
	v_mul_f32_e32 v37, 0xbfb8aa3b, v35
	v_exp_f32_e32 v36, v36
	v_exp_f32_e32 v37, v37
	v_add_f32_e32 v36, 1.0, v36
	v_add_f32_e32 v37, 1.0, v37
	v_rcp_f32_e32 v36, v36
	v_rcp_f32_e32 v37, v37
	s_nop 0
	v_pk_mul_f32 v[34:35], v[36:37], v[34:35]
	s_nop 0
	v_pk_mul_f32 v[18:19], v[18:19], v[34:35]
	v_lshlrev_b32_e32 v34, 16, v157
	v_cvt_pk_bf16_f32 v18, v18, v19
	v_mul_f32_e32 v19, 0xbfb8aa3b, v34
	v_exp_f32_e32 v19, v19
	v_and_b32_e32 v35, 0xffff0000, v157
	v_add_f32_e32 v19, 1.0, v19
	v_rcp_f32_e32 v36, v19
	v_mul_f32_e32 v19, 0xbfb8aa3b, v35
	v_exp_f32_e32 v19, v19
	s_nop 0
	v_add_f32_e32 v19, 1.0, v19
	v_rcp_f32_e32 v37, v19
	s_nop 0
	v_pk_mul_f32 v[34:35], v[36:37], v[34:35]
	s_nop 0
	v_pk_mul_f32 v[20:21], v[20:21], v[34:35]
	s_nop 0
	v_cvt_pk_bf16_f32 v19, v20, v21
	global_store_dwordx2 v[130:131], v[18:19], off offset:128 sc1
	s_waitcnt vmcnt(15)
	v_lshlrev_b32_e32 v18, 16, v154
	v_and_b32_e32 v19, 0xffff0000, v154
	v_mul_f32_e32 v20, 0xbfb8aa3b, v18
	v_mul_f32_e32 v21, 0xbfb8aa3b, v19
	v_exp_f32_e32 v20, v20
	v_exp_f32_e32 v21, v21
	v_add_f32_e32 v20, 1.0, v20
	v_add_f32_e32 v21, 1.0, v21
	v_rcp_f32_e32 v20, v20
	v_rcp_f32_e32 v21, v21
	s_nop 0
	v_pk_mul_f32 v[18:19], v[20:21], v[18:19]
	s_nop 0
	v_pk_mul_f32 v[18:19], v[22:23], v[18:19]
	v_lshlrev_b32_e32 v20, 16, v155
	v_cvt_pk_bf16_f32 v18, v18, v19
	v_mul_f32_e32 v19, 0xbfb8aa3b, v20
	v_exp_f32_e32 v19, v19
	v_and_b32_e32 v21, 0xffff0000, v155
	v_add_f32_e32 v19, 1.0, v19
	v_rcp_f32_e32 v22, v19
	v_mul_f32_e32 v19, 0xbfb8aa3b, v21
	v_exp_f32_e32 v19, v19
	s_nop 0
	v_add_f32_e32 v19, 1.0, v19
	v_rcp_f32_e32 v23, v19
	s_nop 0
	v_pk_mul_f32 v[20:21], v[22:23], v[20:21]
	s_nop 0
	v_pk_mul_f32 v[20:21], v[24:25], v[20:21]
	v_pk_mul_f32 v[22:23], v[0:1], v[26:27] op_sel_hi:[0,1]
	v_cvt_pk_bf16_f32 v19, v20, v21
	global_store_dwordx2 v[130:131], v[18:19], off offset:144 sc1
	s_waitcnt vmcnt(15)
	v_lshlrev_b32_e32 v18, 16, v152
	v_and_b32_e32 v19, 0xffff0000, v152
	v_mul_f32_e32 v20, 0xbfb8aa3b, v18
	v_mul_f32_e32 v21, 0xbfb8aa3b, v19
	v_exp_f32_e32 v20, v20
	v_exp_f32_e32 v21, v21
	v_pk_mul_f32 v[24:25], v[0:1], v[28:29] op_sel_hi:[0,1]
	v_add_f32_e32 v20, 1.0, v20
	v_add_f32_e32 v21, 1.0, v21
	v_rcp_f32_e32 v20, v20
	v_rcp_f32_e32 v21, v21
	s_nop 0
	v_pk_mul_f32 v[18:19], v[20:21], v[18:19]
	s_nop 0
	v_pk_mul_f32 v[18:19], v[22:23], v[18:19]
	v_lshlrev_b32_e32 v20, 16, v153
	v_cvt_pk_bf16_f32 v18, v18, v19
	v_mul_f32_e32 v19, 0xbfb8aa3b, v20
	v_exp_f32_e32 v19, v19
	v_and_b32_e32 v21, 0xffff0000, v153
	v_add_f32_e32 v19, 1.0, v19
	v_rcp_f32_e32 v22, v19
	v_mul_f32_e32 v19, 0xbfb8aa3b, v21
	v_exp_f32_e32 v19, v19
	s_nop 0
	v_add_f32_e32 v19, 1.0, v19
	v_rcp_f32_e32 v23, v19
	s_nop 0
	v_pk_mul_f32 v[20:21], v[22:23], v[20:21]
	s_nop 0
	v_pk_mul_f32 v[20:21], v[24:25], v[20:21]
	v_pk_mul_f32 v[22:23], v[0:1], v[30:31] op_sel_hi:[0,1]
	v_cvt_pk_bf16_f32 v19, v20, v21
	global_store_dwordx2 v[130:131], v[18:19], off offset:160 sc1
	s_waitcnt vmcnt(15)
	v_lshlrev_b32_e32 v18, 16, v150
	v_and_b32_e32 v19, 0xffff0000, v150
	v_mul_f32_e32 v20, 0xbfb8aa3b, v18
	v_mul_f32_e32 v21, 0xbfb8aa3b, v19
	v_exp_f32_e32 v20, v20
	v_exp_f32_e32 v21, v21
	v_pk_mul_f32 v[24:25], v[0:1], v[32:33] op_sel_hi:[0,1]
	v_add_f32_e32 v20, 1.0, v20
	v_add_f32_e32 v21, 1.0, v21
	v_rcp_f32_e32 v20, v20
	v_rcp_f32_e32 v21, v21
	s_nop 0
	v_pk_mul_f32 v[18:19], v[20:21], v[18:19]
	s_nop 0
	v_pk_mul_f32 v[18:19], v[22:23], v[18:19]
	v_lshlrev_b32_e32 v20, 16, v151
	v_cvt_pk_bf16_f32 v18, v18, v19
	v_mul_f32_e32 v19, 0xbfb8aa3b, v20
	v_exp_f32_e32 v19, v19
	v_and_b32_e32 v21, 0xffff0000, v151
	v_add_f32_e32 v19, 1.0, v19
	v_rcp_f32_e32 v22, v19
	v_mul_f32_e32 v19, 0xbfb8aa3b, v21
	v_exp_f32_e32 v19, v19
	s_nop 0
	v_add_f32_e32 v19, 1.0, v19
	v_rcp_f32_e32 v23, v19
	s_nop 0
	v_pk_mul_f32 v[20:21], v[22:23], v[20:21]
	s_nop 0
	v_pk_mul_f32 v[20:21], v[24:25], v[20:21]
	s_nop 0
	v_cvt_pk_bf16_f32 v19, v20, v21
	global_store_dwordx2 v[130:131], v[18:19], off offset:176 sc1
	s_waitcnt vmcnt(15)
	v_lshlrev_b32_e32 v18, 16, v148
	v_and_b32_e32 v19, 0xffff0000, v148
	v_mul_f32_e32 v20, 0xbfb8aa3b, v18
	v_mul_f32_e32 v21, 0xbfb8aa3b, v19
	v_exp_f32_e32 v20, v20
	v_exp_f32_e32 v21, v21
	v_add_f32_e32 v20, 1.0, v20
	v_add_f32_e32 v21, 1.0, v21
	v_rcp_f32_e32 v20, v20
	v_rcp_f32_e32 v21, v21
	s_nop 0
	v_pk_mul_f32 v[18:19], v[20:21], v[18:19]
	s_nop 0
	v_pk_mul_f32 v[2:3], v[2:3], v[18:19]
	v_lshlrev_b32_e32 v18, 16, v149
	v_cvt_pk_bf16_f32 v2, v2, v3
	v_mul_f32_e32 v3, 0xbfb8aa3b, v18
	v_exp_f32_e32 v3, v3
	v_and_b32_e32 v19, 0xffff0000, v149
	v_add_f32_e32 v3, 1.0, v3
	v_rcp_f32_e32 v20, v3
	v_mul_f32_e32 v3, 0xbfb8aa3b, v19
	v_exp_f32_e32 v3, v3
	s_nop 0
	v_add_f32_e32 v3, 1.0, v3
	v_rcp_f32_e32 v21, v3
	s_nop 0
	v_pk_mul_f32 v[18:19], v[20:21], v[18:19]
	s_nop 0
	v_pk_mul_f32 v[4:5], v[4:5], v[18:19]
	s_nop 0
	v_cvt_pk_bf16_f32 v3, v4, v5
	global_store_dwordx2 v[130:131], v[2:3], off offset:192 sc1
	s_waitcnt vmcnt(15)
	v_lshlrev_b32_e32 v2, 16, v146
	v_and_b32_e32 v3, 0xffff0000, v146
	v_mul_f32_e32 v4, 0xbfb8aa3b, v2
	v_mul_f32_e32 v5, 0xbfb8aa3b, v3
	v_exp_f32_e32 v4, v4
	v_exp_f32_e32 v5, v5
	v_add_f32_e32 v4, 1.0, v4
	v_add_f32_e32 v5, 1.0, v5
	v_rcp_f32_e32 v4, v4
	v_rcp_f32_e32 v5, v5
	s_nop 0
	v_pk_mul_f32 v[2:3], v[4:5], v[2:3]
	s_nop 0
	v_pk_mul_f32 v[2:3], v[6:7], v[2:3]
	v_lshlrev_b32_e32 v4, 16, v147
	v_cvt_pk_bf16_f32 v2, v2, v3
	v_mul_f32_e32 v3, 0xbfb8aa3b, v4
	v_exp_f32_e32 v3, v3
	v_and_b32_e32 v5, 0xffff0000, v147
	v_add_f32_e32 v3, 1.0, v3
	v_rcp_f32_e32 v6, v3
	v_mul_f32_e32 v3, 0xbfb8aa3b, v5
	v_exp_f32_e32 v3, v3
	s_nop 0
	v_add_f32_e32 v3, 1.0, v3
	v_rcp_f32_e32 v7, v3
	s_nop 0
	v_pk_mul_f32 v[4:5], v[6:7], v[4:5]
	s_nop 0
	v_pk_mul_f32 v[4:5], v[8:9], v[4:5]
	v_pk_mul_f32 v[6:7], v[0:1], v[10:11] op_sel_hi:[0,1]
	v_cvt_pk_bf16_f32 v3, v4, v5
	global_store_dwordx2 v[130:131], v[2:3], off offset:208 sc1
	s_waitcnt vmcnt(15)
	v_lshlrev_b32_e32 v2, 16, v144
	v_and_b32_e32 v3, 0xffff0000, v144
	v_mul_f32_e32 v4, 0xbfb8aa3b, v2
	v_mul_f32_e32 v5, 0xbfb8aa3b, v3
	v_exp_f32_e32 v4, v4
	v_exp_f32_e32 v5, v5
	v_pk_mul_f32 v[8:9], v[0:1], v[12:13] op_sel_hi:[0,1]
	v_add_f32_e32 v4, 1.0, v4
	v_add_f32_e32 v5, 1.0, v5
	v_rcp_f32_e32 v4, v4
	v_rcp_f32_e32 v5, v5
	s_nop 0
	v_pk_mul_f32 v[2:3], v[4:5], v[2:3]
	s_nop 0
	v_pk_mul_f32 v[2:3], v[6:7], v[2:3]
	v_lshlrev_b32_e32 v4, 16, v145
	v_cvt_pk_bf16_f32 v2, v2, v3
	v_mul_f32_e32 v3, 0xbfb8aa3b, v4
	v_exp_f32_e32 v3, v3
	v_and_b32_e32 v5, 0xffff0000, v145
	v_add_f32_e32 v3, 1.0, v3
	v_rcp_f32_e32 v6, v3
	v_mul_f32_e32 v3, 0xbfb8aa3b, v5
	v_exp_f32_e32 v3, v3
	s_nop 0
	v_add_f32_e32 v3, 1.0, v3
	v_rcp_f32_e32 v7, v3
	s_nop 0
	v_pk_mul_f32 v[4:5], v[6:7], v[4:5]
	s_nop 0
	v_pk_mul_f32 v[4:5], v[8:9], v[4:5]
	v_pk_mul_f32 v[6:7], v[0:1], v[14:15] op_sel_hi:[0,1]
	v_cvt_pk_bf16_f32 v3, v4, v5
	global_store_dwordx2 v[130:131], v[2:3], off offset:224 sc1
	s_waitcnt vmcnt(15)
	v_lshlrev_b32_e32 v2, 16, v142
	v_and_b32_e32 v3, 0xffff0000, v142
	v_mul_f32_e32 v4, 0xbfb8aa3b, v2
	v_mul_f32_e32 v5, 0xbfb8aa3b, v3
	v_exp_f32_e32 v4, v4
	v_exp_f32_e32 v5, v5
	v_pk_mul_f32 v[8:9], v[0:1], v[16:17] op_sel_hi:[0,1]
	v_add_f32_e32 v4, 1.0, v4
	v_add_f32_e32 v5, 1.0, v5
	v_rcp_f32_e32 v4, v4
	v_rcp_f32_e32 v5, v5
	s_nop 0
	v_pk_mul_f32 v[2:3], v[4:5], v[2:3]
	s_nop 0
	v_pk_mul_f32 v[2:3], v[6:7], v[2:3]
	v_lshlrev_b32_e32 v4, 16, v143
	v_cvt_pk_bf16_f32 v2, v2, v3
	v_mul_f32_e32 v3, 0xbfb8aa3b, v4
	v_exp_f32_e32 v3, v3
	v_and_b32_e32 v5, 0xffff0000, v143
	v_add_f32_e32 v3, 1.0, v3
	v_rcp_f32_e32 v6, v3
	v_mul_f32_e32 v3, 0xbfb8aa3b, v5
	v_exp_f32_e32 v3, v3
	s_nop 0
	v_add_f32_e32 v3, 1.0, v3
	v_rcp_f32_e32 v7, v3
	s_nop 0
	v_pk_mul_f32 v[4:5], v[6:7], v[4:5]
	s_nop 0
	v_pk_mul_f32 v[4:5], v[8:9], v[4:5]
	s_nop 0
	v_cvt_pk_bf16_f32 v3, v4, v5
	global_store_dwordx2 v[130:131], v[2:3], off offset:240 sc1
	s_waitcnt lgkmcnt(0)
	s_barrier
	global_load_dwordx4 v[142:145], v[138:139], off offset:128
	global_load_dwordx4 v[146:149], v[140:141], off offset:128
	ds_read_b128 v[2:5], v133
	ds_read_b128 v[6:9], v133 offset:4608
	ds_read_b128 v[10:13], v133 offset:9216
	ds_read_b128 v[14:17], v133 offset:13824
	ds_read_b128 v[150:153], v133 offset:32
	ds_read_b128 v[154:157], v133 offset:4640
	ds_read_b128 v[158:161], v133 offset:9248
	ds_read_b128 v[162:165], v133 offset:13856
	s_waitcnt lgkmcnt(7)
	v_mfma_f32_32x32x16_bf16 v[50:65], v[2:5], v[114:117], 0
	s_waitcnt lgkmcnt(6)
	v_mfma_f32_32x32x16_bf16 v[34:49], v[6:9], v[114:117], 0
	s_waitcnt lgkmcnt(5)
	v_mfma_f32_32x32x16_bf16 v[18:33], v[10:13], v[114:117], 0
	s_waitcnt lgkmcnt(4)
	v_mfma_f32_32x32x16_bf16 v[2:17], v[14:17], v[114:117], 0
	s_waitcnt lgkmcnt(3)
	v_mfma_f32_32x32x16_bf16 v[50:65], v[150:153], v[118:121], v[50:65]
	s_waitcnt lgkmcnt(2)
	v_mfma_f32_32x32x16_bf16 v[34:49], v[154:157], v[118:121], v[34:49]
	s_waitcnt lgkmcnt(1)
	v_mfma_f32_32x32x16_bf16 v[18:33], v[158:161], v[118:121], v[18:33]
	ds_read_b128 v[114:117], v133 offset:64
	ds_read_b128 v[150:153], v133 offset:4672
	ds_read_b128 v[154:157], v133 offset:9280
	ds_read_b128 v[158:161], v133 offset:13888
	s_waitcnt lgkmcnt(4)
	v_mfma_f32_32x32x16_bf16 v[2:17], v[162:165], v[118:121], v[2:17]
	s_waitcnt lgkmcnt(3)
	v_mfma_f32_32x32x16_bf16 v[50:65], v[114:117], v[82:85], v[50:65]
	s_waitcnt lgkmcnt(2)
	v_mfma_f32_32x32x16_bf16 v[34:49], v[150:153], v[82:85], v[34:49]
	s_waitcnt lgkmcnt(1)
	v_mfma_f32_32x32x16_bf16 v[18:33], v[154:157], v[82:85], v[18:33]
	ds_read_b128 v[114:117], v133 offset:96
	ds_read_b128 v[118:121], v133 offset:4704
	ds_read_b128 v[150:153], v133 offset:9312
	ds_read_b128 v[154:157], v133 offset:13920
	s_waitcnt lgkmcnt(4)
	v_mfma_f32_32x32x16_bf16 v[2:17], v[158:161], v[82:85], v[2:17]
	s_waitcnt lgkmcnt(3)
	v_mfma_f32_32x32x16_bf16 v[50:65], v[114:117], v[86:89], v[50:65]
	s_waitcnt lgkmcnt(2)
	v_mfma_f32_32x32x16_bf16 v[34:49], v[118:121], v[86:89], v[34:49]
	s_waitcnt lgkmcnt(1)
	v_mfma_f32_32x32x16_bf16 v[18:33], v[150:153], v[86:89], v[18:33]
	s_waitcnt lgkmcnt(0)
	v_mfma_f32_32x32x16_bf16 v[2:17], v[154:157], v[86:89], v[2:17]
	s_waitcnt vmcnt(1)
	ds_write_b128 v132, v[142:145] offset:18432
	s_waitcnt vmcnt(0)
	ds_write_b128 v134, v[146:149] offset:18432
	s_waitcnt lgkmcnt(0)
	s_barrier
	global_load_dwordx4 v[82:85], v[138:139], off offset:256
	global_load_dwordx4 v[86:89], v[140:141], off offset:256
	ds_read_b128 v[114:117], v133 offset:18432
	ds_read_b128 v[118:121], v133 offset:23040
	ds_read_b128 v[142:145], v133 offset:27648
	ds_read_b128 v[146:149], v133 offset:32256
	s_waitcnt lgkmcnt(3)
	v_mfma_f32_32x32x16_bf16 v[50:65], v[114:117], v[90:93], v[50:65]
	s_waitcnt lgkmcnt(2)
	v_mfma_f32_32x32x16_bf16 v[34:49], v[118:121], v[90:93], v[34:49]
	s_waitcnt lgkmcnt(1)
	v_mfma_f32_32x32x16_bf16 v[18:33], v[142:145], v[90:93], v[18:33]
	ds_read_b128 v[114:117], v133 offset:18464
	ds_read_b128 v[118:121], v133 offset:23072
	ds_read_b128 v[142:145], v133 offset:27680
	ds_read_b128 v[150:153], v133 offset:32288
	s_waitcnt lgkmcnt(4)
	v_mfma_f32_32x32x16_bf16 v[2:17], v[146:149], v[90:93], v[2:17]
	s_waitcnt lgkmcnt(3)
	v_mfma_f32_32x32x16_bf16 v[50:65], v[114:117], v[94:97], v[50:65]
	s_waitcnt lgkmcnt(2)
	v_mfma_f32_32x32x16_bf16 v[34:49], v[118:121], v[94:97], v[34:49]
	s_waitcnt lgkmcnt(1)
	v_mfma_f32_32x32x16_bf16 v[18:33], v[142:145], v[94:97], v[18:33]
	ds_read_b128 v[90:93], v133 offset:18496
	ds_read_b128 v[114:117], v133 offset:23104
	ds_read_b128 v[118:121], v133 offset:27712
	ds_read_b128 v[142:145], v133 offset:32320
	s_waitcnt lgkmcnt(4)
	v_mfma_f32_32x32x16_bf16 v[2:17], v[150:153], v[94:97], v[2:17]
	s_waitcnt lgkmcnt(3)
	v_mfma_f32_32x32x16_bf16 v[50:65], v[90:93], v[98:101], v[50:65]
	s_waitcnt lgkmcnt(2)
	v_mfma_f32_32x32x16_bf16 v[34:49], v[114:117], v[98:101], v[34:49]
	s_waitcnt lgkmcnt(1)
	v_mfma_f32_32x32x16_bf16 v[18:33], v[118:121], v[98:101], v[18:33]
	ds_read_b128 v[90:93], v133 offset:18528
	ds_read_b128 v[94:97], v133 offset:23136
	ds_read_b128 v[114:117], v133 offset:27744
	ds_read_b128 v[118:121], v133 offset:32352
	s_waitcnt lgkmcnt(4)
	v_mfma_f32_32x32x16_bf16 v[2:17], v[142:145], v[98:101], v[2:17]
	s_waitcnt lgkmcnt(3)
	v_mfma_f32_32x32x16_bf16 v[50:65], v[90:93], v[102:105], v[50:65]
	s_waitcnt lgkmcnt(2)
	v_mfma_f32_32x32x16_bf16 v[34:49], v[94:97], v[102:105], v[34:49]
	s_waitcnt lgkmcnt(1)
	v_mfma_f32_32x32x16_bf16 v[18:33], v[114:117], v[102:105], v[18:33]
	s_waitcnt lgkmcnt(0)
	v_mfma_f32_32x32x16_bf16 v[2:17], v[118:121], v[102:105], v[2:17]
	s_waitcnt vmcnt(1)
	ds_write_b128 v132, v[82:85]
	s_waitcnt vmcnt(0)
	ds_write_b128 v134, v[86:89]
	s_waitcnt lgkmcnt(0)
	s_barrier
	global_load_dwordx4 v[82:85], v[138:139], off offset:384
	global_load_dwordx4 v[86:89], v[140:141], off offset:384
	ds_read_b128 v[90:93], v133
	ds_read_b128 v[94:97], v133 offset:4608
	ds_read_b128 v[98:101], v133 offset:9216
	ds_read_b128 v[102:105], v133 offset:13824
	s_waitcnt lgkmcnt(3)
	v_mfma_f32_32x32x16_bf16 v[50:65], v[90:93], v[66:69], v[50:65]
	s_waitcnt lgkmcnt(2)
	v_mfma_f32_32x32x16_bf16 v[34:49], v[94:97], v[66:69], v[34:49]
	s_waitcnt lgkmcnt(1)
	v_mfma_f32_32x32x16_bf16 v[18:33], v[98:101], v[66:69], v[18:33]
	ds_read_b128 v[90:93], v133 offset:32
	ds_read_b128 v[94:97], v133 offset:4640
	ds_read_b128 v[98:101], v133 offset:9248
	ds_read_b128 v[114:117], v133 offset:13856
	s_waitcnt lgkmcnt(4)
	v_mfma_f32_32x32x16_bf16 v[2:17], v[102:105], v[66:69], v[2:17]
	s_waitcnt lgkmcnt(3)
	v_mfma_f32_32x32x16_bf16 v[50:65], v[90:93], v[70:73], v[50:65]
	s_waitcnt lgkmcnt(2)
	v_mfma_f32_32x32x16_bf16 v[34:49], v[94:97], v[70:73], v[34:49]
	s_waitcnt lgkmcnt(1)
	v_mfma_f32_32x32x16_bf16 v[18:33], v[98:101], v[70:73], v[18:33]
	ds_read_b128 v[66:69], v133 offset:64
	ds_read_b128 v[90:93], v133 offset:4672
	ds_read_b128 v[94:97], v133 offset:9280
	ds_read_b128 v[98:101], v133 offset:13888
	s_waitcnt lgkmcnt(4)
	v_mfma_f32_32x32x16_bf16 v[2:17], v[114:117], v[70:73], v[2:17]
	s_waitcnt lgkmcnt(3)
	v_mfma_f32_32x32x16_bf16 v[50:65], v[66:69], v[74:77], v[50:65]
	s_waitcnt lgkmcnt(2)
	v_mfma_f32_32x32x16_bf16 v[34:49], v[90:93], v[74:77], v[34:49]
	s_waitcnt lgkmcnt(1)
	v_mfma_f32_32x32x16_bf16 v[18:33], v[94:97], v[74:77], v[18:33]
	ds_read_b128 v[66:69], v133 offset:96
	ds_read_b128 v[70:73], v133 offset:4704
	ds_read_b128 v[90:93], v133 offset:9312
	ds_read_b128 v[94:97], v133 offset:13920
	s_waitcnt lgkmcnt(4)
	v_mfma_f32_32x32x16_bf16 v[2:17], v[98:101], v[74:77], v[2:17]
	s_waitcnt lgkmcnt(3)
	v_mfma_f32_32x32x16_bf16 v[50:65], v[66:69], v[78:81], v[50:65]
	s_waitcnt lgkmcnt(2)
	v_mfma_f32_32x32x16_bf16 v[34:49], v[70:73], v[78:81], v[34:49]
	s_waitcnt lgkmcnt(1)
	v_mfma_f32_32x32x16_bf16 v[18:33], v[90:93], v[78:81], v[18:33]
	s_waitcnt lgkmcnt(0)
	v_mfma_f32_32x32x16_bf16 v[2:17], v[94:97], v[78:81], v[2:17]
	s_waitcnt vmcnt(1)
	ds_write_b128 v132, v[82:85] offset:18432
	s_waitcnt vmcnt(0)
	ds_write_b128 v134, v[86:89] offset:18432
	s_waitcnt lgkmcnt(0)
	s_barrier
	ds_read_b128 v[66:69], v133 offset:18432
	ds_read_b128 v[70:73], v133 offset:23040
	ds_read_b128 v[74:77], v133 offset:27648
	ds_read_b128 v[78:81], v133 offset:32256
	s_waitcnt lgkmcnt(3)
	v_mfma_f32_32x32x16_bf16 v[50:65], v[66:69], v[106:109], v[50:65]
	s_waitcnt lgkmcnt(2)
	v_mfma_f32_32x32x16_bf16 v[34:49], v[70:73], v[106:109], v[34:49]
	s_waitcnt lgkmcnt(1)
	v_mfma_f32_32x32x16_bf16 v[18:33], v[74:77], v[106:109], v[18:33]
	ds_read_b128 v[66:69], v133 offset:18464
	ds_read_b128 v[70:73], v133 offset:23072
	ds_read_b128 v[74:77], v133 offset:27680
	ds_read_b128 v[82:85], v133 offset:32288
	s_waitcnt lgkmcnt(4)
	v_mfma_f32_32x32x16_bf16 v[2:17], v[78:81], v[106:109], v[2:17]
	s_waitcnt lgkmcnt(3)
	v_mfma_f32_32x32x16_bf16 v[50:65], v[66:69], v[110:113], v[50:65]
	s_waitcnt lgkmcnt(2)
	v_mfma_f32_32x32x16_bf16 v[34:49], v[70:73], v[110:113], v[34:49]
	s_waitcnt lgkmcnt(1)
	v_mfma_f32_32x32x16_bf16 v[18:33], v[74:77], v[110:113], v[18:33]
	ds_read_b128 v[66:69], v133 offset:18496
	ds_read_b128 v[70:73], v133 offset:23104
	ds_read_b128 v[74:77], v133 offset:27712
	ds_read_b128 v[78:81], v133 offset:32320
	s_waitcnt lgkmcnt(4)
	v_mfma_f32_32x32x16_bf16 v[2:17], v[82:85], v[110:113], v[2:17]
	s_waitcnt lgkmcnt(3)
	v_mfma_f32_32x32x16_bf16 v[50:65], v[66:69], v[122:125], v[50:65]
	s_waitcnt lgkmcnt(2)
	v_mfma_f32_32x32x16_bf16 v[34:49], v[70:73], v[122:125], v[34:49]
	s_waitcnt lgkmcnt(1)
	v_mfma_f32_32x32x16_bf16 v[18:33], v[74:77], v[122:125], v[18:33]
	ds_read_b128 v[66:69], v133 offset:18528
	ds_read_b128 v[70:73], v133 offset:23136
	ds_read_b128 v[74:77], v133 offset:27744
	ds_read_b128 v[82:85], v133 offset:32352
	s_waitcnt lgkmcnt(4)
	v_mfma_f32_32x32x16_bf16 v[2:17], v[78:81], v[122:125], v[2:17]
	s_waitcnt lgkmcnt(3)
	v_mfma_f32_32x32x16_bf16 v[50:65], v[66:69], v[126:129], v[50:65]
	s_waitcnt lgkmcnt(2)
	v_mfma_f32_32x32x16_bf16 v[34:49], v[70:73], v[126:129], v[34:49]
	s_waitcnt lgkmcnt(1)
	v_mfma_f32_32x32x16_bf16 v[18:33], v[74:77], v[126:129], v[18:33]
	s_waitcnt lgkmcnt(0)
	v_mfma_f32_32x32x16_bf16 v[2:17], v[82:85], v[126:129], v[2:17]
	global_load_dwordx2 v[94:95], v[136:137], off offset:256
	global_load_dwordx2 v[96:97], v[136:137], off offset:272
	global_load_dwordx2 v[92:93], v[136:137], off offset:288
	global_load_dwordx2 v[90:91], v[136:137], off offset:304
	global_load_dwordx2 v[88:89], v[136:137], off offset:320
	global_load_dwordx2 v[86:87], v[136:137], off offset:336
	global_load_dwordx2 v[84:85], v[136:137], off offset:352
	global_load_dwordx2 v[82:83], v[136:137], off offset:368
	global_load_dwordx2 v[80:81], v[136:137], off offset:384
	global_load_dwordx2 v[78:79], v[136:137], off offset:400
	global_load_dwordx2 v[76:77], v[136:137], off offset:416
	global_load_dwordx2 v[74:75], v[136:137], off offset:432
	global_load_dwordx2 v[72:73], v[136:137], off offset:448
	global_load_dwordx2 v[70:71], v[136:137], off offset:464
	global_load_dwordx2 v[68:69], v[136:137], off offset:480
	global_load_dwordx2 v[66:67], v[136:137], off offset:496
	v_pk_mul_f32 v[50:51], v[0:1], v[50:51] op_sel_hi:[0,1]
	v_pk_mul_f32 v[52:53], v[0:1], v[52:53] op_sel_hi:[0,1]
	v_pk_mul_f32 v[54:55], v[0:1], v[54:55] op_sel_hi:[0,1]
	v_pk_mul_f32 v[56:57], v[0:1], v[56:57] op_sel_hi:[0,1]
	v_pk_mul_f32 v[34:35], v[0:1], v[34:35] op_sel_hi:[0,1]
	v_pk_mul_f32 v[36:37], v[0:1], v[36:37] op_sel_hi:[0,1]
	v_pk_mul_f32 v[38:39], v[0:1], v[38:39] op_sel_hi:[0,1]
	v_pk_mul_f32 v[40:41], v[0:1], v[40:41] op_sel_hi:[0,1]
	v_pk_mul_f32 v[18:19], v[0:1], v[18:19] op_sel_hi:[0,1]
	v_pk_mul_f32 v[20:21], v[0:1], v[20:21] op_sel_hi:[0,1]
	v_pk_mul_f32 v[22:23], v[0:1], v[22:23] op_sel_hi:[0,1]
	v_pk_mul_f32 v[24:25], v[0:1], v[24:25] op_sel_hi:[0,1]
	v_pk_mul_f32 v[2:3], v[0:1], v[2:3] op_sel_hi:[0,1]
	v_pk_mul_f32 v[4:5], v[0:1], v[4:5] op_sel_hi:[0,1]
	v_pk_mul_f32 v[6:7], v[0:1], v[6:7] op_sel_hi:[0,1]
	v_pk_mul_f32 v[8:9], v[0:1], v[8:9] op_sel_hi:[0,1]
	s_mov_b64 s[0:1], 0
	s_waitcnt vmcnt(15)
	v_lshlrev_b32_e32 v98, 16, v94
	v_and_b32_e32 v99, 0xffff0000, v94
	v_mul_f32_e32 v94, 0xbfb8aa3b, v98
	v_exp_f32_e32 v94, v94
	s_nop 0
	v_add_f32_e32 v94, 1.0, v94
	v_rcp_f32_e32 v100, v94
	v_mul_f32_e32 v94, 0xbfb8aa3b, v99
	v_exp_f32_e32 v94, v94
	s_nop 0
	v_add_f32_e32 v94, 1.0, v94
	v_rcp_f32_e32 v101, v94
	v_lshlrev_b32_e32 v94, 16, v95
	v_and_b32_e32 v95, 0xffff0000, v95
	v_pk_mul_f32 v[98:99], v[100:101], v[98:99]
	s_nop 0
	v_pk_mul_f32 v[50:51], v[50:51], v[98:99]
	s_nop 0
	v_cvt_pk_bf16_f32 v50, v50, v51
	v_mul_f32_e32 v51, 0xbfb8aa3b, v94
	v_exp_f32_e32 v51, v51
	s_nop 0
	v_add_f32_e32 v51, 1.0, v51
	v_rcp_f32_e32 v98, v51
	v_mul_f32_e32 v51, 0xbfb8aa3b, v95
	v_exp_f32_e32 v51, v51
	s_nop 0
	v_add_f32_e32 v51, 1.0, v51
	v_rcp_f32_e32 v99, v51
	s_nop 0
	v_pk_mul_f32 v[94:95], v[98:99], v[94:95]
	s_nop 0
	v_pk_mul_f32 v[52:53], v[52:53], v[94:95]
	s_nop 0
	v_cvt_pk_bf16_f32 v51, v52, v53
	global_store_dwordx2 v[130:131], v[50:51], off offset:256 sc1
	s_waitcnt vmcnt(15)
	v_lshlrev_b32_e32 v50, 16, v96
	v_and_b32_e32 v51, 0xffff0000, v96
	v_mul_f32_e32 v52, 0xbfb8aa3b, v50
	v_mul_f32_e32 v53, 0xbfb8aa3b, v51
	v_exp_f32_e32 v52, v52
	v_exp_f32_e32 v53, v53
	v_add_f32_e32 v52, 1.0, v52
	v_add_f32_e32 v53, 1.0, v53
	v_rcp_f32_e32 v52, v52
	v_rcp_f32_e32 v53, v53
	s_nop 0
	v_pk_mul_f32 v[50:51], v[52:53], v[50:51]
	s_nop 0
	v_pk_mul_f32 v[50:51], v[54:55], v[50:51]
	v_lshlrev_b32_e32 v52, 16, v97
	v_cvt_pk_bf16_f32 v50, v50, v51
	v_mul_f32_e32 v51, 0xbfb8aa3b, v52
	v_exp_f32_e32 v51, v51
	v_and_b32_e32 v53, 0xffff0000, v97
	v_add_f32_e32 v51, 1.0, v51
	v_rcp_f32_e32 v54, v51
	v_mul_f32_e32 v51, 0xbfb8aa3b, v53
	v_exp_f32_e32 v51, v51
	s_nop 0
	v_add_f32_e32 v51, 1.0, v51
	v_rcp_f32_e32 v55, v51
	s_nop 0
	v_pk_mul_f32 v[52:53], v[54:55], v[52:53]
	s_nop 0
	v_pk_mul_f32 v[52:53], v[56:57], v[52:53]
	v_pk_mul_f32 v[54:55], v[0:1], v[58:59] op_sel_hi:[0,1]
	v_cvt_pk_bf16_f32 v51, v52, v53
	global_store_dwordx2 v[130:131], v[50:51], off offset:272 sc1
	s_waitcnt vmcnt(15)
	v_lshlrev_b32_e32 v50, 16, v92
	v_and_b32_e32 v51, 0xffff0000, v92
	v_mul_f32_e32 v52, 0xbfb8aa3b, v50
	v_mul_f32_e32 v53, 0xbfb8aa3b, v51
	v_exp_f32_e32 v52, v52
	v_exp_f32_e32 v53, v53
	v_pk_mul_f32 v[56:57], v[0:1], v[60:61] op_sel_hi:[0,1]
	v_add_f32_e32 v52, 1.0, v52
	v_add_f32_e32 v53, 1.0, v53
	v_rcp_f32_e32 v52, v52
	v_rcp_f32_e32 v53, v53
	s_nop 0
	v_pk_mul_f32 v[50:51], v[52:53], v[50:51]
	s_nop 0
	v_pk_mul_f32 v[50:51], v[54:55], v[50:51]
	v_lshlrev_b32_e32 v52, 16, v93
	v_cvt_pk_bf16_f32 v50, v50, v51
	v_mul_f32_e32 v51, 0xbfb8aa3b, v52
	v_exp_f32_e32 v51, v51
	v_and_b32_e32 v53, 0xffff0000, v93
	v_add_f32_e32 v51, 1.0, v51
	v_rcp_f32_e32 v54, v51
	v_mul_f32_e32 v51, 0xbfb8aa3b, v53
	v_exp_f32_e32 v51, v51
	s_nop 0
	v_add_f32_e32 v51, 1.0, v51
	v_rcp_f32_e32 v55, v51
	s_nop 0
	v_pk_mul_f32 v[52:53], v[54:55], v[52:53]
	s_nop 0
	v_pk_mul_f32 v[52:53], v[56:57], v[52:53]
	v_pk_mul_f32 v[54:55], v[0:1], v[62:63] op_sel_hi:[0,1]
	v_cvt_pk_bf16_f32 v51, v52, v53
	global_store_dwordx2 v[130:131], v[50:51], off offset:288 sc1
	s_waitcnt vmcnt(15)
	v_lshlrev_b32_e32 v50, 16, v90
	v_and_b32_e32 v51, 0xffff0000, v90
	v_mul_f32_e32 v52, 0xbfb8aa3b, v50
	v_mul_f32_e32 v53, 0xbfb8aa3b, v51
	v_exp_f32_e32 v52, v52
	v_exp_f32_e32 v53, v53
	v_pk_mul_f32 v[56:57], v[0:1], v[64:65] op_sel_hi:[0,1]
	v_add_f32_e32 v52, 1.0, v52
	v_add_f32_e32 v53, 1.0, v53
	v_rcp_f32_e32 v52, v52
	v_rcp_f32_e32 v53, v53
	s_nop 0
	v_pk_mul_f32 v[50:51], v[52:53], v[50:51]
	s_nop 0
	v_pk_mul_f32 v[50:51], v[54:55], v[50:51]
	v_lshlrev_b32_e32 v52, 16, v91
	v_cvt_pk_bf16_f32 v50, v50, v51
	v_mul_f32_e32 v51, 0xbfb8aa3b, v52
	v_exp_f32_e32 v51, v51
	v_and_b32_e32 v53, 0xffff0000, v91
	v_add_f32_e32 v51, 1.0, v51
	v_rcp_f32_e32 v54, v51
	v_mul_f32_e32 v51, 0xbfb8aa3b, v53
	v_exp_f32_e32 v51, v51
	s_nop 0
	v_add_f32_e32 v51, 1.0, v51
	v_rcp_f32_e32 v55, v51
	s_nop 0
	v_pk_mul_f32 v[52:53], v[54:55], v[52:53]
	s_nop 0
	v_pk_mul_f32 v[52:53], v[56:57], v[52:53]
	s_nop 0
	v_cvt_pk_bf16_f32 v51, v52, v53
	global_store_dwordx2 v[130:131], v[50:51], off offset:304 sc1
	s_waitcnt vmcnt(15)
	v_lshlrev_b32_e32 v50, 16, v88
	v_and_b32_e32 v51, 0xffff0000, v88
	v_mul_f32_e32 v52, 0xbfb8aa3b, v50
	v_mul_f32_e32 v53, 0xbfb8aa3b, v51
	v_exp_f32_e32 v52, v52
	v_exp_f32_e32 v53, v53
	v_add_f32_e32 v52, 1.0, v52
	v_add_f32_e32 v53, 1.0, v53
	v_rcp_f32_e32 v52, v52
	v_rcp_f32_e32 v53, v53
	s_nop 0
	v_pk_mul_f32 v[50:51], v[52:53], v[50:51]
	s_nop 0
	v_pk_mul_f32 v[34:35], v[34:35], v[50:51]
	v_lshlrev_b32_e32 v50, 16, v89
	v_cvt_pk_bf16_f32 v34, v34, v35
	v_mul_f32_e32 v35, 0xbfb8aa3b, v50
	v_exp_f32_e32 v35, v35
	v_and_b32_e32 v51, 0xffff0000, v89
	v_add_f32_e32 v35, 1.0, v35
	v_rcp_f32_e32 v52, v35
	v_mul_f32_e32 v35, 0xbfb8aa3b, v51
	v_exp_f32_e32 v35, v35
	s_nop 0
	v_add_f32_e32 v35, 1.0, v35
	v_rcp_f32_e32 v53, v35
	s_nop 0
	v_pk_mul_f32 v[50:51], v[52:53], v[50:51]
	s_nop 0
	v_pk_mul_f32 v[36:37], v[36:37], v[50:51]
	s_nop 0
	v_cvt_pk_bf16_f32 v35, v36, v37
	global_store_dwordx2 v[130:131], v[34:35], off offset:320 sc1
	s_waitcnt vmcnt(15)
	v_lshlrev_b32_e32 v34, 16, v86
	v_and_b32_e32 v35, 0xffff0000, v86
	v_mul_f32_e32 v36, 0xbfb8aa3b, v34
	v_mul_f32_e32 v37, 0xbfb8aa3b, v35
	v_exp_f32_e32 v36, v36
	v_exp_f32_e32 v37, v37
	v_add_f32_e32 v36, 1.0, v36
	v_add_f32_e32 v37, 1.0, v37
	v_rcp_f32_e32 v36, v36
	v_rcp_f32_e32 v37, v37
	s_nop 0
	v_pk_mul_f32 v[34:35], v[36:37], v[34:35]
	s_nop 0
	v_pk_mul_f32 v[34:35], v[38:39], v[34:35]
	v_lshlrev_b32_e32 v36, 16, v87
	v_cvt_pk_bf16_f32 v34, v34, v35
	v_mul_f32_e32 v35, 0xbfb8aa3b, v36
	v_exp_f32_e32 v35, v35
	v_and_b32_e32 v37, 0xffff0000, v87
	v_add_f32_e32 v35, 1.0, v35
	v_rcp_f32_e32 v38, v35
	v_mul_f32_e32 v35, 0xbfb8aa3b, v37
	v_exp_f32_e32 v35, v35
	s_nop 0
	v_add_f32_e32 v35, 1.0, v35
	v_rcp_f32_e32 v39, v35
	s_nop 0
	v_pk_mul_f32 v[36:37], v[38:39], v[36:37]
	s_nop 0
	v_pk_mul_f32 v[36:37], v[40:41], v[36:37]
	v_pk_mul_f32 v[38:39], v[0:1], v[42:43] op_sel_hi:[0,1]
	v_cvt_pk_bf16_f32 v35, v36, v37
	global_store_dwordx2 v[130:131], v[34:35], off offset:336 sc1
	s_waitcnt vmcnt(15)
	v_lshlrev_b32_e32 v34, 16, v84
	v_and_b32_e32 v35, 0xffff0000, v84
	v_mul_f32_e32 v36, 0xbfb8aa3b, v34
	v_mul_f32_e32 v37, 0xbfb8aa3b, v35
	v_exp_f32_e32 v36, v36
	v_exp_f32_e32 v37, v37
	v_pk_mul_f32 v[40:41], v[0:1], v[44:45] op_sel_hi:[0,1]
	v_add_f32_e32 v36, 1.0, v36
	v_add_f32_e32 v37, 1.0, v37
	v_rcp_f32_e32 v36, v36
	v_rcp_f32_e32 v37, v37
	s_nop 0
	v_pk_mul_f32 v[34:35], v[36:37], v[34:35]
	s_nop 0
	v_pk_mul_f32 v[34:35], v[38:39], v[34:35]
	v_lshlrev_b32_e32 v36, 16, v85
	v_cvt_pk_bf16_f32 v34, v34, v35
	v_mul_f32_e32 v35, 0xbfb8aa3b, v36
	v_exp_f32_e32 v35, v35
	v_and_b32_e32 v37, 0xffff0000, v85
	v_add_f32_e32 v35, 1.0, v35
	v_rcp_f32_e32 v38, v35
	v_mul_f32_e32 v35, 0xbfb8aa3b, v37
	v_exp_f32_e32 v35, v35
	s_nop 0
	v_add_f32_e32 v35, 1.0, v35
	v_rcp_f32_e32 v39, v35
	s_nop 0
	v_pk_mul_f32 v[36:37], v[38:39], v[36:37]
	s_nop 0
	v_pk_mul_f32 v[36:37], v[40:41], v[36:37]
	v_pk_mul_f32 v[38:39], v[0:1], v[46:47] op_sel_hi:[0,1]
	v_cvt_pk_bf16_f32 v35, v36, v37
	global_store_dwordx2 v[130:131], v[34:35], off offset:352 sc1
	s_waitcnt vmcnt(15)
	v_lshlrev_b32_e32 v34, 16, v82
	v_and_b32_e32 v35, 0xffff0000, v82
	v_mul_f32_e32 v36, 0xbfb8aa3b, v34
	v_mul_f32_e32 v37, 0xbfb8aa3b, v35
	v_exp_f32_e32 v36, v36
	v_exp_f32_e32 v37, v37
	v_pk_mul_f32 v[40:41], v[0:1], v[48:49] op_sel_hi:[0,1]
	v_add_f32_e32 v36, 1.0, v36
	v_add_f32_e32 v37, 1.0, v37
	v_rcp_f32_e32 v36, v36
	v_rcp_f32_e32 v37, v37
	s_nop 0
	v_pk_mul_f32 v[34:35], v[36:37], v[34:35]
	s_nop 0
	v_pk_mul_f32 v[34:35], v[38:39], v[34:35]
	v_lshlrev_b32_e32 v36, 16, v83
	v_cvt_pk_bf16_f32 v34, v34, v35
	v_mul_f32_e32 v35, 0xbfb8aa3b, v36
	v_exp_f32_e32 v35, v35
	v_and_b32_e32 v37, 0xffff0000, v83
	v_add_f32_e32 v35, 1.0, v35
	v_rcp_f32_e32 v38, v35
	v_mul_f32_e32 v35, 0xbfb8aa3b, v37
	v_exp_f32_e32 v35, v35
	s_nop 0
	v_add_f32_e32 v35, 1.0, v35
	v_rcp_f32_e32 v39, v35
	s_nop 0
	v_pk_mul_f32 v[36:37], v[38:39], v[36:37]
	s_nop 0
	v_pk_mul_f32 v[36:37], v[40:41], v[36:37]
	s_nop 0
	v_cvt_pk_bf16_f32 v35, v36, v37
	global_store_dwordx2 v[130:131], v[34:35], off offset:368 sc1
	s_waitcnt vmcnt(15)
	v_lshlrev_b32_e32 v34, 16, v80
	v_and_b32_e32 v35, 0xffff0000, v80
	v_mul_f32_e32 v36, 0xbfb8aa3b, v34
	v_mul_f32_e32 v37, 0xbfb8aa3b, v35
	v_exp_f32_e32 v36, v36
	v_exp_f32_e32 v37, v37
	v_add_f32_e32 v36, 1.0, v36
	v_add_f32_e32 v37, 1.0, v37
	v_rcp_f32_e32 v36, v36
	v_rcp_f32_e32 v37, v37
	s_nop 0
	v_pk_mul_f32 v[34:35], v[36:37], v[34:35]
	s_nop 0
	v_pk_mul_f32 v[18:19], v[18:19], v[34:35]
	v_lshlrev_b32_e32 v34, 16, v81
	v_cvt_pk_bf16_f32 v18, v18, v19
	v_mul_f32_e32 v19, 0xbfb8aa3b, v34
	v_exp_f32_e32 v19, v19
	v_and_b32_e32 v35, 0xffff0000, v81
	v_add_f32_e32 v19, 1.0, v19
	v_rcp_f32_e32 v36, v19
	v_mul_f32_e32 v19, 0xbfb8aa3b, v35
	v_exp_f32_e32 v19, v19
	s_nop 0
	v_add_f32_e32 v19, 1.0, v19
	v_rcp_f32_e32 v37, v19
	s_nop 0
	v_pk_mul_f32 v[34:35], v[36:37], v[34:35]
	s_nop 0
	v_pk_mul_f32 v[20:21], v[20:21], v[34:35]
	s_nop 0
	v_cvt_pk_bf16_f32 v19, v20, v21
	global_store_dwordx2 v[130:131], v[18:19], off offset:384 sc1
	s_waitcnt vmcnt(15)
	v_lshlrev_b32_e32 v18, 16, v78
	v_and_b32_e32 v19, 0xffff0000, v78
	v_mul_f32_e32 v20, 0xbfb8aa3b, v18
	v_mul_f32_e32 v21, 0xbfb8aa3b, v19
	v_exp_f32_e32 v20, v20
	v_exp_f32_e32 v21, v21
	v_add_f32_e32 v20, 1.0, v20
	v_add_f32_e32 v21, 1.0, v21
	v_rcp_f32_e32 v20, v20
	v_rcp_f32_e32 v21, v21
	s_nop 0
	v_pk_mul_f32 v[18:19], v[20:21], v[18:19]
	s_nop 0
	v_pk_mul_f32 v[18:19], v[22:23], v[18:19]
	v_lshlrev_b32_e32 v20, 16, v79
	v_cvt_pk_bf16_f32 v18, v18, v19
	v_mul_f32_e32 v19, 0xbfb8aa3b, v20
	v_exp_f32_e32 v19, v19
	v_and_b32_e32 v21, 0xffff0000, v79
	v_add_f32_e32 v19, 1.0, v19
	v_rcp_f32_e32 v22, v19
	v_mul_f32_e32 v19, 0xbfb8aa3b, v21
	v_exp_f32_e32 v19, v19
	s_nop 0
	v_add_f32_e32 v19, 1.0, v19
	v_rcp_f32_e32 v23, v19
	s_nop 0
	v_pk_mul_f32 v[20:21], v[22:23], v[20:21]
	s_nop 0
	v_pk_mul_f32 v[20:21], v[24:25], v[20:21]
	v_pk_mul_f32 v[22:23], v[0:1], v[26:27] op_sel_hi:[0,1]
	v_cvt_pk_bf16_f32 v19, v20, v21
	global_store_dwordx2 v[130:131], v[18:19], off offset:400 sc1
	s_waitcnt vmcnt(15)
	v_lshlrev_b32_e32 v18, 16, v76
	v_and_b32_e32 v19, 0xffff0000, v76
	v_mul_f32_e32 v20, 0xbfb8aa3b, v18
	v_mul_f32_e32 v21, 0xbfb8aa3b, v19
	v_exp_f32_e32 v20, v20
	v_exp_f32_e32 v21, v21
	v_pk_mul_f32 v[24:25], v[0:1], v[28:29] op_sel_hi:[0,1]
	v_add_f32_e32 v20, 1.0, v20
	v_add_f32_e32 v21, 1.0, v21
	v_rcp_f32_e32 v20, v20
	v_rcp_f32_e32 v21, v21
	s_nop 0
	v_pk_mul_f32 v[18:19], v[20:21], v[18:19]
	s_nop 0
	v_pk_mul_f32 v[18:19], v[22:23], v[18:19]
	v_lshlrev_b32_e32 v20, 16, v77
	v_cvt_pk_bf16_f32 v18, v18, v19
	v_mul_f32_e32 v19, 0xbfb8aa3b, v20
	v_exp_f32_e32 v19, v19
	v_and_b32_e32 v21, 0xffff0000, v77
	v_add_f32_e32 v19, 1.0, v19
	v_rcp_f32_e32 v22, v19
	v_mul_f32_e32 v19, 0xbfb8aa3b, v21
	v_exp_f32_e32 v19, v19
	s_nop 0
	v_add_f32_e32 v19, 1.0, v19
	v_rcp_f32_e32 v23, v19
	s_nop 0
	v_pk_mul_f32 v[20:21], v[22:23], v[20:21]
	s_nop 0
	v_pk_mul_f32 v[20:21], v[24:25], v[20:21]
	v_pk_mul_f32 v[22:23], v[0:1], v[30:31] op_sel_hi:[0,1]
	v_cvt_pk_bf16_f32 v19, v20, v21
	global_store_dwordx2 v[130:131], v[18:19], off offset:416 sc1
	s_waitcnt vmcnt(15)
	v_lshlrev_b32_e32 v18, 16, v74
	v_and_b32_e32 v19, 0xffff0000, v74
	v_mul_f32_e32 v20, 0xbfb8aa3b, v18
	v_mul_f32_e32 v21, 0xbfb8aa3b, v19
	v_exp_f32_e32 v20, v20
	v_exp_f32_e32 v21, v21
	v_pk_mul_f32 v[24:25], v[0:1], v[32:33] op_sel_hi:[0,1]
	v_add_f32_e32 v20, 1.0, v20
	v_add_f32_e32 v21, 1.0, v21
	v_rcp_f32_e32 v20, v20
	v_rcp_f32_e32 v21, v21
	s_nop 0
	v_pk_mul_f32 v[18:19], v[20:21], v[18:19]
	s_nop 0
	v_pk_mul_f32 v[18:19], v[22:23], v[18:19]
	v_lshlrev_b32_e32 v20, 16, v75
	v_cvt_pk_bf16_f32 v18, v18, v19
	v_mul_f32_e32 v19, 0xbfb8aa3b, v20
	v_exp_f32_e32 v19, v19
	v_and_b32_e32 v21, 0xffff0000, v75
	v_add_f32_e32 v19, 1.0, v19
	v_rcp_f32_e32 v22, v19
	v_mul_f32_e32 v19, 0xbfb8aa3b, v21
	v_exp_f32_e32 v19, v19
	s_nop 0
	v_add_f32_e32 v19, 1.0, v19
	v_rcp_f32_e32 v23, v19
	s_nop 0
	v_pk_mul_f32 v[20:21], v[22:23], v[20:21]
	s_nop 0
	v_pk_mul_f32 v[20:21], v[24:25], v[20:21]
	s_nop 0
	v_cvt_pk_bf16_f32 v19, v20, v21
	global_store_dwordx2 v[130:131], v[18:19], off offset:432 sc1
	s_waitcnt vmcnt(15)
	v_lshlrev_b32_e32 v18, 16, v72
	v_and_b32_e32 v19, 0xffff0000, v72
	v_mul_f32_e32 v20, 0xbfb8aa3b, v18
	v_mul_f32_e32 v21, 0xbfb8aa3b, v19
	v_exp_f32_e32 v20, v20
	v_exp_f32_e32 v21, v21
	v_add_f32_e32 v20, 1.0, v20
	v_add_f32_e32 v21, 1.0, v21
	v_rcp_f32_e32 v20, v20
	v_rcp_f32_e32 v21, v21
	s_nop 0
	v_pk_mul_f32 v[18:19], v[20:21], v[18:19]
	s_nop 0
	v_pk_mul_f32 v[2:3], v[2:3], v[18:19]
	v_lshlrev_b32_e32 v18, 16, v73
	v_cvt_pk_bf16_f32 v2, v2, v3
	v_mul_f32_e32 v3, 0xbfb8aa3b, v18
	v_exp_f32_e32 v3, v3
	v_and_b32_e32 v19, 0xffff0000, v73
	v_add_f32_e32 v3, 1.0, v3
	v_rcp_f32_e32 v20, v3
	v_mul_f32_e32 v3, 0xbfb8aa3b, v19
	v_exp_f32_e32 v3, v3
	s_nop 0
	v_add_f32_e32 v3, 1.0, v3
	v_rcp_f32_e32 v21, v3
	s_nop 0
	v_pk_mul_f32 v[18:19], v[20:21], v[18:19]
	s_nop 0
	v_pk_mul_f32 v[4:5], v[4:5], v[18:19]
	s_nop 0
	v_cvt_pk_bf16_f32 v3, v4, v5
	global_store_dwordx2 v[130:131], v[2:3], off offset:448 sc1
	s_waitcnt vmcnt(15)
	v_lshlrev_b32_e32 v2, 16, v70
	v_and_b32_e32 v3, 0xffff0000, v70
	v_mul_f32_e32 v4, 0xbfb8aa3b, v2
	v_mul_f32_e32 v5, 0xbfb8aa3b, v3
	v_exp_f32_e32 v4, v4
	v_exp_f32_e32 v5, v5
	v_add_f32_e32 v4, 1.0, v4
	v_add_f32_e32 v5, 1.0, v5
	v_rcp_f32_e32 v4, v4
	v_rcp_f32_e32 v5, v5
	s_nop 0
	v_pk_mul_f32 v[2:3], v[4:5], v[2:3]
	s_nop 0
	v_pk_mul_f32 v[2:3], v[6:7], v[2:3]
	v_lshlrev_b32_e32 v4, 16, v71
	v_cvt_pk_bf16_f32 v2, v2, v3
	v_mul_f32_e32 v3, 0xbfb8aa3b, v4
	v_exp_f32_e32 v3, v3
	v_and_b32_e32 v5, 0xffff0000, v71
	v_add_f32_e32 v3, 1.0, v3
	v_rcp_f32_e32 v6, v3
	v_mul_f32_e32 v3, 0xbfb8aa3b, v5
	v_exp_f32_e32 v3, v3
	s_nop 0
	v_add_f32_e32 v3, 1.0, v3
	v_rcp_f32_e32 v7, v3
	s_nop 0
	v_pk_mul_f32 v[4:5], v[6:7], v[4:5]
	s_nop 0
	v_pk_mul_f32 v[4:5], v[8:9], v[4:5]
	v_pk_mul_f32 v[6:7], v[0:1], v[10:11] op_sel_hi:[0,1]
	v_cvt_pk_bf16_f32 v3, v4, v5
	global_store_dwordx2 v[130:131], v[2:3], off offset:464 sc1
	s_waitcnt vmcnt(15)
	v_lshlrev_b32_e32 v2, 16, v68
	v_and_b32_e32 v3, 0xffff0000, v68
	v_mul_f32_e32 v4, 0xbfb8aa3b, v2
	v_mul_f32_e32 v5, 0xbfb8aa3b, v3
	v_exp_f32_e32 v4, v4
	v_exp_f32_e32 v5, v5
	v_pk_mul_f32 v[8:9], v[0:1], v[12:13] op_sel_hi:[0,1]
	v_add_f32_e32 v4, 1.0, v4
	v_add_f32_e32 v5, 1.0, v5
	v_rcp_f32_e32 v4, v4
	v_rcp_f32_e32 v5, v5
	s_nop 0
	v_pk_mul_f32 v[2:3], v[4:5], v[2:3]
	s_nop 0
	v_pk_mul_f32 v[2:3], v[6:7], v[2:3]
	v_lshlrev_b32_e32 v4, 16, v69
	v_cvt_pk_bf16_f32 v2, v2, v3
	v_mul_f32_e32 v3, 0xbfb8aa3b, v4
	v_exp_f32_e32 v3, v3
	v_and_b32_e32 v5, 0xffff0000, v69
	v_add_f32_e32 v3, 1.0, v3
	v_rcp_f32_e32 v6, v3
	v_mul_f32_e32 v3, 0xbfb8aa3b, v5
	v_exp_f32_e32 v3, v3
	s_nop 0
	v_add_f32_e32 v3, 1.0, v3
	v_rcp_f32_e32 v7, v3
	s_nop 0
	v_pk_mul_f32 v[4:5], v[6:7], v[4:5]
	s_nop 0
	v_pk_mul_f32 v[4:5], v[8:9], v[4:5]
	v_pk_mul_f32 v[6:7], v[0:1], v[14:15] op_sel_hi:[0,1]
	v_cvt_pk_bf16_f32 v3, v4, v5
	global_store_dwordx2 v[130:131], v[2:3], off offset:480 sc1
	s_waitcnt vmcnt(15)
	v_lshlrev_b32_e32 v2, 16, v66
	v_and_b32_e32 v3, 0xffff0000, v66
	v_mul_f32_e32 v4, 0xbfb8aa3b, v2
	v_mul_f32_e32 v5, 0xbfb8aa3b, v3
	v_exp_f32_e32 v4, v4
	v_exp_f32_e32 v5, v5
	v_pk_mul_f32 v[8:9], v[0:1], v[16:17] op_sel_hi:[0,1]
	v_add_f32_e32 v4, 1.0, v4
	v_add_f32_e32 v5, 1.0, v5
	v_rcp_f32_e32 v4, v4
	v_rcp_f32_e32 v5, v5
	s_nop 0
	v_pk_mul_f32 v[2:3], v[4:5], v[2:3]
	s_nop 0
	v_pk_mul_f32 v[2:3], v[6:7], v[2:3]
	v_lshlrev_b32_e32 v4, 16, v67
	v_and_b32_e32 v5, 0xffff0000, v67
	v_cvt_pk_bf16_f32 v2, v2, v3
	v_mul_f32_e32 v3, 0xbfb8aa3b, v4
	v_mul_f32_e32 v0, 0xbfb8aa3b, v5
	v_exp_f32_e32 v3, v3
	v_exp_f32_e32 v0, v0
	v_add_f32_e32 v3, 1.0, v3
	v_add_f32_e32 v0, 1.0, v0
	v_rcp_f32_e32 v6, v3
	v_rcp_f32_e32 v7, v0
	s_nop 0
	v_pk_mul_f32 v[4:5], v[6:7], v[4:5]
	s_nop 0
	v_pk_mul_f32 v[4:5], v[8:9], v[4:5]
	s_nop 0
	v_cvt_pk_bf16_f32 v3, v4, v5
	global_store_dwordx2 v[130:131], v[2:3], off offset:496 sc1
	s_barrier

.LBB0_406:
	s_waitcnt vmcnt(0)
	v_mul_f32_e32 v14, v115, v115
	v_fmac_f32_e32 v14, v114, v114
	v_fmac_f32_e32 v14, v116, v116
	v_fmac_f32_e32 v14, v117, v117
	v_fmac_f32_e32 v14, v118, v118
	v_fmac_f32_e32 v14, v119, v119
	v_fmac_f32_e32 v14, v120, v120
	v_fmac_f32_e32 v14, v121, v121
	v_fmac_f32_e32 v14, v122, v122
	v_fmac_f32_e32 v14, v123, v123
	v_fmac_f32_e32 v14, v124, v124
	v_fmac_f32_e32 v14, v125, v125
	v_fmac_f32_e32 v14, v126, v126
	v_fmac_f32_e32 v14, v127, v127
	v_fmac_f32_e32 v14, v128, v128
	v_fmac_f32_e32 v14, v129, v129
	v_fmac_f32_e32 v14, v98, v98
	v_fmac_f32_e32 v14, v99, v99
	v_fmac_f32_e32 v14, v100, v100
	v_fmac_f32_e32 v14, v101, v101
	v_fmac_f32_e32 v14, v102, v102
	v_fmac_f32_e32 v14, v103, v103
	v_fmac_f32_e32 v14, v104, v104
	v_fmac_f32_e32 v14, v105, v105
	v_fmac_f32_e32 v14, v106, v106
	v_fmac_f32_e32 v14, v107, v107
	v_fmac_f32_e32 v14, v108, v108
	v_fmac_f32_e32 v14, v109, v109
	v_fmac_f32_e32 v14, v110, v110
	v_fmac_f32_e32 v14, v111, v111
	v_fmac_f32_e32 v14, v112, v112
	v_fmac_f32_e32 v14, v113, v113
	v_fmac_f32_e32 v14, v82, v82
	v_fmac_f32_e32 v14, v83, v83
	v_fmac_f32_e32 v14, v84, v84
	v_fmac_f32_e32 v14, v85, v85
	v_fmac_f32_e32 v14, v86, v86
	v_fmac_f32_e32 v14, v87, v87
	v_fmac_f32_e32 v14, v88, v88
	v_fmac_f32_e32 v14, v89, v89
	v_fmac_f32_e32 v14, v90, v90
	v_fmac_f32_e32 v14, v91, v91
	v_fmac_f32_e32 v14, v92, v92
	v_fmac_f32_e32 v14, v93, v93
	v_fmac_f32_e32 v14, v94, v94
	v_fmac_f32_e32 v14, v95, v95
	v_fmac_f32_e32 v14, v96, v96
	v_fmac_f32_e32 v14, v97, v97
	v_fmac_f32_e32 v14, v66, v66
	v_fmac_f32_e32 v14, v67, v67
	v_fmac_f32_e32 v14, v68, v68
	v_fmac_f32_e32 v14, v69, v69
	v_pk_mul_f32 v[12:13], v[70:71], v[70:71]
	v_pk_mul_f32 v[10:11], v[72:73], v[72:73]
	v_add_f32_e32 v12, v12, v14
	v_add_f32_e32 v12, v13, v12
	v_add_f32_e32 v10, v10, v12
	v_readlane_b32 s0, v255, 53
	v_pk_mul_f32 v[8:9], v[74:75], v[74:75]
	v_add_f32_e32 v10, v11, v10
	v_readlane_b32 s1, v255, 54
	v_mbcnt_lo_u32_b32 v0, -1, 0
	v_mbcnt_hi_u32_b32 v0, -1, v0
	v_add_f32_e32 v8, v8, v10
	v_pk_mul_f32 v[6:7], v[76:77], v[76:77]
	v_add_f32_e32 v8, v9, v8
	v_add_f32_e32 v6, v6, v8
	s_nop 0
	global_load_dword v166, v1, s[0:1]
	v_pk_mul_f32 v[4:5], v[78:79], v[78:79]
	v_add_f32_e32 v6, v7, v6
	v_and_or_b32 v58, v0, 31, v179
	v_add_f32_e32 v4, v4, v6
	v_ashrrev_i32_e32 v0, 3, v0
	v_pk_mul_f32 v[2:3], v[80:81], v[80:81]
	v_add_f32_e32 v4, v5, v4
	v_and_b32_e32 v0, -4, v0
	v_add_f32_e32 v2, v2, v4
	v_add_u32_e32 v4, s20, v0
	v_mov_b64_e32 v[6:7], s[88:89]
	v_ashrrev_i32_e32 v5, 31, v4
	v_mad_i64_i32 v[6:7], s[0:1], v58, s87, v[6:7]
	v_lshlrev_b64 v[158:159], 1, v[4:5]
	v_lshl_add_u64 v[6:7], v[6:7], 0, v[158:159]
	s_movk_i32 s0, 0x3000
	v_add_co_u32_e32 v8, vcc, s0, v6
	v_readlane_b32 s0, v255, 33
	s_nop 0
	v_addc_co_u32_e32 v9, vcc, 0, v7, vcc
	global_load_dwordx2 v[160:161], v[8:9], off
	v_readlane_b32 s1, v255, 34
	s_load_dwordx2 s[0:1], s[0:1], 0x50
	v_add_f32_e32 v0, v3, v2
	v_mov_b32_e32 v2, v0
	v_mov_b32_e32 v3, v0
	v_readlane_b32 s4, v255, 39
	s_nop 0
	v_permlane32_swap_b32_e32 v2, v3
	v_readlane_b32 s5, v255, 40
	v_cmp_eq_u32_e32 vcc, v2, v0
	s_lshl_b64 s[4:5], s[4:5], 2
	s_waitcnt lgkmcnt(0)
	s_add_u32 s0, s0, s4
	v_cndmask_b32_e32 v8, v2, v3, vcc
	s_addc_u32 s1, s1, s5
	v_add_f32_e32 v0, v0, v8
	v_lshl_add_u64 v[2:3], v[4:5], 2, s[0:1]
	v_fmamk_f32 v0, v0, 0x3c000000, v200
	s_mov_b32 s0, 0xf800000
	global_load_dwordx4 v[146:149], v[2:3], off
	v_mul_f32_e32 v4, 0x4f800000, v0
	v_cmp_gt_f32_e32 vcc, s0, v0
	s_mov_b64 s[0:1], 0x3000
	v_ashrrev_i32_e32 v59, 31, v58
	v_cndmask_b32_e32 v0, v0, v4, vcc
	v_sqrt_f32_e32 v4, v0
	v_lshlrev_b64 v[58:59], 11, v[58:59]
	v_add_u32_e32 v5, -1, v4
	v_fma_f32 v8, -v5, v4, v0
	v_cmp_ge_f32_e64 s[6:7], 0, v8
	v_add_u32_e32 v8, 1, v4
	s_nop 0
	v_cndmask_b32_e64 v5, v4, v5, s[6:7]
	v_fma_f32 v4, -v8, v4, v0
	v_cmp_lt_f32_e64 s[6:7], 0, v4
	s_nop 1
	v_cndmask_b32_e64 v8, v5, v8, s[6:7]
	v_lshl_add_u64 v[4:5], v[6:7], 0, s[0:1]
	global_load_dwordx2 v[162:163], v[4:5], off offset:16
	global_load_dwordx4 v[150:153], v[2:3], off offset:32
	global_load_dwordx2 v[164:165], v[4:5], off offset:32
	global_load_dwordx2 v[144:145], v[4:5], off offset:48
	global_load_dwordx4 v[154:157], v[2:3], off offset:64
	global_load_dwordx4 v[50:53], v[2:3], off offset:96
	global_load_dwordx4 v[46:49], v[2:3], off offset:128
	global_load_dwordx4 v[42:45], v[2:3], off offset:160
	global_load_dwordx2 v[142:143], v[4:5], off offset:64
	global_load_dwordx2 v[140:141], v[4:5], off offset:80
	global_load_dwordx2 v[138:139], v[4:5], off offset:96
	global_load_dwordx2 v[136:137], v[4:5], off offset:112
	global_load_dwordx4 v[38:41], v[2:3], off offset:192
	global_load_dwordx4 v[34:37], v[2:3], off offset:224
	global_load_dwordx4 v[30:33], v[2:3], off offset:256
	global_load_dwordx4 v[26:29], v[2:3], off offset:288
	global_load_dwordx2 v[134:135], v[4:5], off offset:128
	global_load_dwordx2 v[132:133], v[4:5], off offset:144
	global_load_dwordx2 v[130:131], v[4:5], off offset:160
	global_load_dwordx2 v[64:65], v[4:5], off offset:176
	global_load_dwordx4 v[22:25], v[2:3], off offset:320
	global_load_dwordx4 v[18:21], v[2:3], off offset:352
	global_load_dwordx4 v[14:17], v[2:3], off offset:384
	global_load_dwordx4 v[10:13], v[2:3], off offset:416
	v_mul_f32_e32 v6, 0x37800000, v8
	v_cndmask_b32_e32 v6, v8, v6, vcc
	v_cmp_class_f32_e32 vcc, v0, v201
	s_nop 1
	v_cndmask_b32_e32 v0, v6, v0, vcc
	global_load_dwordx2 v[62:63], v[4:5], off offset:192
	global_load_dwordx2 v[60:61], v[4:5], off offset:208
	global_load_dwordx2 v[56:57], v[4:5], off offset:224
	global_load_dwordx2 v[54:55], v[4:5], off offset:240
	global_load_dwordx4 v[6:9], v[2:3], off offset:448
	s_nop 0
	global_load_dwordx4 v[2:5], v[2:3], off offset:480
	s_waitcnt vmcnt(32)
	v_div_scale_f32 v167, s[0:1], v0, v0, v166
	v_rcp_f32_e32 v168, v167
	v_readlane_b32 s0, v255, 51
	v_readlane_b32 s1, v255, 52
	v_fma_f32 v169, -v167, v168, 1.0
	v_fmac_f32_e32 v168, v169, v168
	v_div_scale_f32 v169, vcc, v166, v0, v166
	v_mul_f32_e32 v170, v169, v168
	v_fma_f32 v171, -v167, v170, v169
	v_fmac_f32_e32 v170, v171, v168
	v_fma_f32 v167, -v167, v170, v169
	v_div_fmas_f32 v167, v167, v168, v170
	v_div_fixup_f32 v0, v167, v0, v166
	v_pk_mul_f32 v[114:115], v[114:115], v[0:1] op_sel_hi:[1,0]
	v_pk_mul_f32 v[116:117], v[116:117], v[0:1] op_sel_hi:[1,0]
	v_lshl_add_u64 v[58:59], s[0:1], 0, v[58:59]
	v_lshl_add_u64 v[58:59], v[58:59], 0, v[158:159]
	v_pk_mul_f32 v[120:121], v[120:121], v[0:1] op_sel_hi:[1,0]
	s_mov_b64 s[0:1], 0
	s_waitcnt vmcnt(31)
	v_lshlrev_b32_e32 v166, 16, v160
	v_and_b32_e32 v167, 0xffff0000, v160
	v_mul_f32_e32 v160, 0xbfb8aa3b, v166
	v_exp_f32_e32 v160, v160
	v_mul_f32_e32 v168, 0xbfb8aa3b, v167
	v_exp_f32_e32 v169, v168
	v_add_f32_e32 v160, 1.0, v160
	v_rcp_f32_e32 v168, v160
	v_add_f32_e32 v160, 1.0, v169
	v_rcp_f32_e32 v169, v160
	v_lshlrev_b32_e32 v160, 16, v161
	v_and_b32_e32 v161, 0xffff0000, v161
	s_waitcnt vmcnt(30)
	v_pk_mul_f32 v[114:115], v[146:147], v[114:115]
	v_pk_mul_f32 v[146:147], v[168:169], v[166:167]
	v_mul_f32_e32 v166, 0xbfb8aa3b, v160
	v_mul_f32_e32 v167, 0xbfb8aa3b, v161
	v_exp_f32_e32 v166, v166
	v_exp_f32_e32 v167, v167
	v_pk_mul_f32 v[114:115], v[114:115], v[146:147]
	v_pk_mul_f32 v[116:117], v[148:149], v[116:117]
	v_add_f32_e32 v146, 1.0, v166
	v_add_f32_e32 v147, 1.0, v167
	v_rcp_f32_e32 v146, v146
	v_rcp_f32_e32 v147, v147
	v_cvt_pk_bf16_f32 v114, v114, v115
	s_waitcnt vmcnt(28)
	v_pk_mul_f32 v[120:121], v[152:153], v[120:121]
	v_pk_mul_f32 v[146:147], v[146:147], v[160:161]
	s_nop 0
	v_pk_mul_f32 v[116:117], v[116:117], v[146:147]
	s_nop 0
	v_cvt_pk_bf16_f32 v115, v116, v117
	global_store_dwordx2 v[58:59], v[114:115], off sc1
	v_pk_mul_f32 v[114:115], v[118:119], v[0:1] op_sel_hi:[1,0]
	v_lshlrev_b32_e32 v116, 16, v162
	v_and_b32_e32 v117, 0xffff0000, v162
	v_mul_f32_e32 v146, 0xbfb8aa3b, v116
	v_mul_f32_e32 v147, 0xbfb8aa3b, v117
	v_exp_f32_e32 v146, v146
	v_exp_f32_e32 v147, v147
	v_lshlrev_b32_e32 v118, 16, v163
	v_and_b32_e32 v119, 0xffff0000, v163
	v_add_f32_e32 v146, 1.0, v146
	v_add_f32_e32 v147, 1.0, v147
	v_rcp_f32_e32 v146, v146
	v_rcp_f32_e32 v147, v147
	v_pk_mul_f32 v[114:115], v[150:151], v[114:115]
	v_pk_mul_f32 v[116:117], v[146:147], v[116:117]
	v_mul_f32_e32 v146, 0xbfb8aa3b, v118
	v_mul_f32_e32 v147, 0xbfb8aa3b, v119
	v_exp_f32_e32 v146, v146
	v_exp_f32_e32 v147, v147
	v_pk_mul_f32 v[114:115], v[114:115], v[116:117]
	v_add_f32_e32 v116, 1.0, v146
	v_add_f32_e32 v117, 1.0, v147
	v_rcp_f32_e32 v116, v116
	v_rcp_f32_e32 v117, v117
	v_cvt_pk_bf16_f32 v114, v114, v115
	v_pk_mul_f32 v[116:117], v[116:117], v[118:119]
	s_waitcnt vmcnt(28)
	v_lshlrev_b32_e32 v118, 16, v164
	v_and_b32_e32 v119, 0xffff0000, v164
	v_mul_f32_e32 v115, 0xbfb8aa3b, v118
	v_pk_mul_f32 v[116:117], v[120:121], v[116:117]
	v_exp_f32_e32 v120, v115
	v_mul_f32_e32 v115, 0xbfb8aa3b, v119
	v_exp_f32_e32 v121, v115
	v_cvt_pk_bf16_f32 v115, v116, v117
	v_add_f32_e32 v116, 1.0, v120
	v_rcp_f32_e32 v116, v116
	v_add_f32_e32 v117, 1.0, v121
	v_rcp_f32_e32 v117, v117
	global_store_dwordx2 v[58:59], v[114:115], off offset:16 sc1
	v_pk_mul_f32 v[114:115], v[122:123], v[0:1] op_sel_hi:[1,0]
	v_pk_mul_f32 v[116:117], v[116:117], v[118:119]
	v_lshlrev_b32_e32 v118, 16, v165
	v_and_b32_e32 v119, 0xffff0000, v165
	v_mul_f32_e32 v120, 0xbfb8aa3b, v118
	v_mul_f32_e32 v121, 0xbfb8aa3b, v119
	v_exp_f32_e32 v120, v120
	v_exp_f32_e32 v121, v121
	s_waitcnt vmcnt(27)
	v_pk_mul_f32 v[114:115], v[154:155], v[114:115]
	s_nop 0
	v_pk_mul_f32 v[114:115], v[114:115], v[116:117]
	v_add_f32_e32 v116, 1.0, v120
	v_add_f32_e32 v117, 1.0, v121
	v_rcp_f32_e32 v116, v116
	v_rcp_f32_e32 v117, v117
	v_pk_mul_f32 v[120:121], v[124:125], v[0:1] op_sel_hi:[1,0]
	v_cvt_pk_bf16_f32 v114, v114, v115
	v_pk_mul_f32 v[120:121], v[156:157], v[120:121]
	v_pk_mul_f32 v[116:117], v[116:117], v[118:119]
	v_lshlrev_b32_e32 v118, 16, v144
	v_and_b32_e32 v119, 0xffff0000, v144
	v_mul_f32_e32 v115, 0xbfb8aa3b, v118
	v_pk_mul_f32 v[116:117], v[120:121], v[116:117]
	v_exp_f32_e32 v120, v115
	v_mul_f32_e32 v115, 0xbfb8aa3b, v119
	v_exp_f32_e32 v121, v115
	v_cvt_pk_bf16_f32 v115, v116, v117
	v_add_f32_e32 v116, 1.0, v120
	v_rcp_f32_e32 v116, v116
	v_add_f32_e32 v117, 1.0, v121
	v_rcp_f32_e32 v117, v117
	global_store_dwordx2 v[58:59], v[114:115], off offset:32 sc1
	v_pk_mul_f32 v[114:115], v[126:127], v[0:1] op_sel_hi:[1,0]
	s_waitcnt vmcnt(27)
	v_pk_mul_f32 v[50:51], v[114:115], v[50:51]
	v_pk_mul_f32 v[114:115], v[116:117], v[118:119]
	v_lshlrev_b32_e32 v116, 16, v145
	v_and_b32_e32 v117, 0xffff0000, v145
	v_mul_f32_e32 v118, 0xbfb8aa3b, v116
	v_mul_f32_e32 v119, 0xbfb8aa3b, v117
	v_exp_f32_e32 v118, v118
	v_exp_f32_e32 v119, v119
	v_pk_mul_f32 v[50:51], v[50:51], v[114:115]
	v_add_f32_e32 v114, 1.0, v118
	v_add_f32_e32 v115, 1.0, v119
	v_rcp_f32_e32 v114, v114
	v_rcp_f32_e32 v115, v115
	v_pk_mul_f32 v[118:119], v[128:129], v[0:1] op_sel_hi:[1,0]
	v_cvt_pk_bf16_f32 v50, v50, v51
	v_pk_mul_f32 v[52:53], v[118:119], v[52:53]
	v_pk_mul_f32 v[114:115], v[114:115], v[116:117]
	s_nop 0
	v_pk_mul_f32 v[52:53], v[52:53], v[114:115]
	s_waitcnt vmcnt(24)
	v_lshlrev_b32_e32 v114, 16, v142
	v_and_b32_e32 v115, 0xffff0000, v142
	v_mul_f32_e32 v51, 0xbfb8aa3b, v114
	v_exp_f32_e32 v116, v51
	v_mul_f32_e32 v51, 0xbfb8aa3b, v115
	v_exp_f32_e32 v117, v51
	v_cvt_pk_bf16_f32 v51, v52, v53
	v_add_f32_e32 v52, 1.0, v116
	v_rcp_f32_e32 v52, v52
	v_add_f32_e32 v53, 1.0, v117
	v_rcp_f32_e32 v53, v53
	global_store_dwordx2 v[58:59], v[50:51], off offset:48 sc1
	v_pk_mul_f32 v[50:51], v[98:99], v[0:1] op_sel_hi:[1,0]
	s_nop 0
	v_pk_mul_f32 v[46:47], v[50:51], v[46:47]
	v_pk_mul_f32 v[50:51], v[52:53], v[114:115]
	v_lshlrev_b32_e32 v52, 16, v143
	v_and_b32_e32 v53, 0xffff0000, v143
	v_mul_f32_e32 v98, 0xbfb8aa3b, v52
	v_mul_f32_e32 v99, 0xbfb8aa3b, v53
	v_exp_f32_e32 v98, v98
	v_exp_f32_e32 v99, v99
	v_pk_mul_f32 v[46:47], v[46:47], v[50:51]
	v_add_f32_e32 v50, 1.0, v98
	v_add_f32_e32 v51, 1.0, v99
	v_rcp_f32_e32 v50, v50
	v_rcp_f32_e32 v51, v51
	v_pk_mul_f32 v[98:99], v[100:101], v[0:1] op_sel_hi:[1,0]
	v_cvt_pk_bf16_f32 v46, v46, v47
	v_pk_mul_f32 v[48:49], v[98:99], v[48:49]
	v_pk_mul_f32 v[50:51], v[50:51], v[52:53]
	s_nop 0
	v_pk_mul_f32 v[48:49], v[48:49], v[50:51]
	s_waitcnt vmcnt(24)
	v_lshlrev_b32_e32 v50, 16, v140
	v_and_b32_e32 v51, 0xffff0000, v140
	v_mul_f32_e32 v47, 0xbfb8aa3b, v50
	v_exp_f32_e32 v52, v47
	v_mul_f32_e32 v47, 0xbfb8aa3b, v51
	v_exp_f32_e32 v53, v47
	v_cvt_pk_bf16_f32 v47, v48, v49
	v_add_f32_e32 v48, 1.0, v52
	v_rcp_f32_e32 v48, v48
	v_add_f32_e32 v49, 1.0, v53
	v_rcp_f32_e32 v49, v49
	global_store_dwordx2 v[58:59], v[46:47], off offset:64 sc1
	v_pk_mul_f32 v[46:47], v[102:103], v[0:1] op_sel_hi:[1,0]
	s_nop 0
	v_pk_mul_f32 v[42:43], v[46:47], v[42:43]
	v_pk_mul_f32 v[46:47], v[48:49], v[50:51]
	v_lshlrev_b32_e32 v48, 16, v141
	v_and_b32_e32 v49, 0xffff0000, v141
	v_mul_f32_e32 v50, 0xbfb8aa3b, v48
	v_mul_f32_e32 v51, 0xbfb8aa3b, v49
	v_exp_f32_e32 v50, v50
	v_exp_f32_e32 v51, v51
	v_pk_mul_f32 v[42:43], v[42:43], v[46:47]
	v_add_f32_e32 v46, 1.0, v50
	v_add_f32_e32 v47, 1.0, v51
	v_rcp_f32_e32 v46, v46
	v_rcp_f32_e32 v47, v47
	v_pk_mul_f32 v[50:51], v[104:105], v[0:1] op_sel_hi:[1,0]
	v_cvt_pk_bf16_f32 v42, v42, v43
	v_pk_mul_f32 v[44:45], v[50:51], v[44:45]
	v_pk_mul_f32 v[46:47], v[46:47], v[48:49]
	s_nop 0
	v_pk_mul_f32 v[44:45], v[44:45], v[46:47]
	s_waitcnt vmcnt(24)
	v_lshlrev_b32_e32 v46, 16, v138
	v_and_b32_e32 v47, 0xffff0000, v138
	v_mul_f32_e32 v43, 0xbfb8aa3b, v46
	v_exp_f32_e32 v48, v43
	v_mul_f32_e32 v43, 0xbfb8aa3b, v47
	v_exp_f32_e32 v49, v43
	v_cvt_pk_bf16_f32 v43, v44, v45
	v_add_f32_e32 v44, 1.0, v48
	v_rcp_f32_e32 v44, v44
	v_add_f32_e32 v45, 1.0, v49
	v_rcp_f32_e32 v45, v45
	global_store_dwordx2 v[58:59], v[42:43], off offset:80 sc1
	v_pk_mul_f32 v[42:43], v[106:107], v[0:1] op_sel_hi:[1,0]
	s_waitcnt vmcnt(23)
	v_pk_mul_f32 v[38:39], v[42:43], v[38:39]
	v_pk_mul_f32 v[42:43], v[44:45], v[46:47]
	v_lshlrev_b32_e32 v44, 16, v139
	v_and_b32_e32 v45, 0xffff0000, v139
	v_mul_f32_e32 v46, 0xbfb8aa3b, v44
	v_mul_f32_e32 v47, 0xbfb8aa3b, v45
	v_exp_f32_e32 v46, v46
	v_exp_f32_e32 v47, v47
	v_pk_mul_f32 v[38:39], v[38:39], v[42:43]
	v_add_f32_e32 v42, 1.0, v46
	v_add_f32_e32 v43, 1.0, v47
	v_rcp_f32_e32 v42, v42
	v_rcp_f32_e32 v43, v43
	v_pk_mul_f32 v[46:47], v[108:109], v[0:1] op_sel_hi:[1,0]
	v_cvt_pk_bf16_f32 v38, v38, v39
	v_pk_mul_f32 v[40:41], v[46:47], v[40:41]
	v_pk_mul_f32 v[42:43], v[42:43], v[44:45]
	s_nop 0
	v_pk_mul_f32 v[40:41], v[40:41], v[42:43]
	v_lshlrev_b32_e32 v42, 16, v136
	v_and_b32_e32 v43, 0xffff0000, v136
	v_mul_f32_e32 v39, 0xbfb8aa3b, v42
	v_exp_f32_e32 v44, v39
	v_mul_f32_e32 v39, 0xbfb8aa3b, v43
	v_exp_f32_e32 v45, v39
	v_cvt_pk_bf16_f32 v39, v40, v41
	v_add_f32_e32 v40, 1.0, v44
	v_rcp_f32_e32 v40, v40
	v_add_f32_e32 v41, 1.0, v45
	v_rcp_f32_e32 v41, v41
	global_store_dwordx2 v[58:59], v[38:39], off offset:96 sc1
	v_pk_mul_f32 v[38:39], v[110:111], v[0:1] op_sel_hi:[1,0]
	s_waitcnt vmcnt(23)
	v_pk_mul_f32 v[34:35], v[38:39], v[34:35]
	v_pk_mul_f32 v[38:39], v[40:41], v[42:43]
	v_lshlrev_b32_e32 v40, 16, v137
	v_and_b32_e32 v41, 0xffff0000, v137
	v_mul_f32_e32 v42, 0xbfb8aa3b, v40
	v_mul_f32_e32 v43, 0xbfb8aa3b, v41
	v_exp_f32_e32 v42, v42
	v_exp_f32_e32 v43, v43
	v_pk_mul_f32 v[34:35], v[34:35], v[38:39]
	v_add_f32_e32 v38, 1.0, v42
	v_add_f32_e32 v39, 1.0, v43
	v_rcp_f32_e32 v38, v38
	v_rcp_f32_e32 v39, v39
	v_pk_mul_f32 v[42:43], v[112:113], v[0:1] op_sel_hi:[1,0]
	v_cvt_pk_bf16_f32 v34, v34, v35
	v_pk_mul_f32 v[36:37], v[42:43], v[36:37]
	v_pk_mul_f32 v[38:39], v[38:39], v[40:41]
	s_nop 0
	v_pk_mul_f32 v[36:37], v[36:37], v[38:39]
	s_waitcnt vmcnt(20)
	v_lshlrev_b32_e32 v38, 16, v134
	v_and_b32_e32 v39, 0xffff0000, v134
	v_mul_f32_e32 v35, 0xbfb8aa3b, v38
	v_exp_f32_e32 v40, v35
	v_mul_f32_e32 v35, 0xbfb8aa3b, v39
	v_exp_f32_e32 v41, v35
	v_cvt_pk_bf16_f32 v35, v36, v37
	v_add_f32_e32 v36, 1.0, v40
	v_rcp_f32_e32 v36, v36
	v_add_f32_e32 v37, 1.0, v41
	v_rcp_f32_e32 v37, v37
	global_store_dwordx2 v[58:59], v[34:35], off offset:112 sc1
	v_pk_mul_f32 v[34:35], v[82:83], v[0:1] op_sel_hi:[1,0]
	s_nop 0
	v_pk_mul_f32 v[30:31], v[34:35], v[30:31]
	v_pk_mul_f32 v[34:35], v[36:37], v[38:39]
	v_lshlrev_b32_e32 v36, 16, v135
	v_and_b32_e32 v37, 0xffff0000, v135
	v_mul_f32_e32 v38, 0xbfb8aa3b, v36
	v_mul_f32_e32 v39, 0xbfb8aa3b, v37
	v_exp_f32_e32 v38, v38
	v_exp_f32_e32 v39, v39
	v_pk_mul_f32 v[30:31], v[30:31], v[34:35]
	v_add_f32_e32 v34, 1.0, v38
	v_add_f32_e32 v35, 1.0, v39
	v_rcp_f32_e32 v34, v34
	v_rcp_f32_e32 v35, v35
	v_pk_mul_f32 v[38:39], v[84:85], v[0:1] op_sel_hi:[1,0]
	v_cvt_pk_bf16_f32 v30, v30, v31
	v_pk_mul_f32 v[32:33], v[38:39], v[32:33]
	v_pk_mul_f32 v[34:35], v[34:35], v[36:37]
	s_nop 0
	v_pk_mul_f32 v[32:33], v[32:33], v[34:35]
	s_waitcnt vmcnt(20)
	v_lshlrev_b32_e32 v34, 16, v132
	v_and_b32_e32 v35, 0xffff0000, v132
	v_mul_f32_e32 v31, 0xbfb8aa3b, v34
	v_exp_f32_e32 v36, v31
	v_mul_f32_e32 v31, 0xbfb8aa3b, v35
	v_exp_f32_e32 v37, v31
	v_cvt_pk_bf16_f32 v31, v32, v33
	v_add_f32_e32 v32, 1.0, v36
	v_rcp_f32_e32 v32, v32
	v_add_f32_e32 v33, 1.0, v37
	v_rcp_f32_e32 v33, v33
	global_store_dwordx2 v[58:59], v[30:31], off offset:128 sc1
	v_pk_mul_f32 v[30:31], v[86:87], v[0:1] op_sel_hi:[1,0]
	s_nop 0
	v_pk_mul_f32 v[26:27], v[30:31], v[26:27]
	v_pk_mul_f32 v[30:31], v[32:33], v[34:35]
	v_lshlrev_b32_e32 v32, 16, v133
	v_and_b32_e32 v33, 0xffff0000, v133
	v_mul_f32_e32 v34, 0xbfb8aa3b, v32
	v_mul_f32_e32 v35, 0xbfb8aa3b, v33
	v_exp_f32_e32 v34, v34
	v_exp_f32_e32 v35, v35
	v_pk_mul_f32 v[26:27], v[26:27], v[30:31]
	v_add_f32_e32 v30, 1.0, v34
	v_add_f32_e32 v31, 1.0, v35
	v_rcp_f32_e32 v30, v30
	v_rcp_f32_e32 v31, v31
	v_pk_mul_f32 v[34:35], v[88:89], v[0:1] op_sel_hi:[1,0]
	v_cvt_pk_bf16_f32 v26, v26, v27
	v_pk_mul_f32 v[28:29], v[34:35], v[28:29]
	v_pk_mul_f32 v[30:31], v[30:31], v[32:33]
	s_nop 0
	v_pk_mul_f32 v[28:29], v[28:29], v[30:31]
	s_waitcnt vmcnt(20)
	v_lshlrev_b32_e32 v30, 16, v130
	v_and_b32_e32 v31, 0xffff0000, v130
	v_mul_f32_e32 v27, 0xbfb8aa3b, v30
	v_exp_f32_e32 v32, v27
	v_mul_f32_e32 v27, 0xbfb8aa3b, v31
	v_exp_f32_e32 v33, v27
	v_cvt_pk_bf16_f32 v27, v28, v29
	v_add_f32_e32 v28, 1.0, v32
	v_rcp_f32_e32 v28, v28
	v_add_f32_e32 v29, 1.0, v33
	v_rcp_f32_e32 v29, v29
	global_store_dwordx2 v[58:59], v[26:27], off offset:144 sc1
	v_pk_mul_f32 v[26:27], v[90:91], v[0:1] op_sel_hi:[1,0]
	s_waitcnt vmcnt(19)
	v_pk_mul_f32 v[22:23], v[26:27], v[22:23]
	v_pk_mul_f32 v[26:27], v[28:29], v[30:31]
	v_lshlrev_b32_e32 v28, 16, v131
	v_and_b32_e32 v29, 0xffff0000, v131
	v_mul_f32_e32 v30, 0xbfb8aa3b, v28
	v_mul_f32_e32 v31, 0xbfb8aa3b, v29
	v_exp_f32_e32 v30, v30
	v_exp_f32_e32 v31, v31
	v_pk_mul_f32 v[22:23], v[22:23], v[26:27]
	v_add_f32_e32 v26, 1.0, v30
	v_add_f32_e32 v27, 1.0, v31
	v_rcp_f32_e32 v26, v26
	v_rcp_f32_e32 v27, v27
	v_pk_mul_f32 v[30:31], v[92:93], v[0:1] op_sel_hi:[1,0]
	v_cvt_pk_bf16_f32 v22, v22, v23
	v_pk_mul_f32 v[24:25], v[30:31], v[24:25]
	v_pk_mul_f32 v[26:27], v[26:27], v[28:29]
	s_nop 0
	v_pk_mul_f32 v[24:25], v[24:25], v[26:27]
	v_lshlrev_b32_e32 v26, 16, v64
	v_and_b32_e32 v27, 0xffff0000, v64
	v_mul_f32_e32 v23, 0xbfb8aa3b, v26
	v_exp_f32_e32 v28, v23
	v_mul_f32_e32 v23, 0xbfb8aa3b, v27
	v_exp_f32_e32 v29, v23
	v_cvt_pk_bf16_f32 v23, v24, v25
	v_add_f32_e32 v24, 1.0, v28
	v_rcp_f32_e32 v24, v24
	v_add_f32_e32 v25, 1.0, v29
	v_rcp_f32_e32 v25, v25
	global_store_dwordx2 v[58:59], v[22:23], off offset:160 sc1
	v_pk_mul_f32 v[22:23], v[94:95], v[0:1] op_sel_hi:[1,0]
	s_waitcnt vmcnt(19)
	v_pk_mul_f32 v[18:19], v[22:23], v[18:19]
	v_pk_mul_f32 v[22:23], v[24:25], v[26:27]
	v_lshlrev_b32_e32 v24, 16, v65
	v_and_b32_e32 v25, 0xffff0000, v65
	v_mul_f32_e32 v26, 0xbfb8aa3b, v24
	v_mul_f32_e32 v27, 0xbfb8aa3b, v25
	v_exp_f32_e32 v26, v26
	v_exp_f32_e32 v27, v27
	v_pk_mul_f32 v[18:19], v[18:19], v[22:23]
	v_add_f32_e32 v22, 1.0, v26
	v_add_f32_e32 v23, 1.0, v27
	v_rcp_f32_e32 v22, v22
	v_rcp_f32_e32 v23, v23
	v_pk_mul_f32 v[26:27], v[96:97], v[0:1] op_sel_hi:[1,0]
	v_cvt_pk_bf16_f32 v18, v18, v19
	v_pk_mul_f32 v[20:21], v[26:27], v[20:21]
	v_pk_mul_f32 v[22:23], v[22:23], v[24:25]
	s_nop 0
	v_pk_mul_f32 v[20:21], v[20:21], v[22:23]
	s_waitcnt vmcnt(16)
	v_lshlrev_b32_e32 v22, 16, v62
	v_and_b32_e32 v23, 0xffff0000, v62
	v_mul_f32_e32 v19, 0xbfb8aa3b, v22
	v_exp_f32_e32 v24, v19
	v_mul_f32_e32 v19, 0xbfb8aa3b, v23
	v_exp_f32_e32 v25, v19
	v_cvt_pk_bf16_f32 v19, v20, v21
	v_add_f32_e32 v20, 1.0, v24
	v_rcp_f32_e32 v20, v20
	v_add_f32_e32 v21, 1.0, v25
	v_rcp_f32_e32 v21, v21
	global_store_dwordx2 v[58:59], v[18:19], off offset:176 sc1
	v_pk_mul_f32 v[18:19], v[66:67], v[0:1] op_sel_hi:[1,0]
	s_nop 0
	v_pk_mul_f32 v[14:15], v[18:19], v[14:15]
	v_pk_mul_f32 v[18:19], v[20:21], v[22:23]
	v_lshlrev_b32_e32 v20, 16, v63
	v_and_b32_e32 v21, 0xffff0000, v63
	v_mul_f32_e32 v22, 0xbfb8aa3b, v20
	v_mul_f32_e32 v23, 0xbfb8aa3b, v21
	v_exp_f32_e32 v22, v22
	v_exp_f32_e32 v23, v23
	v_pk_mul_f32 v[14:15], v[14:15], v[18:19]
	v_add_f32_e32 v18, 1.0, v22
	v_add_f32_e32 v19, 1.0, v23
	v_rcp_f32_e32 v18, v18
	v_rcp_f32_e32 v19, v19
	v_pk_mul_f32 v[22:23], v[68:69], v[0:1] op_sel_hi:[1,0]
	v_cvt_pk_bf16_f32 v14, v14, v15
	v_pk_mul_f32 v[16:17], v[22:23], v[16:17]
	v_pk_mul_f32 v[18:19], v[18:19], v[20:21]
	s_nop 0
	v_pk_mul_f32 v[16:17], v[16:17], v[18:19]
	s_waitcnt vmcnt(16)
	v_lshlrev_b32_e32 v18, 16, v60
	v_and_b32_e32 v19, 0xffff0000, v60
	v_mul_f32_e32 v15, 0xbfb8aa3b, v18
	v_exp_f32_e32 v20, v15
	v_mul_f32_e32 v15, 0xbfb8aa3b, v19
	v_exp_f32_e32 v21, v15
	v_cvt_pk_bf16_f32 v15, v16, v17
	v_add_f32_e32 v16, 1.0, v20
	v_rcp_f32_e32 v16, v16
	v_add_f32_e32 v17, 1.0, v21
	v_rcp_f32_e32 v17, v17
	global_store_dwordx2 v[58:59], v[14:15], off offset:192 sc1
	v_pk_mul_f32 v[14:15], v[70:71], v[0:1] op_sel_hi:[1,0]
	s_nop 0
	v_pk_mul_f32 v[10:11], v[14:15], v[10:11]
	v_pk_mul_f32 v[14:15], v[16:17], v[18:19]
	v_lshlrev_b32_e32 v16, 16, v61
	v_and_b32_e32 v17, 0xffff0000, v61
	v_mul_f32_e32 v18, 0xbfb8aa3b, v16
	v_mul_f32_e32 v19, 0xbfb8aa3b, v17
	v_exp_f32_e32 v18, v18
	v_exp_f32_e32 v19, v19
	v_pk_mul_f32 v[10:11], v[10:11], v[14:15]
	v_add_f32_e32 v14, 1.0, v18
	v_add_f32_e32 v15, 1.0, v19
	v_rcp_f32_e32 v14, v14
	v_rcp_f32_e32 v15, v15
	v_pk_mul_f32 v[18:19], v[72:73], v[0:1] op_sel_hi:[1,0]
	v_cvt_pk_bf16_f32 v10, v10, v11
	v_pk_mul_f32 v[12:13], v[18:19], v[12:13]
	v_pk_mul_f32 v[14:15], v[14:15], v[16:17]
	s_nop 0
	v_pk_mul_f32 v[12:13], v[12:13], v[14:15]
	s_waitcnt vmcnt(16)
	v_lshlrev_b32_e32 v14, 16, v56
	v_and_b32_e32 v15, 0xffff0000, v56
	v_mul_f32_e32 v11, 0xbfb8aa3b, v14
	v_exp_f32_e32 v16, v11
	v_mul_f32_e32 v11, 0xbfb8aa3b, v15
	v_exp_f32_e32 v17, v11
	v_cvt_pk_bf16_f32 v11, v12, v13
	v_add_f32_e32 v12, 1.0, v16
	v_rcp_f32_e32 v12, v12
	v_add_f32_e32 v13, 1.0, v17
	v_rcp_f32_e32 v13, v13
	global_store_dwordx2 v[58:59], v[10:11], off offset:208 sc1
	v_pk_mul_f32 v[10:11], v[74:75], v[0:1] op_sel_hi:[1,0]
	s_waitcnt vmcnt(15)
	v_pk_mul_f32 v[6:7], v[10:11], v[6:7]
	v_pk_mul_f32 v[10:11], v[12:13], v[14:15]
	v_lshlrev_b32_e32 v12, 16, v57
	v_and_b32_e32 v13, 0xffff0000, v57
	v_mul_f32_e32 v14, 0xbfb8aa3b, v12
	v_mul_f32_e32 v15, 0xbfb8aa3b, v13
	v_exp_f32_e32 v14, v14
	v_exp_f32_e32 v15, v15
	v_pk_mul_f32 v[6:7], v[6:7], v[10:11]
	v_add_f32_e32 v10, 1.0, v14
	v_add_f32_e32 v11, 1.0, v15
	v_rcp_f32_e32 v10, v10
	v_rcp_f32_e32 v11, v11
	v_pk_mul_f32 v[14:15], v[76:77], v[0:1] op_sel_hi:[1,0]
	v_cvt_pk_bf16_f32 v6, v6, v7
	v_pk_mul_f32 v[8:9], v[14:15], v[8:9]
	v_pk_mul_f32 v[10:11], v[10:11], v[12:13]
	s_nop 0
	v_pk_mul_f32 v[8:9], v[8:9], v[10:11]
	v_lshlrev_b32_e32 v10, 16, v54
	v_and_b32_e32 v11, 0xffff0000, v54
	v_mul_f32_e32 v7, 0xbfb8aa3b, v10
	v_exp_f32_e32 v12, v7
	v_mul_f32_e32 v7, 0xbfb8aa3b, v11
	v_exp_f32_e32 v13, v7
	v_cvt_pk_bf16_f32 v7, v8, v9
	v_add_f32_e32 v8, 1.0, v12
	v_rcp_f32_e32 v8, v8
	v_add_f32_e32 v9, 1.0, v13
	v_rcp_f32_e32 v9, v9
	global_store_dwordx2 v[58:59], v[6:7], off offset:224 sc1
	v_pk_mul_f32 v[6:7], v[78:79], v[0:1] op_sel_hi:[1,0]
	s_waitcnt vmcnt(15)
	v_pk_mul_f32 v[2:3], v[6:7], v[2:3]
	v_pk_mul_f32 v[6:7], v[8:9], v[10:11]
	v_lshlrev_b32_e32 v8, 16, v55
	v_and_b32_e32 v9, 0xffff0000, v55
	v_mul_f32_e32 v10, 0xbfb8aa3b, v8
	v_mul_f32_e32 v11, 0xbfb8aa3b, v9
	v_exp_f32_e32 v10, v10
	v_exp_f32_e32 v11, v11
	v_pk_mul_f32 v[2:3], v[2:3], v[6:7]
	v_add_f32_e32 v6, 1.0, v10
	v_add_f32_e32 v7, 1.0, v11
	v_rcp_f32_e32 v6, v6
	v_rcp_f32_e32 v7, v7
	v_pk_mul_f32 v[10:11], v[80:81], v[0:1] op_sel_hi:[1,0]
	v_cvt_pk_bf16_f32 v2, v2, v3
	v_pk_mul_f32 v[4:5], v[10:11], v[4:5]
	v_pk_mul_f32 v[6:7], v[6:7], v[8:9]
	s_nop 0
	v_pk_mul_f32 v[4:5], v[4:5], v[6:7]
	s_nop 0
	v_cvt_pk_bf16_f32 v3, v4, v5
	global_store_dwordx2 v[58:59], v[2:3], off offset:240 sc1

.LBB0_425:
	s_lshl_b32 s0, s4, 8
	s_ashr_i32 s1, s0, 31
	v_mbcnt_lo_u32_b32 v6, -1, 0
	v_mbcnt_hi_u32_b32 v6, -1, v6
	s_lshl_b64 s[22:23], s[0:1], 2
	v_and_b32_e32 v92, 15, v6
	v_ashrrev_i32_e32 v6, 1, v6
	s_add_u32 s22, s39, s22
	v_and_b32_e32 v6, -8, v6
	s_addc_u32 s23, s40, s23
	s_lshl_b32 s4, s4, 14
	v_add_u32_e32 v90, s81, v6
	v_subrev_u32_e32 v92, s4, v92
	v_ashrrev_i32_e32 v91, 31, v90
	v_add_u32_e32 v184, s44, v92
	v_mov_b64_e32 v[186:187], s[10:11]
	v_lshl_add_u64 v[14:15], v[90:91], 2, s[22:23]
	v_mad_i64_i32 v[92:93], s[4:5], v184, s87, v[186:187]
	s_lshl_b64 s[22:23], s[0:1], 1
	v_lshl_add_u64 v[92:93], v[92:93], 0, s[22:23]
	v_lshlrev_b64 v[188:189], 1, v[90:91]
	v_add_u32_e32 v206, s0, v90
	v_lshl_add_u64 v[90:91], v[92:93], 0, v[188:189]
	s_mov_b64 s[4:5], 0x4000
	v_lshl_add_u64 v[92:93], v[90:91], 0, s[4:5]
	v_add_co_u32_e32 v90, vcc, s84, v90
	global_load_dwordx4 v[22:25], v[14:15], off offset:16
	global_load_dwordx4 v[30:33], v[14:15], off
	global_load_dwordx4 v[6:9], v[14:15], off offset:528
	s_nop 0
	global_load_dwordx4 v[14:17], v[14:15], off offset:512
	v_addc_co_u32_e32 v91, vcc, 0, v91, vcc
	global_load_dwordx4 v[170:173], v[90:91], off
	global_load_dwordx4 v[158:161], v[92:93], off offset:256
	v_add_u32_e32 v204, 16, v184
	v_mad_i64_i32 v[90:91], s[0:1], v204, s87, v[186:187]
	v_lshl_add_u64 v[90:91], v[90:91], 0, s[22:23]
	v_lshl_add_u64 v[90:91], v[90:91], 0, v[188:189]
	v_lshl_add_u64 v[92:93], v[90:91], 0, s[4:5]
	v_add_co_u32_e32 v90, vcc, s84, v90
	v_add_u32_e32 v192, 32, v184
	s_nop 0
	v_addc_co_u32_e32 v91, vcc, 0, v91, vcc
	global_load_dwordx4 v[150:153], v[90:91], off
	global_load_dwordx4 v[138:141], v[92:93], off offset:256
	v_mad_i64_i32 v[90:91], s[0:1], v192, s87, v[186:187]
	v_lshl_add_u64 v[90:91], v[90:91], 0, s[22:23]
	v_lshl_add_u64 v[90:91], v[90:91], 0, v[188:189]
	v_lshl_add_u64 v[92:93], v[90:91], 0, s[4:5]
	v_add_co_u32_e32 v90, vcc, s84, v90
	v_add_u32_e32 v190, 48, v184
	s_nop 0
	v_addc_co_u32_e32 v91, vcc, 0, v91, vcc
	global_load_dwordx4 v[126:129], v[90:91], off
	global_load_dwordx4 v[114:117], v[92:93], off offset:256
	v_mad_i64_i32 v[90:91], s[0:1], v190, s87, v[186:187]
	v_ashrrev_i32_e32 v185, 31, v184
	v_lshl_add_u64 v[90:91], v[90:91], 0, s[22:23]
	v_lshl_add_u64 v[90:91], v[90:91], 0, v[188:189]
	v_lshlrev_b64 v[208:209], 11, v[184:185]
	v_ashrrev_i32_e32 v207, 31, v206
	v_lshl_add_u64 v[92:93], v[90:91], 0, s[4:5]
	v_add_co_u32_e32 v90, vcc, s84, v90
	v_ashrrev_i32_e32 v205, 31, v204
	s_nop 0
	v_addc_co_u32_e32 v91, vcc, 0, v91, vcc
	global_load_dwordx4 v[102:105], v[90:91], off
	s_nop 0
	global_load_dwordx4 v[90:93], v[92:93], off offset:256
	v_ashrrev_i32_e32 v193, 31, v192
	v_ashrrev_i32_e32 v191, 31, v190
	v_mov_b64_e32 v[246:247], v[202:203]
	v_mov_b64_e32 v[202:203], 0x1ff
	s_waitcnt vmcnt(0)
	v_pk_mul_f32 v[166:167], v[166:167], v[22:23]
	v_pk_mul_f32 v[174:175], v[174:175], v[30:31]
	v_pk_mul_f32 v[176:177], v[176:177], v[32:33]
	v_pk_mul_f32 v[168:169], v[168:169], v[24:25]
	v_pk_mul_f32 v[162:163], v[162:163], v[14:15]
	v_lshlrev_b32_e32 v194, 16, v170
	v_and_b32_e32 v195, 0xffff0000, v170
	v_mul_f32_e32 v170, 0xbfb8aa3b, v194
	v_exp_f32_e32 v170, v170
	v_pk_mul_f32 v[164:165], v[164:165], v[16:17]
	v_pk_mul_f32 v[154:155], v[154:155], v[6:7]
	v_pk_mul_f32 v[156:157], v[156:157], v[8:9]
	v_add_f32_e32 v170, 1.0, v170
	v_rcp_f32_e32 v196, v170
	v_mul_f32_e32 v170, 0xbfb8aa3b, v195
	v_exp_f32_e32 v170, v170
	v_pk_mul_f32 v[146:147], v[146:147], v[30:31]
	v_pk_mul_f32 v[148:149], v[148:149], v[32:33]
	v_pk_mul_f32 v[142:143], v[142:143], v[22:23]
	v_add_f32_e32 v170, 1.0, v170
	v_rcp_f32_e32 v197, v170
	v_pk_mul_f32 v[144:145], v[144:145], v[24:25]
	v_pk_mul_f32 v[134:135], v[134:135], v[14:15]
	v_pk_mul_f32 v[136:137], v[136:137], v[16:17]
	v_pk_mul_f32 v[194:195], v[196:197], v[194:195]
	v_pk_mul_f32 v[130:131], v[130:131], v[6:7]
	v_pk_mul_f32 v[174:175], v[174:175], v[194:195]
	v_pk_mul_f32 v[132:133], v[132:133], v[8:9]
	v_cvt_pk_bf16_f32 v170, v174, v175
	v_lshlrev_b32_e32 v174, 16, v171
	v_and_b32_e32 v175, 0xffff0000, v171
	v_mul_f32_e32 v171, 0xbfb8aa3b, v174
	v_exp_f32_e32 v171, v171
	v_pk_mul_f32 v[122:123], v[122:123], v[30:31]
	v_pk_mul_f32 v[124:125], v[124:125], v[32:33]
	v_pk_mul_f32 v[118:119], v[118:119], v[22:23]
	v_add_f32_e32 v171, 1.0, v171
	v_rcp_f32_e32 v194, v171
	v_mul_f32_e32 v171, 0xbfb8aa3b, v175
	v_exp_f32_e32 v171, v171
	v_pk_mul_f32 v[120:121], v[120:121], v[24:25]
	v_pk_mul_f32 v[110:111], v[110:111], v[14:15]
	v_pk_mul_f32 v[112:113], v[112:113], v[16:17]
	v_add_f32_e32 v171, 1.0, v171
	v_rcp_f32_e32 v195, v171
	v_pk_mul_f32 v[106:107], v[106:107], v[6:7]
	v_pk_mul_f32 v[108:109], v[108:109], v[8:9]
	v_pk_mul_f32 v[98:99], v[98:99], v[30:31]
	v_pk_mul_f32 v[174:175], v[194:195], v[174:175]
	v_pk_mul_f32 v[100:101], v[100:101], v[32:33]
	v_pk_mul_f32 v[174:175], v[176:177], v[174:175]
	v_pk_mul_f32 v[94:95], v[94:95], v[22:23]
	v_cvt_pk_bf16_f32 v171, v174, v175
	v_lshlrev_b32_e32 v174, 16, v172
	v_and_b32_e32 v175, 0xffff0000, v172
	v_mul_f32_e32 v172, 0xbfb8aa3b, v174
	v_exp_f32_e32 v172, v172
	v_pk_mul_f32 v[96:97], v[96:97], v[24:25]
	v_pk_mul_f32 v[86:87], v[86:87], v[14:15]
	v_pk_mul_f32 v[88:89], v[88:89], v[16:17]
	v_add_f32_e32 v172, 1.0, v172
	v_rcp_f32_e32 v176, v172
	v_mul_f32_e32 v172, 0xbfb8aa3b, v175
	v_exp_f32_e32 v172, v172
	v_pk_mul_f32 v[82:83], v[82:83], v[6:7]
	v_pk_mul_f32 v[84:85], v[84:85], v[8:9]
	v_pk_mul_f32 v[78:79], v[78:79], v[30:31]
	v_add_f32_e32 v172, 1.0, v172
	v_rcp_f32_e32 v177, v172
	v_pk_mul_f32 v[80:81], v[80:81], v[32:33]
	v_pk_mul_f32 v[74:75], v[74:75], v[22:23]
	v_pk_mul_f32 v[76:77], v[76:77], v[24:25]
	v_pk_mul_f32 v[174:175], v[176:177], v[174:175]
	v_pk_mul_f32 v[70:71], v[70:71], v[14:15]
	v_pk_mul_f32 v[166:167], v[166:167], v[174:175]
	v_pk_mul_f32 v[72:73], v[72:73], v[16:17]
	v_cvt_pk_bf16_f32 v172, v166, v167
	v_lshlrev_b32_e32 v166, 16, v173
	v_and_b32_e32 v167, 0xffff0000, v173
	v_mul_f32_e32 v173, 0xbfb8aa3b, v166
	v_exp_f32_e32 v173, v173
	v_pk_mul_f32 v[66:67], v[66:67], v[6:7]
	v_pk_mul_f32 v[68:69], v[68:69], v[8:9]
	v_pk_mul_f32 v[62:63], v[62:63], v[30:31]
	v_add_f32_e32 v173, 1.0, v173
	v_rcp_f32_e32 v174, v173
	v_mul_f32_e32 v173, 0xbfb8aa3b, v167
	v_exp_f32_e32 v173, v173
	v_pk_mul_f32 v[64:65], v[64:65], v[32:33]
	v_pk_mul_f32 v[58:59], v[58:59], v[22:23]
	v_pk_mul_f32 v[60:61], v[60:61], v[24:25]
	v_add_f32_e32 v173, 1.0, v173
	v_rcp_f32_e32 v175, v173
	v_pk_mul_f32 v[54:55], v[54:55], v[14:15]
	v_pk_mul_f32 v[56:57], v[56:57], v[16:17]
	v_pk_mul_f32 v[50:51], v[50:51], v[6:7]
	v_pk_mul_f32 v[166:167], v[174:175], v[166:167]
	v_pk_mul_f32 v[52:53], v[52:53], v[8:9]
	v_pk_mul_f32 v[166:167], v[168:169], v[166:167]
	v_lshl_add_u64 v[168:169], s[16:17], 0, v[208:209]
	v_cvt_pk_bf16_f32 v173, v166, v167
	v_lshlrev_b64 v[166:167], 1, v[206:207]
	v_lshl_add_u64 v[168:169], v[168:169], 0, v[166:167]
	global_store_dwordx4 v[168:169], v[170:173], off sc1
	v_pk_mul_f32 v[46:47], v[46:47], v[30:31]
	v_pk_mul_f32 v[48:49], v[48:49], v[32:33]
	v_lshlrev_b32_e32 v170, 16, v158
	v_and_b32_e32 v171, 0xffff0000, v158
	v_mul_f32_e32 v158, 0xbfb8aa3b, v170
	v_exp_f32_e32 v158, v158
	v_pk_mul_f32 v[42:43], v[42:43], v[22:23]
	v_pk_mul_f32 v[44:45], v[44:45], v[24:25]
	v_pk_mul_f32 v[38:39], v[38:39], v[14:15]
	v_add_f32_e32 v158, 1.0, v158
	v_rcp_f32_e32 v172, v158
	v_mul_f32_e32 v158, 0xbfb8aa3b, v171
	v_exp_f32_e32 v158, v158
	v_pk_mul_f32 v[40:41], v[40:41], v[16:17]
	v_pk_mul_f32 v[34:35], v[34:35], v[6:7]
	v_pk_mul_f32 v[36:37], v[36:37], v[8:9]
	v_add_f32_e32 v158, 1.0, v158
	v_rcp_f32_e32 v173, v158
	v_pk_mul_f32 v[26:27], v[26:27], v[30:31]
	v_pk_mul_f32 v[28:29], v[28:29], v[32:33]
	v_pk_mul_f32 v[18:19], v[18:19], v[22:23]
	v_pk_mul_f32 v[170:171], v[172:173], v[170:171]
	v_pk_mul_f32 v[20:21], v[20:21], v[24:25]
	v_pk_mul_f32 v[162:163], v[162:163], v[170:171]
	v_pk_mul_f32 v[10:11], v[10:11], v[14:15]
	v_cvt_pk_bf16_f32 v158, v162, v163
	v_lshlrev_b32_e32 v162, 16, v159
	v_and_b32_e32 v163, 0xffff0000, v159
	v_mul_f32_e32 v159, 0xbfb8aa3b, v162
	v_exp_f32_e32 v159, v159
	v_pk_mul_f32 v[12:13], v[12:13], v[16:17]
	v_pk_mul_f32 v[2:3], v[2:3], v[6:7]
	v_pk_mul_f32 v[4:5], v[4:5], v[8:9]
	v_add_f32_e32 v159, 1.0, v159
	v_rcp_f32_e32 v170, v159
	v_mul_f32_e32 v159, 0xbfb8aa3b, v163
	v_exp_f32_e32 v159, v159
	s_nop 0
	v_add_f32_e32 v159, 1.0, v159
	v_rcp_f32_e32 v171, v159
	s_nop 0
	v_pk_mul_f32 v[162:163], v[170:171], v[162:163]
	s_nop 0
	v_pk_mul_f32 v[162:163], v[164:165], v[162:163]
	s_nop 0
	v_cvt_pk_bf16_f32 v159, v162, v163
	v_lshlrev_b32_e32 v162, 16, v160
	v_and_b32_e32 v163, 0xffff0000, v160
	v_mul_f32_e32 v160, 0xbfb8aa3b, v162
	v_exp_f32_e32 v160, v160
	s_nop 0
	v_add_f32_e32 v160, 1.0, v160
	v_rcp_f32_e32 v164, v160
	v_mul_f32_e32 v160, 0xbfb8aa3b, v163
	v_exp_f32_e32 v160, v160
	s_nop 0
	v_add_f32_e32 v160, 1.0, v160
	v_rcp_f32_e32 v165, v160
	s_nop 0
	v_pk_mul_f32 v[162:163], v[164:165], v[162:163]
	s_nop 0
	v_pk_mul_f32 v[154:155], v[154:155], v[162:163]
	s_nop 0
	v_cvt_pk_bf16_f32 v160, v154, v155
	v_lshlrev_b32_e32 v154, 16, v161
	v_and_b32_e32 v155, 0xffff0000, v161
	v_mul_f32_e32 v161, 0xbfb8aa3b, v154
	v_exp_f32_e32 v161, v161
	s_nop 0
	v_add_f32_e32 v161, 1.0, v161
	v_rcp_f32_e32 v162, v161
	v_mul_f32_e32 v161, 0xbfb8aa3b, v155
	v_exp_f32_e32 v161, v161
	s_nop 0
	v_add_f32_e32 v161, 1.0, v161
	v_rcp_f32_e32 v163, v161
	s_nop 0
	v_pk_mul_f32 v[154:155], v[162:163], v[154:155]
	s_nop 0
	v_pk_mul_f32 v[154:155], v[156:157], v[154:155]
	v_lshlrev_b32_e32 v156, 16, v150
	v_and_b32_e32 v157, 0xffff0000, v150
	v_mul_f32_e32 v150, 0xbfb8aa3b, v156
	v_exp_f32_e32 v150, v150
	v_cvt_pk_bf16_f32 v161, v154, v155
	global_store_dwordx4 v[168:169], v[158:161], off offset:256 sc1
	v_lshlrev_b64 v[154:155], 11, v[204:205]
	v_add_f32_e32 v150, 1.0, v150
	v_rcp_f32_e32 v158, v150
	v_mul_f32_e32 v150, 0xbfb8aa3b, v157
	v_exp_f32_e32 v150, v150
	s_nop 0
	v_add_f32_e32 v150, 1.0, v150
	v_rcp_f32_e32 v159, v150
	v_lshlrev_b32_e32 v150, 16, v151
	v_and_b32_e32 v151, 0xffff0000, v151
	v_pk_mul_f32 v[156:157], v[158:159], v[156:157]
	s_nop 0
	v_pk_mul_f32 v[146:147], v[146:147], v[156:157]
	s_nop 0
	v_cvt_pk_bf16_f32 v146, v146, v147
	v_mul_f32_e32 v147, 0xbfb8aa3b, v150
	v_exp_f32_e32 v147, v147
	s_nop 0
	v_add_f32_e32 v147, 1.0, v147
	v_rcp_f32_e32 v156, v147
	v_mul_f32_e32 v147, 0xbfb8aa3b, v151
	v_exp_f32_e32 v147, v147
	s_nop 0
	v_add_f32_e32 v147, 1.0, v147
	v_rcp_f32_e32 v157, v147
	s_nop 0
	v_pk_mul_f32 v[150:151], v[156:157], v[150:151]
	s_nop 0
	v_pk_mul_f32 v[148:149], v[148:149], v[150:151]
	s_nop 0
	v_cvt_pk_bf16_f32 v147, v148, v149
	v_lshlrev_b32_e32 v148, 16, v152
	v_and_b32_e32 v149, 0xffff0000, v152
	v_mul_f32_e32 v150, 0xbfb8aa3b, v148
	v_mul_f32_e32 v151, 0xbfb8aa3b, v149
	v_exp_f32_e32 v150, v150
	v_exp_f32_e32 v151, v151
	v_add_f32_e32 v150, 1.0, v150
	v_add_f32_e32 v151, 1.0, v151
	v_rcp_f32_e32 v150, v150
	v_rcp_f32_e32 v151, v151
	s_nop 0
	v_pk_mul_f32 v[148:149], v[150:151], v[148:149]
	s_nop 0
	v_pk_mul_f32 v[142:143], v[142:143], v[148:149]
	s_nop 0
	v_cvt_pk_bf16_f32 v148, v142, v143
	v_lshlrev_b32_e32 v142, 16, v153
	v_mul_f32_e32 v149, 0xbfb8aa3b, v142
	v_exp_f32_e32 v149, v149
	v_and_b32_e32 v143, 0xffff0000, v153
	v_add_f32_e32 v149, 1.0, v149
	v_rcp_f32_e32 v150, v149
	v_mul_f32_e32 v149, 0xbfb8aa3b, v143
	v_exp_f32_e32 v149, v149
	s_nop 0
	v_add_f32_e32 v149, 1.0, v149
	v_rcp_f32_e32 v151, v149
	s_nop 0
	v_pk_mul_f32 v[142:143], v[150:151], v[142:143]
	s_nop 0
	v_pk_mul_f32 v[142:143], v[144:145], v[142:143]
	v_lshlrev_b32_e32 v144, 16, v138
	v_and_b32_e32 v145, 0xffff0000, v138
	v_mul_f32_e32 v138, 0xbfb8aa3b, v144
	v_exp_f32_e32 v138, v138
	v_cvt_pk_bf16_f32 v149, v142, v143
	v_lshl_add_u64 v[142:143], s[16:17], 0, v[154:155]
	v_lshl_add_u64 v[142:143], v[142:143], 0, v[166:167]
	v_add_f32_e32 v138, 1.0, v138
	global_store_dwordx4 v[142:143], v[146:149], off sc1
	s_nop 1
	v_rcp_f32_e32 v146, v138
	v_mul_f32_e32 v138, 0xbfb8aa3b, v145
	v_exp_f32_e32 v138, v138
	s_nop 0
	v_add_f32_e32 v138, 1.0, v138
	v_rcp_f32_e32 v147, v138
	v_lshlrev_b32_e32 v138, 16, v139
	v_and_b32_e32 v139, 0xffff0000, v139
	v_pk_mul_f32 v[144:145], v[146:147], v[144:145]
	s_nop 0
	v_pk_mul_f32 v[134:135], v[134:135], v[144:145]
	s_nop 0
	v_cvt_pk_bf16_f32 v134, v134, v135
	v_mul_f32_e32 v135, 0xbfb8aa3b, v138
	v_exp_f32_e32 v135, v135
	s_nop 0
	v_add_f32_e32 v135, 1.0, v135
	v_rcp_f32_e32 v144, v135
	v_mul_f32_e32 v135, 0xbfb8aa3b, v139
	v_exp_f32_e32 v135, v135
	s_nop 0
	v_add_f32_e32 v135, 1.0, v135
	v_rcp_f32_e32 v145, v135
	s_nop 0
	v_pk_mul_f32 v[138:139], v[144:145], v[138:139]
	s_nop 0
	v_pk_mul_f32 v[136:137], v[136:137], v[138:139]
	s_nop 0
	v_cvt_pk_bf16_f32 v135, v136, v137
	v_lshlrev_b32_e32 v136, 16, v140
	v_and_b32_e32 v137, 0xffff0000, v140
	v_mul_f32_e32 v138, 0xbfb8aa3b, v136
	v_mul_f32_e32 v139, 0xbfb8aa3b, v137
	v_exp_f32_e32 v138, v138
	v_exp_f32_e32 v139, v139
	v_add_f32_e32 v138, 1.0, v138
	v_add_f32_e32 v139, 1.0, v139
	v_rcp_f32_e32 v138, v138
	v_rcp_f32_e32 v139, v139
	s_nop 0
	v_pk_mul_f32 v[136:137], v[138:139], v[136:137]
	s_nop 0
	v_pk_mul_f32 v[130:131], v[130:131], v[136:137]
	s_nop 0
	v_cvt_pk_bf16_f32 v136, v130, v131
	v_lshlrev_b32_e32 v130, 16, v141
	v_mul_f32_e32 v137, 0xbfb8aa3b, v130
	v_exp_f32_e32 v137, v137
	v_and_b32_e32 v131, 0xffff0000, v141
	v_add_f32_e32 v137, 1.0, v137
	v_rcp_f32_e32 v138, v137
	v_mul_f32_e32 v137, 0xbfb8aa3b, v131
	v_exp_f32_e32 v137, v137
	s_nop 0
	v_add_f32_e32 v137, 1.0, v137
	v_rcp_f32_e32 v139, v137
	s_nop 0
	v_pk_mul_f32 v[130:131], v[138:139], v[130:131]
	s_nop 0
	v_pk_mul_f32 v[130:131], v[132:133], v[130:131]
	v_lshlrev_b32_e32 v132, 16, v126
	v_and_b32_e32 v133, 0xffff0000, v126
	v_mul_f32_e32 v126, 0xbfb8aa3b, v132
	v_exp_f32_e32 v126, v126
	v_cvt_pk_bf16_f32 v137, v130, v131
	global_store_dwordx4 v[142:143], v[134:137], off offset:256 sc1
	v_lshlrev_b64 v[130:131], 11, v[192:193]
	v_add_f32_e32 v126, 1.0, v126
	v_rcp_f32_e32 v134, v126
	v_mul_f32_e32 v126, 0xbfb8aa3b, v133
	v_exp_f32_e32 v126, v126
	s_nop 0
	v_add_f32_e32 v126, 1.0, v126
	v_rcp_f32_e32 v135, v126
	v_lshlrev_b32_e32 v126, 16, v127
	v_and_b32_e32 v127, 0xffff0000, v127
	v_pk_mul_f32 v[132:133], v[134:135], v[132:133]
	s_nop 0
	v_pk_mul_f32 v[122:123], v[122:123], v[132:133]
	s_nop 0
	v_cvt_pk_bf16_f32 v122, v122, v123
	v_mul_f32_e32 v123, 0xbfb8aa3b, v126
	v_exp_f32_e32 v123, v123
	s_nop 0
	v_add_f32_e32 v123, 1.0, v123
	v_rcp_f32_e32 v132, v123
	v_mul_f32_e32 v123, 0xbfb8aa3b, v127
	v_exp_f32_e32 v123, v123
	s_nop 0
	v_add_f32_e32 v123, 1.0, v123
	v_rcp_f32_e32 v133, v123
	s_nop 0
	v_pk_mul_f32 v[126:127], v[132:133], v[126:127]
	s_nop 0
	v_pk_mul_f32 v[124:125], v[124:125], v[126:127]
	s_nop 0
	v_cvt_pk_bf16_f32 v123, v124, v125
	v_lshlrev_b32_e32 v124, 16, v128
	v_and_b32_e32 v125, 0xffff0000, v128
	v_mul_f32_e32 v126, 0xbfb8aa3b, v124
	v_mul_f32_e32 v127, 0xbfb8aa3b, v125
	v_exp_f32_e32 v126, v126
	v_exp_f32_e32 v127, v127
	v_add_f32_e32 v126, 1.0, v126
	v_add_f32_e32 v127, 1.0, v127
	v_rcp_f32_e32 v126, v126
	v_rcp_f32_e32 v127, v127
	s_nop 0
	v_pk_mul_f32 v[124:125], v[126:127], v[124:125]
	s_nop 0
	v_pk_mul_f32 v[118:119], v[118:119], v[124:125]
	s_nop 0
	v_cvt_pk_bf16_f32 v124, v118, v119
	v_lshlrev_b32_e32 v118, 16, v129
	v_mul_f32_e32 v125, 0xbfb8aa3b, v118
	v_exp_f32_e32 v125, v125
	v_and_b32_e32 v119, 0xffff0000, v129
	v_add_f32_e32 v125, 1.0, v125
	v_rcp_f32_e32 v126, v125
	v_mul_f32_e32 v125, 0xbfb8aa3b, v119
	v_exp_f32_e32 v125, v125
	s_nop 0
	v_add_f32_e32 v125, 1.0, v125
	v_rcp_f32_e32 v127, v125
	s_nop 0
	v_pk_mul_f32 v[118:119], v[126:127], v[118:119]
	s_nop 0
	v_pk_mul_f32 v[118:119], v[120:121], v[118:119]
	v_lshlrev_b32_e32 v120, 16, v114
	v_and_b32_e32 v121, 0xffff0000, v114
	v_mul_f32_e32 v114, 0xbfb8aa3b, v120
	v_exp_f32_e32 v114, v114
	v_cvt_pk_bf16_f32 v125, v118, v119
	v_lshl_add_u64 v[118:119], s[16:17], 0, v[130:131]
	v_lshl_add_u64 v[118:119], v[118:119], 0, v[166:167]
	v_add_f32_e32 v114, 1.0, v114
	global_store_dwordx4 v[118:119], v[122:125], off sc1
	s_nop 1
	v_rcp_f32_e32 v122, v114
	v_mul_f32_e32 v114, 0xbfb8aa3b, v121
	v_exp_f32_e32 v114, v114
	s_nop 0
	v_add_f32_e32 v114, 1.0, v114
	v_rcp_f32_e32 v123, v114
	v_lshlrev_b32_e32 v114, 16, v115
	v_and_b32_e32 v115, 0xffff0000, v115
	v_pk_mul_f32 v[120:121], v[122:123], v[120:121]
	s_nop 0
	v_pk_mul_f32 v[110:111], v[110:111], v[120:121]
	s_nop 0
	v_cvt_pk_bf16_f32 v110, v110, v111
	v_mul_f32_e32 v111, 0xbfb8aa3b, v114
	v_exp_f32_e32 v111, v111
	s_nop 0
	v_add_f32_e32 v111, 1.0, v111
	v_rcp_f32_e32 v120, v111
	v_mul_f32_e32 v111, 0xbfb8aa3b, v115
	v_exp_f32_e32 v111, v111
	s_nop 0
	v_add_f32_e32 v111, 1.0, v111
	v_rcp_f32_e32 v121, v111
	s_nop 0
	v_pk_mul_f32 v[114:115], v[120:121], v[114:115]
	s_nop 0
	v_pk_mul_f32 v[112:113], v[112:113], v[114:115]
	v_add_u32_e32 v120, 0x80, v184
	v_cvt_pk_bf16_f32 v111, v112, v113
	v_lshlrev_b32_e32 v112, 16, v116
	v_and_b32_e32 v113, 0xffff0000, v116
	v_mul_f32_e32 v114, 0xbfb8aa3b, v112
	v_mul_f32_e32 v115, 0xbfb8aa3b, v113
	v_exp_f32_e32 v114, v114
	v_exp_f32_e32 v115, v115
	v_add_u32_e32 v116, 0xa0, v184
	v_ashrrev_i32_e32 v121, 31, v120
	v_add_f32_e32 v114, 1.0, v114
	v_add_f32_e32 v115, 1.0, v115
	v_rcp_f32_e32 v114, v114
	v_rcp_f32_e32 v115, v115
	s_nop 0
	v_pk_mul_f32 v[112:113], v[114:115], v[112:113]
	s_nop 0
	v_pk_mul_f32 v[106:107], v[106:107], v[112:113]
	s_nop 0
	v_cvt_pk_bf16_f32 v112, v106, v107
	v_lshlrev_b32_e32 v106, 16, v117
	v_mul_f32_e32 v113, 0xbfb8aa3b, v106
	v_exp_f32_e32 v113, v113
	v_and_b32_e32 v107, 0xffff0000, v117
	v_ashrrev_i32_e32 v117, 31, v116
	v_add_f32_e32 v113, 1.0, v113
	v_rcp_f32_e32 v114, v113
	v_mul_f32_e32 v113, 0xbfb8aa3b, v107
	v_exp_f32_e32 v113, v113
	s_nop 0
	v_add_f32_e32 v113, 1.0, v113
	v_rcp_f32_e32 v115, v113
	s_nop 0
	v_pk_mul_f32 v[106:107], v[114:115], v[106:107]
	s_nop 0
	v_pk_mul_f32 v[106:107], v[108:109], v[106:107]
	v_lshlrev_b32_e32 v108, 16, v102
	v_and_b32_e32 v109, 0xffff0000, v102
	v_mul_f32_e32 v102, 0xbfb8aa3b, v108
	v_exp_f32_e32 v102, v102
	v_cvt_pk_bf16_f32 v113, v106, v107
	global_store_dwordx4 v[118:119], v[110:113], off offset:256 sc1
	v_lshlrev_b64 v[106:107], 11, v[190:191]
	v_add_f32_e32 v102, 1.0, v102
	v_rcp_f32_e32 v110, v102
	v_mul_f32_e32 v102, 0xbfb8aa3b, v109
	v_exp_f32_e32 v102, v102
	v_add_u32_e32 v118, 0x90, v184
	v_add_u32_e32 v114, 0xb0, v184
	v_ashrrev_i32_e32 v119, 31, v118
	v_add_f32_e32 v102, 1.0, v102
	v_rcp_f32_e32 v111, v102
	v_lshlrev_b32_e32 v102, 16, v103
	v_and_b32_e32 v103, 0xffff0000, v103
	v_ashrrev_i32_e32 v115, 31, v114
	v_pk_mul_f32 v[108:109], v[110:111], v[108:109]
	s_nop 0
	v_pk_mul_f32 v[98:99], v[98:99], v[108:109]
	s_nop 0
	v_cvt_pk_bf16_f32 v98, v98, v99
	v_mul_f32_e32 v99, 0xbfb8aa3b, v102
	v_exp_f32_e32 v99, v99
	s_nop 0
	v_add_f32_e32 v99, 1.0, v99
	v_rcp_f32_e32 v108, v99
	v_mul_f32_e32 v99, 0xbfb8aa3b, v103
	v_exp_f32_e32 v99, v99
	s_nop 0
	v_add_f32_e32 v99, 1.0, v99
	v_rcp_f32_e32 v109, v99
	s_nop 0
	v_pk_mul_f32 v[102:103], v[108:109], v[102:103]
	s_nop 0
	v_pk_mul_f32 v[100:101], v[100:101], v[102:103]
	s_nop 0
	v_cvt_pk_bf16_f32 v99, v100, v101
	v_lshlrev_b32_e32 v100, 16, v104
	v_and_b32_e32 v101, 0xffff0000, v104
	v_mul_f32_e32 v102, 0xbfb8aa3b, v100
	v_mul_f32_e32 v103, 0xbfb8aa3b, v101
	v_exp_f32_e32 v102, v102
	v_exp_f32_e32 v103, v103
	v_add_f32_e32 v102, 1.0, v102
	v_add_f32_e32 v103, 1.0, v103
	v_rcp_f32_e32 v102, v102
	v_rcp_f32_e32 v103, v103
	s_nop 0
	v_pk_mul_f32 v[100:101], v[102:103], v[100:101]
	s_nop 0
	v_pk_mul_f32 v[94:95], v[94:95], v[100:101]
	s_nop 0
	v_cvt_pk_bf16_f32 v100, v94, v95
	v_lshlrev_b32_e32 v94, 16, v105
	v_mul_f32_e32 v101, 0xbfb8aa3b, v94
	v_exp_f32_e32 v101, v101
	v_and_b32_e32 v95, 0xffff0000, v105
	v_add_f32_e32 v101, 1.0, v101
	v_rcp_f32_e32 v102, v101
	v_mul_f32_e32 v101, 0xbfb8aa3b, v95
	v_exp_f32_e32 v101, v101
	s_nop 0
	v_add_f32_e32 v101, 1.0, v101
	v_rcp_f32_e32 v103, v101
	s_nop 0
	v_pk_mul_f32 v[94:95], v[102:103], v[94:95]
	s_nop 0
	v_pk_mul_f32 v[94:95], v[96:97], v[94:95]
	v_lshlrev_b32_e32 v96, 16, v90
	v_and_b32_e32 v97, 0xffff0000, v90
	v_mul_f32_e32 v90, 0xbfb8aa3b, v96
	v_exp_f32_e32 v90, v90
	v_cvt_pk_bf16_f32 v101, v94, v95
	v_lshl_add_u64 v[94:95], s[16:17], 0, v[106:107]
	v_lshl_add_u64 v[94:95], v[94:95], 0, v[166:167]
	v_add_f32_e32 v90, 1.0, v90
	global_store_dwordx4 v[94:95], v[98:101], off sc1
	s_nop 1
	v_rcp_f32_e32 v98, v90
	v_mul_f32_e32 v90, 0xbfb8aa3b, v97
	v_exp_f32_e32 v90, v90
	s_nop 0
	v_add_f32_e32 v90, 1.0, v90
	v_rcp_f32_e32 v99, v90
	v_lshlrev_b32_e32 v90, 16, v91
	v_and_b32_e32 v91, 0xffff0000, v91
	v_pk_mul_f32 v[96:97], v[98:99], v[96:97]
	s_nop 0
	v_pk_mul_f32 v[86:87], v[86:87], v[96:97]
	s_nop 0
	v_cvt_pk_bf16_f32 v86, v86, v87
	v_mul_f32_e32 v87, 0xbfb8aa3b, v90
	v_exp_f32_e32 v87, v87
	s_nop 0
	v_add_f32_e32 v87, 1.0, v87
	v_rcp_f32_e32 v96, v87
	v_mul_f32_e32 v87, 0xbfb8aa3b, v91
	v_exp_f32_e32 v87, v87
	s_nop 0
	v_add_f32_e32 v87, 1.0, v87
	v_rcp_f32_e32 v97, v87
	s_nop 0
	v_pk_mul_f32 v[90:91], v[96:97], v[90:91]
	s_nop 0
	v_pk_mul_f32 v[88:89], v[88:89], v[90:91]
	s_nop 0
	v_cvt_pk_bf16_f32 v87, v88, v89
	v_lshlrev_b32_e32 v88, 16, v92
	v_and_b32_e32 v89, 0xffff0000, v92
	v_mul_f32_e32 v90, 0xbfb8aa3b, v88
	v_mul_f32_e32 v91, 0xbfb8aa3b, v89
	v_exp_f32_e32 v90, v90
	v_exp_f32_e32 v91, v91
	v_add_f32_e32 v90, 1.0, v90
	v_add_f32_e32 v91, 1.0, v91
	v_rcp_f32_e32 v90, v90
	v_rcp_f32_e32 v91, v91
	s_nop 0
	v_pk_mul_f32 v[88:89], v[90:91], v[88:89]
	s_nop 0
	v_pk_mul_f32 v[82:83], v[82:83], v[88:89]
	s_nop 0
	v_cvt_pk_bf16_f32 v88, v82, v83
	v_lshlrev_b32_e32 v82, 16, v93
	v_mul_f32_e32 v89, 0xbfb8aa3b, v82
	v_exp_f32_e32 v89, v89
	v_and_b32_e32 v83, 0xffff0000, v93
	v_add_f32_e32 v89, 1.0, v89
	v_rcp_f32_e32 v90, v89
	v_mul_f32_e32 v89, 0xbfb8aa3b, v83
	v_exp_f32_e32 v89, v89
	s_nop 0
	v_add_f32_e32 v89, 1.0, v89
	v_rcp_f32_e32 v91, v89
	s_nop 0
	v_pk_mul_f32 v[82:83], v[90:91], v[82:83]
	s_nop 0
	v_pk_mul_f32 v[82:83], v[84:85], v[82:83]
	s_nop 0
	v_cvt_pk_bf16_f32 v89, v82, v83
	v_mad_i64_i32 v[82:83], s[0:1], v120, s87, v[186:187]
	v_lshl_add_u64 v[82:83], v[82:83], 0, s[22:23]
	v_lshl_add_u64 v[82:83], v[82:83], 0, v[188:189]
	global_store_dwordx4 v[94:95], v[86:89], off offset:256 sc1
	v_lshl_add_u64 v[84:85], v[82:83], 0, s[4:5]
	v_add_co_u32_e32 v82, vcc, s84, v82
	v_lshlrev_b64 v[120:121], 11, v[120:121]
	s_nop 0
	v_addc_co_u32_e32 v83, vcc, 0, v83, vcc
	global_load_dwordx4 v[110:113], v[82:83], off
	global_load_dwordx4 v[106:109], v[84:85], off offset:256
	v_mad_i64_i32 v[82:83], s[0:1], v118, s87, v[186:187]
	v_lshl_add_u64 v[82:83], v[82:83], 0, s[22:23]
	v_lshl_add_u64 v[82:83], v[82:83], 0, v[188:189]
	v_lshl_add_u64 v[84:85], v[82:83], 0, s[4:5]
	v_add_co_u32_e32 v82, vcc, s84, v82
	s_waitcnt vmcnt(1)
	v_lshlrev_b32_e32 v122, 16, v110
	v_and_b32_e32 v123, 0xffff0000, v110
	v_mul_f32_e32 v110, 0xbfb8aa3b, v122
	v_exp_f32_e32 v110, v110
	v_addc_co_u32_e32 v83, vcc, 0, v83, vcc
	global_load_dwordx4 v[102:105], v[82:83], off
	global_load_dwordx4 v[98:101], v[84:85], off offset:256
	v_add_f32_e32 v110, 1.0, v110
	v_rcp_f32_e32 v124, v110
	v_mul_f32_e32 v110, 0xbfb8aa3b, v123
	v_exp_f32_e32 v110, v110
	v_mad_i64_i32 v[82:83], s[0:1], v116, s87, v[186:187]
	v_lshl_add_u64 v[82:83], v[82:83], 0, s[22:23]
	v_add_f32_e32 v110, 1.0, v110
	v_rcp_f32_e32 v125, v110
	v_lshlrev_b32_e32 v110, 16, v111
	v_and_b32_e32 v111, 0xffff0000, v111
	v_lshl_add_u64 v[82:83], v[82:83], 0, v[188:189]
	v_pk_mul_f32 v[122:123], v[124:125], v[122:123]
	v_lshl_add_u64 v[84:85], v[82:83], 0, s[4:5]
	v_pk_mul_f32 v[78:79], v[78:79], v[122:123]
	v_add_co_u32_e32 v82, vcc, s84, v82
	v_cvt_pk_bf16_f32 v78, v78, v79
	v_mul_f32_e32 v79, 0xbfb8aa3b, v110
	v_exp_f32_e32 v79, v79
	v_addc_co_u32_e32 v83, vcc, 0, v83, vcc
	global_load_dwordx4 v[94:97], v[82:83], off
	global_load_dwordx4 v[90:93], v[84:85], off offset:256
	v_add_f32_e32 v79, 1.0, v79
	v_rcp_f32_e32 v122, v79
	v_mul_f32_e32 v79, 0xbfb8aa3b, v111
	v_exp_f32_e32 v79, v79
	v_mad_i64_i32 v[82:83], s[0:1], v114, s87, v[186:187]
	v_lshl_add_u64 v[82:83], v[82:83], 0, s[22:23]
	v_add_f32_e32 v79, 1.0, v79
	v_rcp_f32_e32 v123, v79
	v_lshl_add_u64 v[82:83], v[82:83], 0, v[188:189]
	v_lshl_add_u64 v[84:85], v[82:83], 0, s[4:5]
	v_add_co_u32_e32 v82, vcc, s84, v82
	v_pk_mul_f32 v[110:111], v[122:123], v[110:111]
	s_nop 0
	v_addc_co_u32_e32 v83, vcc, 0, v83, vcc
	v_pk_mul_f32 v[80:81], v[80:81], v[110:111]
	global_load_dwordx4 v[86:89], v[82:83], off
	s_nop 0
	global_load_dwordx4 v[82:85], v[84:85], off offset:256
	v_cvt_pk_bf16_f32 v79, v80, v81
	v_lshlrev_b32_e32 v80, 16, v112
	v_and_b32_e32 v81, 0xffff0000, v112
	v_mul_f32_e32 v110, 0xbfb8aa3b, v80
	v_mul_f32_e32 v111, 0xbfb8aa3b, v81
	v_exp_f32_e32 v110, v110
	v_exp_f32_e32 v111, v111
	s_mov_b64 s[22:23], -1
	s_andn2_b64 vcc, exec, s[6:7]
	v_add_f32_e32 v110, 1.0, v110
	v_add_f32_e32 v111, 1.0, v111
	v_rcp_f32_e32 v110, v110
	v_rcp_f32_e32 v111, v111
	s_nop 0
	v_pk_mul_f32 v[80:81], v[110:111], v[80:81]
	s_nop 0
	v_pk_mul_f32 v[74:75], v[74:75], v[80:81]
	s_nop 0
	v_cvt_pk_bf16_f32 v80, v74, v75
	v_lshlrev_b32_e32 v74, 16, v113
	v_mul_f32_e32 v81, 0xbfb8aa3b, v74
	v_exp_f32_e32 v81, v81
	v_and_b32_e32 v75, 0xffff0000, v113
	v_add_f32_e32 v81, 1.0, v81
	v_rcp_f32_e32 v110, v81
	v_mul_f32_e32 v81, 0xbfb8aa3b, v75
	v_exp_f32_e32 v81, v81
	s_nop 0
	v_add_f32_e32 v81, 1.0, v81
	v_rcp_f32_e32 v111, v81
	s_nop 0
	v_pk_mul_f32 v[74:75], v[110:111], v[74:75]
	s_nop 0
	v_pk_mul_f32 v[74:75], v[76:77], v[74:75]
	s_waitcnt vmcnt(6)
	v_lshlrev_b32_e32 v76, 16, v106
	v_cvt_pk_bf16_f32 v81, v74, v75
	v_lshl_add_u64 v[74:75], s[16:17], 0, v[120:121]
	v_lshl_add_u64 v[74:75], v[74:75], 0, v[166:167]
	v_and_b32_e32 v77, 0xffff0000, v106
	global_store_dwordx4 v[74:75], v[78:81], off sc1
	s_nop 1
	v_mul_f32_e32 v78, 0xbfb8aa3b, v76
	v_mul_f32_e32 v79, 0xbfb8aa3b, v77
	v_exp_f32_e32 v78, v78
	v_exp_f32_e32 v79, v79
	v_add_f32_e32 v78, 1.0, v78
	v_add_f32_e32 v79, 1.0, v79
	v_rcp_f32_e32 v78, v78
	v_rcp_f32_e32 v79, v79
	s_nop 0
	v_pk_mul_f32 v[76:77], v[78:79], v[76:77]
	s_nop 0
	v_pk_mul_f32 v[70:71], v[70:71], v[76:77]
	v_lshlrev_b32_e32 v76, 16, v107
	v_cvt_pk_bf16_f32 v70, v70, v71
	v_mul_f32_e32 v71, 0xbfb8aa3b, v76
	v_exp_f32_e32 v71, v71
	v_and_b32_e32 v77, 0xffff0000, v107
	v_add_f32_e32 v71, 1.0, v71
	v_rcp_f32_e32 v78, v71
	v_mul_f32_e32 v71, 0xbfb8aa3b, v77
	v_exp_f32_e32 v71, v71
	s_nop 0
	v_add_f32_e32 v71, 1.0, v71
	v_rcp_f32_e32 v79, v71
	s_nop 0
	v_pk_mul_f32 v[76:77], v[78:79], v[76:77]
	s_nop 0
	v_pk_mul_f32 v[72:73], v[72:73], v[76:77]
	s_nop 0
	v_cvt_pk_bf16_f32 v71, v72, v73
	v_lshlrev_b32_e32 v72, 16, v108
	v_and_b32_e32 v73, 0xffff0000, v108
	v_mul_f32_e32 v76, 0xbfb8aa3b, v72
	v_mul_f32_e32 v77, 0xbfb8aa3b, v73
	v_exp_f32_e32 v76, v76
	v_exp_f32_e32 v77, v77
	v_add_f32_e32 v76, 1.0, v76
	v_add_f32_e32 v77, 1.0, v77
	v_rcp_f32_e32 v76, v76
	v_rcp_f32_e32 v77, v77
	s_nop 0
	v_pk_mul_f32 v[72:73], v[76:77], v[72:73]
	s_nop 0
	v_pk_mul_f32 v[66:67], v[66:67], v[72:73]
	s_nop 0
	v_cvt_pk_bf16_f32 v72, v66, v67
	v_lshlrev_b32_e32 v66, 16, v109
	v_mul_f32_e32 v73, 0xbfb8aa3b, v66
	v_exp_f32_e32 v73, v73
	v_and_b32_e32 v67, 0xffff0000, v109
	v_add_f32_e32 v73, 1.0, v73
	v_rcp_f32_e32 v76, v73
	v_mul_f32_e32 v73, 0xbfb8aa3b, v67
	v_exp_f32_e32 v73, v73
	s_nop 0
	v_add_f32_e32 v73, 1.0, v73
	v_rcp_f32_e32 v77, v73
	s_nop 0
	v_pk_mul_f32 v[66:67], v[76:77], v[66:67]
	s_nop 0
	v_pk_mul_f32 v[66:67], v[68:69], v[66:67]
	s_waitcnt vmcnt(6)
	v_lshlrev_b32_e32 v68, 16, v102
	v_cvt_pk_bf16_f32 v73, v66, v67
	v_and_b32_e32 v69, 0xffff0000, v102
	global_store_dwordx4 v[74:75], v[70:73], off offset:256 sc1
	v_lshlrev_b64 v[66:67], 11, v[118:119]
	s_nop 0
	v_mul_f32_e32 v70, 0xbfb8aa3b, v68
	v_mul_f32_e32 v71, 0xbfb8aa3b, v69
	v_exp_f32_e32 v70, v70
	v_exp_f32_e32 v71, v71
	v_add_f32_e32 v70, 1.0, v70
	v_add_f32_e32 v71, 1.0, v71
	v_rcp_f32_e32 v70, v70
	v_rcp_f32_e32 v71, v71
	s_nop 0
	v_pk_mul_f32 v[68:69], v[70:71], v[68:69]
	s_nop 0
	v_pk_mul_f32 v[62:63], v[62:63], v[68:69]
	v_lshlrev_b32_e32 v68, 16, v103
	v_cvt_pk_bf16_f32 v62, v62, v63
	v_mul_f32_e32 v63, 0xbfb8aa3b, v68
	v_exp_f32_e32 v63, v63
	v_and_b32_e32 v69, 0xffff0000, v103
	v_add_f32_e32 v63, 1.0, v63
	v_rcp_f32_e32 v70, v63
	v_mul_f32_e32 v63, 0xbfb8aa3b, v69
	v_exp_f32_e32 v63, v63
	s_nop 0
	v_add_f32_e32 v63, 1.0, v63
	v_rcp_f32_e32 v71, v63
	s_nop 0
	v_pk_mul_f32 v[68:69], v[70:71], v[68:69]
	s_nop 0
	v_pk_mul_f32 v[64:65], v[64:65], v[68:69]
	s_nop 0
	v_cvt_pk_bf16_f32 v63, v64, v65
	v_lshlrev_b32_e32 v64, 16, v104
	v_and_b32_e32 v65, 0xffff0000, v104
	v_mul_f32_e32 v68, 0xbfb8aa3b, v64
	v_mul_f32_e32 v69, 0xbfb8aa3b, v65
	v_exp_f32_e32 v68, v68
	v_exp_f32_e32 v69, v69
	v_add_f32_e32 v68, 1.0, v68
	v_add_f32_e32 v69, 1.0, v69
	v_rcp_f32_e32 v68, v68
	v_rcp_f32_e32 v69, v69
	s_nop 0
	v_pk_mul_f32 v[64:65], v[68:69], v[64:65]
	s_nop 0
	v_pk_mul_f32 v[58:59], v[58:59], v[64:65]
	s_nop 0
	v_cvt_pk_bf16_f32 v64, v58, v59
	v_lshlrev_b32_e32 v58, 16, v105
	v_mul_f32_e32 v65, 0xbfb8aa3b, v58
	v_exp_f32_e32 v65, v65
	v_and_b32_e32 v59, 0xffff0000, v105
	v_add_f32_e32 v65, 1.0, v65
	v_rcp_f32_e32 v68, v65
	v_mul_f32_e32 v65, 0xbfb8aa3b, v59
	v_exp_f32_e32 v65, v65
	s_nop 0
	v_add_f32_e32 v65, 1.0, v65
	v_rcp_f32_e32 v69, v65
	s_nop 0
	v_pk_mul_f32 v[58:59], v[68:69], v[58:59]
	s_nop 0
	v_pk_mul_f32 v[58:59], v[60:61], v[58:59]
	s_waitcnt vmcnt(6)
	v_lshlrev_b32_e32 v60, 16, v98
	v_cvt_pk_bf16_f32 v65, v58, v59
	v_lshl_add_u64 v[58:59], s[16:17], 0, v[66:67]
	v_lshl_add_u64 v[58:59], v[58:59], 0, v[166:167]
	v_and_b32_e32 v61, 0xffff0000, v98
	global_store_dwordx4 v[58:59], v[62:65], off sc1
	s_nop 1
	v_mul_f32_e32 v62, 0xbfb8aa3b, v60
	v_mul_f32_e32 v63, 0xbfb8aa3b, v61
	v_exp_f32_e32 v62, v62
	v_exp_f32_e32 v63, v63
	v_add_f32_e32 v62, 1.0, v62
	v_add_f32_e32 v63, 1.0, v63
	v_rcp_f32_e32 v62, v62
	v_rcp_f32_e32 v63, v63
	s_nop 0
	v_pk_mul_f32 v[60:61], v[62:63], v[60:61]
	s_nop 0
	v_pk_mul_f32 v[54:55], v[54:55], v[60:61]
	v_lshlrev_b32_e32 v60, 16, v99
	v_cvt_pk_bf16_f32 v54, v54, v55
	v_mul_f32_e32 v55, 0xbfb8aa3b, v60
	v_exp_f32_e32 v55, v55
	v_and_b32_e32 v61, 0xffff0000, v99
	v_add_f32_e32 v55, 1.0, v55
	v_rcp_f32_e32 v62, v55
	v_mul_f32_e32 v55, 0xbfb8aa3b, v61
	v_exp_f32_e32 v55, v55
	s_nop 0
	v_add_f32_e32 v55, 1.0, v55
	v_rcp_f32_e32 v63, v55
	s_nop 0
	v_pk_mul_f32 v[60:61], v[62:63], v[60:61]
	s_nop 0
	v_pk_mul_f32 v[56:57], v[56:57], v[60:61]
	s_nop 0
	v_cvt_pk_bf16_f32 v55, v56, v57
	v_lshlrev_b32_e32 v56, 16, v100
	v_and_b32_e32 v57, 0xffff0000, v100
	v_mul_f32_e32 v60, 0xbfb8aa3b, v56
	v_mul_f32_e32 v61, 0xbfb8aa3b, v57
	v_exp_f32_e32 v60, v60
	v_exp_f32_e32 v61, v61
	v_add_f32_e32 v60, 1.0, v60
	v_add_f32_e32 v61, 1.0, v61
	v_rcp_f32_e32 v60, v60
	v_rcp_f32_e32 v61, v61
	s_nop 0
	v_pk_mul_f32 v[56:57], v[60:61], v[56:57]
	s_nop 0
	v_pk_mul_f32 v[50:51], v[50:51], v[56:57]
	s_nop 0
	v_cvt_pk_bf16_f32 v56, v50, v51
	v_lshlrev_b32_e32 v50, 16, v101
	v_mul_f32_e32 v57, 0xbfb8aa3b, v50
	v_exp_f32_e32 v57, v57
	v_and_b32_e32 v51, 0xffff0000, v101
	v_add_f32_e32 v57, 1.0, v57
	v_rcp_f32_e32 v60, v57
	v_mul_f32_e32 v57, 0xbfb8aa3b, v51
	v_exp_f32_e32 v57, v57
	s_nop 0
	v_add_f32_e32 v57, 1.0, v57
	v_rcp_f32_e32 v61, v57
	s_nop 0
	v_pk_mul_f32 v[50:51], v[60:61], v[50:51]
	s_nop 0
	v_pk_mul_f32 v[50:51], v[52:53], v[50:51]
	s_waitcnt vmcnt(6)
	v_lshlrev_b32_e32 v52, 16, v94
	v_cvt_pk_bf16_f32 v57, v50, v51
	v_and_b32_e32 v53, 0xffff0000, v94
	global_store_dwordx4 v[58:59], v[54:57], off offset:256 sc1
	v_lshlrev_b64 v[50:51], 11, v[116:117]
	s_nop 0
	v_mul_f32_e32 v54, 0xbfb8aa3b, v52
	v_mul_f32_e32 v55, 0xbfb8aa3b, v53
	v_exp_f32_e32 v54, v54
	v_exp_f32_e32 v55, v55
	v_add_f32_e32 v54, 1.0, v54
	v_add_f32_e32 v55, 1.0, v55
	v_rcp_f32_e32 v54, v54
	v_rcp_f32_e32 v55, v55
	s_nop 0
	v_pk_mul_f32 v[52:53], v[54:55], v[52:53]
	s_nop 0
	v_pk_mul_f32 v[46:47], v[46:47], v[52:53]
	v_lshlrev_b32_e32 v52, 16, v95
	v_cvt_pk_bf16_f32 v46, v46, v47
	v_mul_f32_e32 v47, 0xbfb8aa3b, v52
	v_exp_f32_e32 v47, v47
	v_and_b32_e32 v53, 0xffff0000, v95
	v_add_f32_e32 v47, 1.0, v47
	v_rcp_f32_e32 v54, v47
	v_mul_f32_e32 v47, 0xbfb8aa3b, v53
	v_exp_f32_e32 v47, v47
	s_nop 0
	v_add_f32_e32 v47, 1.0, v47
	v_rcp_f32_e32 v55, v47
	s_nop 0
	v_pk_mul_f32 v[52:53], v[54:55], v[52:53]
	s_nop 0
	v_pk_mul_f32 v[48:49], v[48:49], v[52:53]
	s_nop 0
	v_cvt_pk_bf16_f32 v47, v48, v49
	v_lshlrev_b32_e32 v48, 16, v96
	v_and_b32_e32 v49, 0xffff0000, v96
	v_mul_f32_e32 v52, 0xbfb8aa3b, v48
	v_mul_f32_e32 v53, 0xbfb8aa3b, v49
	v_exp_f32_e32 v52, v52
	v_exp_f32_e32 v53, v53
	v_add_f32_e32 v52, 1.0, v52
	v_add_f32_e32 v53, 1.0, v53
	v_rcp_f32_e32 v52, v52
	v_rcp_f32_e32 v53, v53
	s_nop 0
	v_pk_mul_f32 v[48:49], v[52:53], v[48:49]
	s_nop 0
	v_pk_mul_f32 v[42:43], v[42:43], v[48:49]
	s_nop 0
	v_cvt_pk_bf16_f32 v48, v42, v43
	v_lshlrev_b32_e32 v42, 16, v97
	v_mul_f32_e32 v49, 0xbfb8aa3b, v42
	v_exp_f32_e32 v49, v49
	v_and_b32_e32 v43, 0xffff0000, v97
	v_add_f32_e32 v49, 1.0, v49
	v_rcp_f32_e32 v52, v49
	v_mul_f32_e32 v49, 0xbfb8aa3b, v43
	v_exp_f32_e32 v49, v49
	s_nop 0
	v_add_f32_e32 v49, 1.0, v49
	v_rcp_f32_e32 v53, v49
	s_nop 0
	v_pk_mul_f32 v[42:43], v[52:53], v[42:43]
	s_nop 0
	v_pk_mul_f32 v[42:43], v[44:45], v[42:43]
	s_waitcnt vmcnt(6)
	v_lshlrev_b32_e32 v44, 16, v90
	v_cvt_pk_bf16_f32 v49, v42, v43
	v_lshl_add_u64 v[42:43], s[16:17], 0, v[50:51]
	v_lshl_add_u64 v[42:43], v[42:43], 0, v[166:167]
	v_and_b32_e32 v45, 0xffff0000, v90
	global_store_dwordx4 v[42:43], v[46:49], off sc1
	s_nop 1
	v_mul_f32_e32 v46, 0xbfb8aa3b, v44
	v_mul_f32_e32 v47, 0xbfb8aa3b, v45
	v_exp_f32_e32 v46, v46
	v_exp_f32_e32 v47, v47
	v_add_f32_e32 v46, 1.0, v46
	v_add_f32_e32 v47, 1.0, v47
	v_rcp_f32_e32 v46, v46
	v_rcp_f32_e32 v47, v47
	s_nop 0
	v_pk_mul_f32 v[44:45], v[46:47], v[44:45]
	s_nop 0
	v_pk_mul_f32 v[38:39], v[38:39], v[44:45]
	v_lshlrev_b32_e32 v44, 16, v91
	v_cvt_pk_bf16_f32 v38, v38, v39
	v_mul_f32_e32 v39, 0xbfb8aa3b, v44
	v_exp_f32_e32 v39, v39
	v_and_b32_e32 v45, 0xffff0000, v91
	v_add_f32_e32 v39, 1.0, v39
	v_rcp_f32_e32 v46, v39
	v_mul_f32_e32 v39, 0xbfb8aa3b, v45
	v_exp_f32_e32 v39, v39
	s_nop 0
	v_add_f32_e32 v39, 1.0, v39
	v_rcp_f32_e32 v47, v39
	s_nop 0
	v_pk_mul_f32 v[44:45], v[46:47], v[44:45]
	s_nop 0
	v_pk_mul_f32 v[40:41], v[40:41], v[44:45]
	s_nop 0
	v_cvt_pk_bf16_f32 v39, v40, v41
	v_lshlrev_b32_e32 v40, 16, v92
	v_and_b32_e32 v41, 0xffff0000, v92
	v_mul_f32_e32 v44, 0xbfb8aa3b, v40
	v_mul_f32_e32 v45, 0xbfb8aa3b, v41
	v_exp_f32_e32 v44, v44
	v_exp_f32_e32 v45, v45
	v_add_f32_e32 v44, 1.0, v44
	v_add_f32_e32 v45, 1.0, v45
	v_rcp_f32_e32 v44, v44
	v_rcp_f32_e32 v45, v45
	s_nop 0
	v_pk_mul_f32 v[40:41], v[44:45], v[40:41]
	s_nop 0
	v_pk_mul_f32 v[34:35], v[34:35], v[40:41]
	s_nop 0
	v_cvt_pk_bf16_f32 v40, v34, v35
	v_lshlrev_b32_e32 v34, 16, v93
	v_mul_f32_e32 v41, 0xbfb8aa3b, v34
	v_exp_f32_e32 v41, v41
	v_and_b32_e32 v35, 0xffff0000, v93
	v_add_f32_e32 v41, 1.0, v41
	v_rcp_f32_e32 v44, v41
	v_mul_f32_e32 v41, 0xbfb8aa3b, v35
	v_exp_f32_e32 v41, v41
	s_nop 0
	v_add_f32_e32 v41, 1.0, v41
	v_rcp_f32_e32 v45, v41
	s_nop 0
	v_pk_mul_f32 v[34:35], v[44:45], v[34:35]
	s_nop 0
	v_pk_mul_f32 v[34:35], v[36:37], v[34:35]
	s_waitcnt vmcnt(6)
	v_lshlrev_b32_e32 v36, 16, v86
	v_cvt_pk_bf16_f32 v41, v34, v35
	v_and_b32_e32 v37, 0xffff0000, v86
	global_store_dwordx4 v[42:43], v[38:41], off offset:256 sc1
	v_mul_f32_e32 v30, 0xbfb8aa3b, v37
	v_exp_f32_e32 v30, v30
	v_mul_f32_e32 v38, 0xbfb8aa3b, v36
	v_exp_f32_e32 v38, v38
	v_lshlrev_b64 v[34:35], 11, v[114:115]
	v_add_f32_e32 v30, 1.0, v30
	v_rcp_f32_e32 v39, v30
	v_add_f32_e32 v38, 1.0, v38
	v_rcp_f32_e32 v38, v38
	s_nop 0
	v_pk_mul_f32 v[30:31], v[38:39], v[36:37]
	s_nop 0
	v_pk_mul_f32 v[26:27], v[26:27], v[30:31]
	v_lshlrev_b32_e32 v30, 16, v87
	v_cvt_pk_bf16_f32 v26, v26, v27
	v_mul_f32_e32 v27, 0xbfb8aa3b, v30
	v_exp_f32_e32 v27, v27
	v_and_b32_e32 v31, 0xffff0000, v87
	v_add_f32_e32 v27, 1.0, v27
	v_rcp_f32_e32 v32, v27
	v_mul_f32_e32 v27, 0xbfb8aa3b, v31
	v_exp_f32_e32 v27, v27
	s_nop 0
	v_add_f32_e32 v27, 1.0, v27
	v_rcp_f32_e32 v33, v27
	s_nop 0
	v_pk_mul_f32 v[30:31], v[32:33], v[30:31]
	s_nop 0
	v_pk_mul_f32 v[28:29], v[28:29], v[30:31]
	s_nop 0
	v_cvt_pk_bf16_f32 v27, v28, v29
	v_lshlrev_b32_e32 v28, 16, v88
	v_and_b32_e32 v29, 0xffff0000, v88
	v_mul_f32_e32 v30, 0xbfb8aa3b, v28
	v_mul_f32_e32 v22, 0xbfb8aa3b, v29
	v_exp_f32_e32 v30, v30
	v_exp_f32_e32 v22, v22
	v_add_f32_e32 v30, 1.0, v30
	v_add_f32_e32 v22, 1.0, v22
	v_rcp_f32_e32 v30, v30
	v_rcp_f32_e32 v31, v22
	s_nop 0
	v_pk_mul_f32 v[22:23], v[30:31], v[28:29]
	s_nop 0
	v_pk_mul_f32 v[18:19], v[18:19], v[22:23]
	s_nop 0
	v_cvt_pk_bf16_f32 v28, v18, v19
	v_lshlrev_b32_e32 v18, 16, v89
	v_and_b32_e32 v19, 0xffff0000, v89
	v_mul_f32_e32 v22, 0xbfb8aa3b, v18
	v_mul_f32_e32 v23, 0xbfb8aa3b, v19
	v_exp_f32_e32 v22, v22
	v_exp_f32_e32 v23, v23
	v_add_f32_e32 v22, 1.0, v22
	v_add_f32_e32 v23, 1.0, v23
	v_rcp_f32_e32 v22, v22
	v_rcp_f32_e32 v23, v23
	s_nop 0
	v_pk_mul_f32 v[18:19], v[22:23], v[18:19]
	s_nop 0
	v_pk_mul_f32 v[18:19], v[20:21], v[18:19]
	s_waitcnt vmcnt(6)
	v_lshlrev_b32_e32 v20, 16, v82
	v_and_b32_e32 v21, 0xffff0000, v82
	v_mul_f32_e32 v22, 0xbfb8aa3b, v20
	v_mul_f32_e32 v14, 0xbfb8aa3b, v21
	v_exp_f32_e32 v22, v22
	v_exp_f32_e32 v14, v14
	v_cvt_pk_bf16_f32 v29, v18, v19
	v_lshl_add_u64 v[18:19], s[16:17], 0, v[34:35]
	v_add_f32_e32 v22, 1.0, v22
	v_add_f32_e32 v14, 1.0, v14
	v_rcp_f32_e32 v22, v22
	v_rcp_f32_e32 v23, v14
	v_lshl_add_u64 v[18:19], v[18:19], 0, v[166:167]
	global_store_dwordx4 v[18:19], v[26:29], off sc1
	v_pk_mul_f32 v[14:15], v[22:23], v[20:21]
	s_nop 0
	v_pk_mul_f32 v[10:11], v[10:11], v[14:15]
	v_lshlrev_b32_e32 v14, 16, v83
	v_cvt_pk_bf16_f32 v10, v10, v11
	v_mul_f32_e32 v11, 0xbfb8aa3b, v14
	v_exp_f32_e32 v11, v11
	v_and_b32_e32 v15, 0xffff0000, v83
	v_add_f32_e32 v11, 1.0, v11
	v_rcp_f32_e32 v16, v11
	v_mul_f32_e32 v11, 0xbfb8aa3b, v15
	v_exp_f32_e32 v11, v11
	s_nop 0
	v_add_f32_e32 v11, 1.0, v11
	v_rcp_f32_e32 v17, v11
	s_nop 0
	v_pk_mul_f32 v[14:15], v[16:17], v[14:15]
	s_nop 0
	v_pk_mul_f32 v[12:13], v[12:13], v[14:15]
	s_nop 0
	v_cvt_pk_bf16_f32 v11, v12, v13
	v_lshlrev_b32_e32 v12, 16, v84
	v_and_b32_e32 v13, 0xffff0000, v84
	v_mul_f32_e32 v14, 0xbfb8aa3b, v12
	v_mul_f32_e32 v6, 0xbfb8aa3b, v13
	v_exp_f32_e32 v14, v14
	v_exp_f32_e32 v6, v6
	v_add_f32_e32 v14, 1.0, v14
	v_add_f32_e32 v6, 1.0, v6
	v_rcp_f32_e32 v14, v14
	v_rcp_f32_e32 v15, v6
	s_nop 0
	v_pk_mul_f32 v[6:7], v[14:15], v[12:13]
	s_nop 0
	v_pk_mul_f32 v[2:3], v[2:3], v[6:7]
	s_nop 0
	v_cvt_pk_bf16_f32 v12, v2, v3
	v_lshlrev_b32_e32 v2, 16, v85
	v_and_b32_e32 v3, 0xffff0000, v85
	v_mul_f32_e32 v6, 0xbfb8aa3b, v2
	v_mul_f32_e32 v7, 0xbfb8aa3b, v3
	v_exp_f32_e32 v6, v6
	v_exp_f32_e32 v7, v7
	v_add_f32_e32 v6, 1.0, v6
	v_add_f32_e32 v7, 1.0, v7
	v_rcp_f32_e32 v6, v6
	v_rcp_f32_e32 v7, v7
	s_nop 0
	v_pk_mul_f32 v[2:3], v[6:7], v[2:3]
	s_nop 0
	v_pk_mul_f32 v[2:3], v[4:5], v[2:3]
	s_nop 0
	v_cvt_pk_bf16_f32 v13, v2, v3
	global_store_dwordx4 v[18:19], v[10:13], off offset:256 sc1
	s_cbranch_vccnz .LBB0_422
	s_andn2_b64 vcc, exec, s[14:15]
	s_cbranch_vccnz .LBB0_421
	s_barrier
	s_branch .LBB0_421
